# P5/P10/P12 epilogues: IEEE f32 division expansion of 1/(1+exp(-x)) replaced by v_rcp_f32 (513 sites, -5100 VALU instructions); store-data WAR pads re-derived
# speedup vs baseline: 1.0173x; 1.0109x over previous
; DI v4u pack8(const f4& a, const f4& b) { v4u w; w.x = cvt_pk_bf16(a[0], a[1]); w.y = cvt_pk_bf16(a[2], a[3]); w.z = cvt_pk_bf16(b[0], b[1]); w.w = cvt_pk_bf16(b[2], b[3]); return w; }
; DI float sigmoidf_(float z) { return 1.0f / (1.0f + __expf(-z)); }
;     DI void operator()(f4 (&acc)[2][2][4][2], const Unit& u, int wr, int wc, int fr, int fq) const {
;     ...
;         } else if (which == 1) {
; #pragma unroll
;             for (int bj = 0; bj < 2; ++bj) { const int col = col0 + bj * HALF; const f4 z0 = *(const f4*)(a0 + col), z1 = *(const f4*)(a0 + col + 4);
; #pragma unroll
;                 for (int ai = 0; ai < 2; ++ai)
; #pragma unroll
;                     for (int m = 0; m < 4; ++m) { const size_t off = (size_t)(row0 + ai * HALF + m * 16) * DB + col;
;                         f4 x0 = acc[ai][bj][m][0] + z0, x1 = acc[ai][bj][m][1] + z1;
; #pragma unroll
;                         for (int e = 0; e < 4; ++e) { x0[e] = sigmoidf_(x0[e]); x1[e] = sigmoidf_(x1[e]); }
;                         *(v4u*)(aout + off) = pack8(x0, x1);
;                         asm volatile("" ::: "memory"); } }
.LBB0_2067:
	s_andn2_b64 vcc, exec, s[0:1]
	s_cbranch_vccnz .LBB0_2069
	v_lshl_add_u64 v[154:155], v[150:151], 2, s[22:23]
	global_load_dwordx4 v[132:135], v[154:155], off
	global_load_dwordx4 v[128:131], v[154:155], off offset:16
	s_waitcnt vmcnt(0)
	v_pk_add_f32 v[158:159], v[124:125], v[132:133]
	v_pk_add_f32 v[162:163], v[120:121], v[128:129]
	v_mul_f32_e32 v158, 0xbfb8aa3b, v158
	v_mul_f32_e32 v162, 0xbfb8aa3b, v162
	v_exp_f32_e32 v158, v158
	v_mul_f32_e32 v159, 0xbfb8aa3b, v159
	v_exp_f32_e32 v162, v162
	v_pk_add_f32 v[156:157], v[126:127], v[134:135]
	v_mul_f32_e32 v163, 0xbfb8aa3b, v163
	v_exp_f32_e32 v159, v159
	v_mul_f32_e32 v156, 0xbfb8aa3b, v156
	v_exp_f32_e32 v163, v163
	v_exp_f32_e32 v156, v156
	v_add_f32_e32 v158, 1.0, v158
	v_add_f32_e32 v162, 1.0, v162
	v_pk_add_f32 v[160:161], v[122:123], v[130:131]
	v_add_f32_e32 v159, 1.0, v159
	v_mul_f32_e32 v160, 0xbfb8aa3b, v160
	v_add_f32_e32 v163, 1.0, v163
	v_exp_f32_e32 v160, v160
	v_add_f32_e32 v156, 1.0, v156
	v_add_f32_e32 v160, 1.0, v160
	v_mul_f32_e32 v157, 0xbfb8aa3b, v157
	v_exp_f32_e32 v157, v157
	v_rcp_f32_e32 v158, v158
	v_rcp_f32_e32 v162, v162
	v_rcp_f32_e32 v159, v159
	v_add_f32_e32 v157, 1.0, v157
	v_rcp_f32_e32 v163, v163
	v_rcp_f32_e32 v156, v156
	v_mul_f32_e32 v161, 0xbfb8aa3b, v161
	v_rcp_f32_e32 v164, v160
	v_exp_f32_e32 v161, v161
	s_nop 0
	v_add_f32_e32 v161, 1.0, v161
	v_rcp_f32_e32 v157, v157
	v_cvt_pk_bf16_f32 v158, v158, v159
	v_rcp_f32_e32 v161, v161
	v_cvt_pk_bf16_f32 v159, v156, v157
	v_cvt_pk_bf16_f32 v160, v162, v163
	v_pk_add_f32 v[162:163], v[116:117], v[132:133]
	v_lshlrev_b64 v[156:157], 12, v[144:145]
	v_mul_f32_e32 v162, 0xbfb8aa3b, v162
	v_exp_f32_e32 v162, v162
	v_lshl_add_u64 v[156:157], s[28:29], 0, v[156:157]
	v_lshl_add_u64 v[156:157], v[156:157], 0, v[152:153]
	v_cvt_pk_bf16_f32 v161, v164, v161
	global_store_dwordx4 v[156:157], v[158:161], off
	v_pk_add_f32 v[166:167], v[112:113], v[128:129]
	v_mul_f32_e32 v163, 0xbfb8aa3b, v163
	v_add_f32_e32 v159, 1.0, v162
	v_mul_f32_e32 v166, 0xbfb8aa3b, v166
	v_exp_f32_e32 v166, v166
	v_exp_f32_e32 v163, v163
	v_add_f32_e32 v166, 1.0, v166
	v_rcp_f32_e32 v162, v159
	v_add_f32_e32 v163, 1.0, v163
	v_mul_f32_e32 v167, 0xbfb8aa3b, v167
	v_rcp_f32_e32 v166, v166
	v_exp_f32_e32 v167, v167
	s_nop 0
	v_add_f32_e32 v167, 1.0, v167
	v_pk_add_f32 v[160:161], v[118:119], v[134:135]
	v_mul_f32_e32 v160, 0xbfb8aa3b, v160
	v_rcp_f32_e32 v163, v163
	v_exp_f32_e32 v160, v160
	s_nop 0
	v_add_f32_e32 v160, 1.0, v160
	v_pk_add_f32 v[164:165], v[114:115], v[130:131]
	v_mul_f32_e32 v164, 0xbfb8aa3b, v164
	v_rcp_f32_e32 v167, v167
	v_exp_f32_e32 v164, v164
	s_nop 0
	v_add_f32_e32 v164, 1.0, v164
	v_mul_f32_e32 v161, 0xbfb8aa3b, v161
	v_rcp_f32_e32 v168, v160
	v_exp_f32_e32 v161, v161
	s_nop 0
	v_add_f32_e32 v161, 1.0, v161
	v_mul_f32_e32 v165, 0xbfb8aa3b, v165
	v_rcp_f32_e32 v164, v164
	v_exp_f32_e32 v165, v165
	s_nop 0
	v_add_f32_e32 v165, 1.0, v165
	v_rcp_f32_e32 v161, v161
	v_rcp_f32_e32 v165, v165
	v_cvt_pk_bf16_f32 v160, v162, v163
	v_cvt_pk_bf16_f32 v161, v168, v161
	v_cvt_pk_bf16_f32 v162, v166, v167
	v_cvt_pk_bf16_f32 v163, v164, v165
	v_pk_add_f32 v[164:165], v[108:109], v[132:133]
	v_or_b32_e32 v158, 16, v144
	v_mul_f32_e32 v164, 0xbfb8aa3b, v164
	v_mov_b32_e32 v159, v145
	v_exp_f32_e32 v164, v164
	v_lshlrev_b64 v[158:159], 12, v[158:159]
	v_lshl_add_u64 v[158:159], s[28:29], 0, v[158:159]
	v_lshl_add_u64 v[158:159], v[158:159], 0, v[152:153]
	global_store_dwordx4 v[158:159], v[160:163], off
	v_pk_add_f32 v[168:169], v[104:105], v[128:129]
	v_mul_f32_e32 v165, 0xbfb8aa3b, v165
	v_add_f32_e32 v161, 1.0, v164
	v_mul_f32_e32 v168, 0xbfb8aa3b, v168
	v_exp_f32_e32 v168, v168
	v_exp_f32_e32 v165, v165
	v_add_f32_e32 v168, 1.0, v168
	v_rcp_f32_e32 v164, v161
	v_add_f32_e32 v165, 1.0, v165
	v_mul_f32_e32 v169, 0xbfb8aa3b, v169
	v_rcp_f32_e32 v168, v168
	v_exp_f32_e32 v169, v169
	s_nop 0
	v_add_f32_e32 v169, 1.0, v169
	v_pk_add_f32 v[162:163], v[110:111], v[134:135]
	v_mul_f32_e32 v162, 0xbfb8aa3b, v162
	v_rcp_f32_e32 v165, v165
	v_exp_f32_e32 v162, v162
	s_nop 0
	v_add_f32_e32 v162, 1.0, v162
	v_pk_add_f32 v[166:167], v[106:107], v[130:131]
	v_mul_f32_e32 v166, 0xbfb8aa3b, v166
	v_rcp_f32_e32 v169, v169
	v_exp_f32_e32 v166, v166
	s_nop 0
	v_add_f32_e32 v166, 1.0, v166
	v_mul_f32_e32 v163, 0xbfb8aa3b, v163
	v_rcp_f32_e32 v175, v162
	v_exp_f32_e32 v163, v163
	s_nop 0
	v_add_f32_e32 v163, 1.0, v163
	v_mul_f32_e32 v167, 0xbfb8aa3b, v167
	v_rcp_f32_e32 v166, v166
	v_exp_f32_e32 v167, v167
	s_nop 0
	v_add_f32_e32 v167, 1.0, v167
	v_rcp_f32_e32 v163, v163
	v_rcp_f32_e32 v167, v167
	v_cvt_pk_bf16_f32 v162, v164, v165
	v_cvt_pk_bf16_f32 v163, v175, v163
	v_cvt_pk_bf16_f32 v164, v168, v169
	v_cvt_pk_bf16_f32 v165, v166, v167
	v_pk_add_f32 v[166:167], v[100:101], v[132:133]
	v_or_b32_e32 v160, 32, v144
	v_mul_f32_e32 v166, 0xbfb8aa3b, v166
	v_mov_b32_e32 v161, v145
	v_exp_f32_e32 v166, v166
	v_lshlrev_b64 v[160:161], 12, v[160:161]
	v_lshl_add_u64 v[160:161], s[28:29], 0, v[160:161]
	v_lshl_add_u64 v[160:161], v[160:161], 0, v[152:153]
	global_store_dwordx4 v[160:161], v[162:165], off
	v_pk_add_f32 v[176:177], v[96:97], v[128:129]
	v_mul_f32_e32 v167, 0xbfb8aa3b, v167
	v_add_f32_e32 v163, 1.0, v166
	v_mul_f32_e32 v176, 0xbfb8aa3b, v176
	v_exp_f32_e32 v176, v176
	v_exp_f32_e32 v167, v167
	v_add_f32_e32 v176, 1.0, v176
	v_rcp_f32_e32 v166, v163
	v_add_f32_e32 v167, 1.0, v167
	v_mul_f32_e32 v177, 0xbfb8aa3b, v177
	v_rcp_f32_e32 v175, v176
	v_exp_f32_e32 v177, v177
	s_nop 0
	v_add_f32_e32 v177, 1.0, v177
	v_pk_add_f32 v[164:165], v[102:103], v[134:135]
	v_mul_f32_e32 v164, 0xbfb8aa3b, v164
	v_rcp_f32_e32 v167, v167
; DI v4u pack8(const f4& a, const f4& b) { v4u w; w.x = cvt_pk_bf16(a[0], a[1]); w.y = cvt_pk_bf16(a[2], a[3]); w.z = cvt_pk_bf16(b[0], b[1]); w.w = cvt_pk_bf16(b[2], b[3]); return w; }
; DI float sigmoidf_(float z) { return 1.0f / (1.0f + __expf(-z)); }
;     DI void operator()(f4 (&acc)[2][2][4][2], const Unit& u, int wr, int wc, int fr, int fq) const {
;     ...
;         } else if (which == 1) {
; #pragma unroll
;             for (int bj = 0; bj < 2; ++bj) { const int col = col0 + bj * HALF; const f4 z0 = *(const f4*)(a0 + col), z1 = *(const f4*)(a0 + col + 4);
; #pragma unroll
;                 for (int ai = 0; ai < 2; ++ai)
; #pragma unroll
;                     for (int m = 0; m < 4; ++m) { const size_t off = (size_t)(row0 + ai * HALF + m * 16) * DB + col;
;                         f4 x0 = acc[ai][bj][m][0] + z0, x1 = acc[ai][bj][m][1] + z1;
; #pragma unroll
;                         for (int e = 0; e < 4; ++e) { x0[e] = sigmoidf_(x0[e]); x1[e] = sigmoidf_(x1[e]); }
;                         *(v4u*)(aout + off) = pack8(x0, x1);
;                         asm volatile("" ::: "memory"); } }
	v_exp_f32_e32 v164, v164
	s_nop 0
	v_add_f32_e32 v164, 1.0, v164
	v_pk_add_f32 v[168:169], v[98:99], v[130:131]
	v_mul_f32_e32 v168, 0xbfb8aa3b, v168
	v_rcp_f32_e32 v176, v177
	v_exp_f32_e32 v168, v168
	s_nop 0
	v_add_f32_e32 v168, 1.0, v168
	v_mul_f32_e32 v165, 0xbfb8aa3b, v165
	v_rcp_f32_e32 v177, v164
	v_exp_f32_e32 v165, v165
	s_nop 0
	v_add_f32_e32 v165, 1.0, v165
	v_mul_f32_e32 v169, 0xbfb8aa3b, v169
	v_rcp_f32_e32 v168, v168
	v_exp_f32_e32 v169, v169
	s_nop 0
	v_add_f32_e32 v169, 1.0, v169
	v_rcp_f32_e32 v165, v165
	v_rcp_f32_e32 v169, v169
	v_cvt_pk_bf16_f32 v164, v166, v167
	v_cvt_pk_bf16_f32 v165, v177, v165
	v_cvt_pk_bf16_f32 v166, v175, v176
	v_cvt_pk_bf16_f32 v167, v168, v169
	v_pk_add_f32 v[168:169], v[92:93], v[132:133]
	v_or_b32_e32 v162, 48, v144
	v_mul_f32_e32 v168, 0xbfb8aa3b, v168
	v_mov_b32_e32 v163, v145
	v_exp_f32_e32 v168, v168
	v_lshlrev_b64 v[162:163], 12, v[162:163]
	v_lshl_add_u64 v[162:163], s[28:29], 0, v[162:163]
	v_lshl_add_u64 v[162:163], v[162:163], 0, v[152:153]
	global_store_dwordx4 v[162:163], v[164:167], off
	v_pk_add_f32 v[178:179], v[88:89], v[128:129]
	v_mul_f32_e32 v169, 0xbfb8aa3b, v169
	v_add_f32_e32 v165, 1.0, v168
	v_mul_f32_e32 v178, 0xbfb8aa3b, v178
	v_exp_f32_e32 v178, v178
	v_exp_f32_e32 v169, v169
	v_add_f32_e32 v178, 1.0, v178
	v_rcp_f32_e32 v168, v165
	v_add_f32_e32 v169, 1.0, v169
	v_mul_f32_e32 v179, 0xbfb8aa3b, v179
	v_rcp_f32_e32 v175, v178
	v_exp_f32_e32 v179, v179
	s_nop 0
	v_add_f32_e32 v179, 1.0, v179
	v_pk_add_f32 v[166:167], v[94:95], v[134:135]
	v_mul_f32_e32 v166, 0xbfb8aa3b, v166
	v_rcp_f32_e32 v169, v169
	v_exp_f32_e32 v166, v166
	s_nop 0
	v_add_f32_e32 v166, 1.0, v166
	v_pk_add_f32 v[176:177], v[90:91], v[130:131]
	v_mul_f32_e32 v176, 0xbfb8aa3b, v176
	v_rcp_f32_e32 v178, v179
	v_exp_f32_e32 v176, v176
	s_nop 0
	v_add_f32_e32 v176, 1.0, v176
	v_mul_f32_e32 v167, 0xbfb8aa3b, v167
	v_rcp_f32_e32 v179, v166
	v_exp_f32_e32 v167, v167
	s_nop 0
	v_add_f32_e32 v167, 1.0, v167
	v_mul_f32_e32 v177, 0xbfb8aa3b, v177
	v_rcp_f32_e32 v176, v176
	v_exp_f32_e32 v177, v177
	s_nop 0
	v_add_f32_e32 v177, 1.0, v177
	v_rcp_f32_e32 v167, v167
	v_rcp_f32_e32 v177, v177
	v_cvt_pk_bf16_f32 v166, v168, v169
	v_cvt_pk_bf16_f32 v167, v179, v167
	v_cvt_pk_bf16_f32 v168, v175, v178
	v_cvt_pk_bf16_f32 v169, v176, v177
	v_pk_add_f32 v[176:177], v[84:85], v[132:133]
	v_add_u32_e32 v164, 0x80, v144
	v_mul_f32_e32 v175, 0xbfb8aa3b, v176
	v_mov_b32_e32 v165, v145
	v_exp_f32_e32 v175, v175
	v_lshlrev_b64 v[164:165], 12, v[164:165]
	v_lshl_add_u64 v[164:165], s[28:29], 0, v[164:165]
	v_lshl_add_u64 v[164:165], v[164:165], 0, v[152:153]
	global_store_dwordx4 v[164:165], v[166:169], off
	v_pk_add_f32 v[180:181], v[80:81], v[128:129]
	v_mul_f32_e32 v177, 0xbfb8aa3b, v177
	v_add_f32_e32 v167, 1.0, v175
	v_mul_f32_e32 v180, 0xbfb8aa3b, v180
	v_exp_f32_e32 v180, v180
	v_exp_f32_e32 v177, v177
	v_add_f32_e32 v180, 1.0, v180
	v_rcp_f32_e32 v175, v167
	v_add_f32_e32 v177, 1.0, v177
	v_mul_f32_e32 v181, 0xbfb8aa3b, v181
	v_rcp_f32_e32 v180, v180
	v_exp_f32_e32 v181, v181
	s_nop 0
	v_add_f32_e32 v181, 1.0, v181
	v_pk_add_f32 v[168:169], v[86:87], v[134:135]
	v_mul_f32_e32 v168, 0xbfb8aa3b, v168
	v_rcp_f32_e32 v176, v177
	v_exp_f32_e32 v168, v168
	s_nop 0
	v_add_f32_e32 v168, 1.0, v168
	v_pk_add_f32 v[178:179], v[82:83], v[130:131]
	v_mul_f32_e32 v178, 0xbfb8aa3b, v178
	v_rcp_f32_e32 v181, v181
	v_exp_f32_e32 v178, v178
	s_nop 0
	v_add_f32_e32 v178, 1.0, v178
	v_mul_f32_e32 v169, 0xbfb8aa3b, v169
	v_rcp_f32_e32 v168, v168
	v_exp_f32_e32 v169, v169
	s_nop 0
	v_add_f32_e32 v169, 1.0, v169
	v_rcp_f32_e32 v184, v178
	v_mul_f32_e32 v178, 0xbfb8aa3b, v179
	v_exp_f32_e32 v178, v178
	s_nop 0
	v_add_f32_e32 v178, 1.0, v178
	v_rcp_f32_e32 v169, v169
	v_cvt_pk_bf16_f32 v176, v175, v176
	v_cvt_pk_bf16_f32 v177, v168, v169
	v_pk_add_f32 v[168:169], v[76:77], v[132:133]
	v_rcp_f32_e32 v179, v178
	v_mul_f32_e32 v168, 0xbfb8aa3b, v168
	v_exp_f32_e32 v175, v168
	v_cvt_pk_bf16_f32 v178, v180, v181
	v_pk_add_f32 v[180:181], v[72:73], v[128:129]
	v_cvt_pk_bf16_f32 v179, v184, v179
	v_add_f32_e32 v175, 1.0, v175
	v_mul_f32_e32 v180, 0xbfb8aa3b, v180
	v_exp_f32_e32 v180, v180
	v_mul_f32_e32 v169, 0xbfb8aa3b, v169
	v_add_f32_e32 v180, 1.0, v180
	v_rcp_f32_e32 v175, v175
	v_exp_f32_e32 v169, v169
	s_nop 0
	v_add_f32_e32 v169, 1.0, v169
	v_mul_f32_e32 v181, 0xbfb8aa3b, v181
	v_rcp_f32_e32 v180, v180
	v_exp_f32_e32 v181, v181
	v_add_u32_e32 v166, 0x90, v144
	v_mov_b32_e32 v167, v145
	v_add_f32_e32 v181, 1.0, v181
	v_lshlrev_b64 v[166:167], 12, v[166:167]
	v_lshl_add_u64 v[166:167], s[28:29], 0, v[166:167]
	v_lshl_add_u64 v[166:167], v[166:167], 0, v[152:153]
	global_store_dwordx4 v[166:167], v[176:179], off
	v_rcp_f32_e32 v182, v169
	s_nop 0
	v_pk_add_f32 v[176:177], v[78:79], v[134:135]
	v_mul_f32_e32 v176, 0xbfb8aa3b, v176
	v_exp_f32_e32 v176, v176
	s_nop 0
	v_add_f32_e32 v176, 1.0, v176
	v_pk_add_f32 v[178:179], v[74:75], v[130:131]
	v_mul_f32_e32 v178, 0xbfb8aa3b, v178
	v_rcp_f32_e32 v181, v181
	v_exp_f32_e32 v178, v178
	s_nop 0
	v_add_f32_e32 v178, 1.0, v178
	v_mul_f32_e32 v177, 0xbfb8aa3b, v177
	v_rcp_f32_e32 v183, v176
	v_exp_f32_e32 v177, v177
	s_nop 0
	v_add_f32_e32 v177, 1.0, v177
	v_rcp_f32_e32 v186, v178
	v_mul_f32_e32 v178, 0xbfb8aa3b, v179
	v_exp_f32_e32 v178, v178
	s_nop 0
	v_add_f32_e32 v178, 1.0, v178
	v_rcp_f32_e32 v177, v177
	v_pk_add_f32 v[132:133], v[68:69], v[132:133]
	v_mul_f32_e32 v132, 0xbfb8aa3b, v132
	v_cvt_pk_bf16_f32 v176, v175, v182
	v_exp_f32_e32 v175, v132
	v_add_u32_e32 v168, 0xa0, v144
	v_rcp_f32_e32 v179, v178
	v_mov_b32_e32 v169, v145
	v_lshlrev_b64 v[168:169], 12, v[168:169]
	v_lshl_add_u64 v[168:169], s[28:29], 0, v[168:169]
; DI v4u pack8(const f4& a, const f4& b) { v4u w; w.x = cvt_pk_bf16(a[0], a[1]); w.y = cvt_pk_bf16(a[2], a[3]); w.z = cvt_pk_bf16(b[0], b[1]); w.w = cvt_pk_bf16(b[2], b[3]); return w; }
; DI float sigmoidf_(float z) { return 1.0f / (1.0f + __expf(-z)); }
;     DI void operator()(f4 (&acc)[2][2][4][2], const Unit& u, int wr, int wc, int fr, int fq) const {
;     ...
;         } else if (which == 1) {
; #pragma unroll
;             for (int bj = 0; bj < 2; ++bj) { const int col = col0 + bj * HALF; const f4 z0 = *(const f4*)(a0 + col), z1 = *(const f4*)(a0 + col + 4);
; #pragma unroll
;                 for (int ai = 0; ai < 2; ++ai)
; #pragma unroll
;                     for (int m = 0; m < 4; ++m) { const size_t off = (size_t)(row0 + ai * HALF + m * 16) * DB + col;
;                         f4 x0 = acc[ai][bj][m][0] + z0, x1 = acc[ai][bj][m][1] + z1;
; #pragma unroll
;                         for (int e = 0; e < 4; ++e) { x0[e] = sigmoidf_(x0[e]); x1[e] = sigmoidf_(x1[e]); }
;                         *(v4u*)(aout + off) = pack8(x0, x1);
;                         asm volatile("" ::: "memory"); } }
	v_lshl_add_u64 v[168:169], v[168:169], 0, v[152:153]
	v_add_f32_e32 v175, 1.0, v175
	v_cvt_pk_bf16_f32 v177, v183, v177
	v_cvt_pk_bf16_f32 v178, v180, v181
	v_cvt_pk_bf16_f32 v179, v186, v179
	global_store_dwordx4 v[168:169], v[176:179], off
	v_pk_add_f32 v[128:129], v[64:65], v[128:129]
	v_mul_f32_e32 v133, 0xbfb8aa3b, v133
	v_mul_f32_e32 v128, 0xbfb8aa3b, v128
	v_exp_f32_e32 v128, v128
	v_exp_f32_e32 v133, v133
	v_add_f32_e32 v128, 1.0, v128
	v_rcp_f32_e32 v175, v175
	v_add_f32_e32 v133, 1.0, v133
	v_mul_f32_e32 v129, 0xbfb8aa3b, v129
	v_rcp_f32_e32 v176, v128
	v_exp_f32_e32 v129, v129
	s_nop 0
	v_add_f32_e32 v129, 1.0, v129
	v_pk_add_f32 v[134:135], v[70:71], v[134:135]
	v_mul_f32_e32 v134, 0xbfb8aa3b, v134
	v_rcp_f32_e32 v128, v133
	v_exp_f32_e32 v134, v134
	s_nop 0
	v_add_f32_e32 v134, 1.0, v134
	v_pk_add_f32 v[130:131], v[66:67], v[130:131]
	v_mul_f32_e32 v130, 0xbfb8aa3b, v130
	v_rcp_f32_e32 v177, v129
	v_exp_f32_e32 v130, v130
	s_nop 0
	v_add_f32_e32 v130, 1.0, v130
	v_mul_f32_e32 v135, 0xbfb8aa3b, v135
	v_exp_f32_e32 v135, v135
	v_rcp_f32_e32 v129, v134
	v_add_f32_e32 v135, 1.0, v135
	v_mul_f32_e32 v131, 0xbfb8aa3b, v131
	v_rcp_f32_e32 v134, v130
	v_exp_f32_e32 v131, v131
	s_nop 0
	v_add_f32_e32 v131, 1.0, v131
	v_rcp_f32_e32 v130, v135
	v_add_u32_e32 v132, 0xb0, v144
	v_rcp_f32_e32 v131, v131
	v_mov_b32_e32 v133, v145
	v_lshlrev_b64 v[132:133], 12, v[132:133]
	v_lshl_add_u64 v[132:133], s[28:29], 0, v[132:133]
	v_lshl_add_u64 v[152:153], v[132:133], 0, v[152:153]
	v_cvt_pk_bf16_f32 v128, v175, v128
	v_cvt_pk_bf16_f32 v129, v129, v130
	v_cvt_pk_bf16_f32 v130, v176, v177
	v_cvt_pk_bf16_f32 v131, v134, v131
	global_store_dwordx4 v[152:153], v[128:131], off
	global_load_dwordx4 v[132:135], v[154:155], off offset:512
	global_load_dwordx4 v[128:131], v[154:155], off offset:528
	s_waitcnt vmcnt(0)
	v_pk_add_f32 v[154:155], v[60:61], v[132:133]
	s_nop 0
	v_mul_f32_e32 v154, 0xbfb8aa3b, v154
	v_exp_f32_e32 v154, v154
	v_pk_add_f32 v[180:181], v[56:57], v[128:129]
	v_mul_f32_e32 v155, 0xbfb8aa3b, v155
	v_mul_f32_e32 v180, 0xbfb8aa3b, v180
	v_add_f32_e32 v154, 1.0, v154
	v_exp_f32_e32 v180, v180
	v_exp_f32_e32 v155, v155
	v_mul_f32_e32 v181, 0xbfb8aa3b, v181
	v_add_f32_e32 v180, 1.0, v180
	v_rcp_f32_e32 v154, v154
	v_add_f32_e32 v155, 1.0, v155
	v_rcp_f32_e32 v175, v180
	v_exp_f32_e32 v181, v181
	s_nop 0
	v_add_f32_e32 v181, 1.0, v181
	v_pk_add_f32 v[176:177], v[62:63], v[134:135]
	v_mul_f32_e32 v176, 0xbfb8aa3b, v176
	v_rcp_f32_e32 v155, v155
	v_exp_f32_e32 v176, v176
	s_nop 0
	v_add_f32_e32 v176, 1.0, v176
	v_pk_add_f32 v[178:179], v[58:59], v[130:131]
	v_mul_f32_e32 v178, 0xbfb8aa3b, v178
	v_rcp_f32_e32 v180, v181
	v_exp_f32_e32 v178, v178
	s_nop 0
	v_add_f32_e32 v178, 1.0, v178
	v_mul_f32_e32 v177, 0xbfb8aa3b, v177
	v_rcp_f32_e32 v181, v176
	v_exp_f32_e32 v177, v177
	s_nop 0
	v_add_f32_e32 v177, 1.0, v177
	v_mul_f32_e32 v179, 0xbfb8aa3b, v179
	v_rcp_f32_e32 v182, v178
	v_exp_f32_e32 v179, v179
	s_nop 0
	v_add_f32_e32 v179, 1.0, v179
	v_rcp_f32_e32 v177, v177
	v_rcp_f32_e32 v179, v179
	v_cvt_pk_bf16_f32 v176, v154, v155
	v_pk_add_f32 v[154:155], v[52:53], v[132:133]
	v_cvt_pk_bf16_f32 v177, v181, v177
	v_cvt_pk_bf16_f32 v178, v175, v180
	v_cvt_pk_bf16_f32 v179, v182, v179
	global_store_dwordx4 v[156:157], v[176:179], off offset:256
	v_mul_f32_e32 v154, 0xbfb8aa3b, v154
	v_exp_f32_e32 v154, v154
	v_pk_add_f32 v[178:179], v[48:49], v[128:129]
	v_mul_f32_e32 v155, 0xbfb8aa3b, v155
	v_mul_f32_e32 v178, 0xbfb8aa3b, v178
	v_add_f32_e32 v154, 1.0, v154
	v_exp_f32_e32 v178, v178
	v_exp_f32_e32 v155, v155
	v_mul_f32_e32 v179, 0xbfb8aa3b, v179
	v_add_f32_e32 v178, 1.0, v178
	v_rcp_f32_e32 v154, v154
	v_add_f32_e32 v155, 1.0, v155
	v_rcp_f32_e32 v175, v178
	v_exp_f32_e32 v179, v179
	s_nop 0
	v_add_f32_e32 v179, 1.0, v179
	v_pk_add_f32 v[156:157], v[54:55], v[134:135]
	v_mul_f32_e32 v156, 0xbfb8aa3b, v156
	v_rcp_f32_e32 v155, v155
	v_exp_f32_e32 v156, v156
	s_nop 0
	v_add_f32_e32 v156, 1.0, v156
	v_pk_add_f32 v[176:177], v[50:51], v[130:131]
	v_mul_f32_e32 v176, 0xbfb8aa3b, v176
	v_rcp_f32_e32 v178, v179
	v_exp_f32_e32 v176, v176
	s_nop 0
	v_add_f32_e32 v176, 1.0, v176
	v_mul_f32_e32 v157, 0xbfb8aa3b, v157
	v_rcp_f32_e32 v156, v156
	v_exp_f32_e32 v157, v157
	s_nop 0
	v_add_f32_e32 v157, 1.0, v157
	v_mul_f32_e32 v177, 0xbfb8aa3b, v177
	v_rcp_f32_e32 v179, v176
	v_exp_f32_e32 v177, v177
	s_nop 0
	v_add_f32_e32 v177, 1.0, v177
	v_rcp_f32_e32 v157, v157
	v_rcp_f32_e32 v180, v177
	v_pk_add_f32 v[176:177], v[44:45], v[132:133]
	v_cvt_pk_bf16_f32 v154, v154, v155
	v_cvt_pk_bf16_f32 v155, v156, v157
	v_cvt_pk_bf16_f32 v156, v175, v178
	s_nop 0
	v_mul_f32_e32 v157, 0xbfb8aa3b, v176
	v_exp_f32_e32 v175, v157
	v_cvt_pk_bf16_f32 v157, v179, v180
	global_store_dwordx4 v[158:159], v[154:157], off offset:256
	v_pk_add_f32 v[158:159], v[40:41], v[128:129]
	v_add_f32_e32 v175, 1.0, v175
	v_mul_f32_e32 v158, 0xbfb8aa3b, v158
	v_exp_f32_e32 v158, v158
	v_mul_f32_e32 v177, 0xbfb8aa3b, v177
	v_add_f32_e32 v158, 1.0, v158
	v_rcp_f32_e32 v175, v175
	v_exp_f32_e32 v177, v177
	s_nop 0
	v_add_f32_e32 v177, 1.0, v177
	v_mul_f32_e32 v159, 0xbfb8aa3b, v159
	v_rcp_f32_e32 v158, v158
	v_exp_f32_e32 v159, v159
	s_nop 0
	v_add_f32_e32 v159, 1.0, v159
	v_pk_add_f32 v[154:155], v[46:47], v[134:135]
	v_mul_f32_e32 v154, 0xbfb8aa3b, v154
	v_rcp_f32_e32 v176, v177
	v_exp_f32_e32 v154, v154
	s_nop 0
	v_add_f32_e32 v154, 1.0, v154
	v_pk_add_f32 v[156:157], v[42:43], v[130:131]
	v_mul_f32_e32 v156, 0xbfb8aa3b, v156
	v_rcp_f32_e32 v159, v159
	v_exp_f32_e32 v156, v156
	s_nop 0
	v_add_f32_e32 v156, 1.0, v156
	v_mul_f32_e32 v155, 0xbfb8aa3b, v155
	v_rcp_f32_e32 v177, v154
	v_exp_f32_e32 v155, v155
; DI v4u pack8(const f4& a, const f4& b) { v4u w; w.x = cvt_pk_bf16(a[0], a[1]); w.y = cvt_pk_bf16(a[2], a[3]); w.z = cvt_pk_bf16(b[0], b[1]); w.w = cvt_pk_bf16(b[2], b[3]); return w; }
; DI float sigmoidf_(float z) { return 1.0f / (1.0f + __expf(-z)); }
;     DI void operator()(f4 (&acc)[2][2][4][2], const Unit& u, int wr, int wc, int fr, int fq) const {
;     ...
;         } else if (which == 1) {
; #pragma unroll
;             for (int bj = 0; bj < 2; ++bj) { const int col = col0 + bj * HALF; const f4 z0 = *(const f4*)(a0 + col), z1 = *(const f4*)(a0 + col + 4);
; #pragma unroll
;                 for (int ai = 0; ai < 2; ++ai)
; #pragma unroll
;                     for (int m = 0; m < 4; ++m) { const size_t off = (size_t)(row0 + ai * HALF + m * 16) * DB + col;
;                         f4 x0 = acc[ai][bj][m][0] + z0, x1 = acc[ai][bj][m][1] + z1;
; #pragma unroll
;                         for (int e = 0; e < 4; ++e) { x0[e] = sigmoidf_(x0[e]); x1[e] = sigmoidf_(x1[e]); }
;                         *(v4u*)(aout + off) = pack8(x0, x1);
;                         asm volatile("" ::: "memory"); } }
	s_nop 0
	v_add_f32_e32 v155, 1.0, v155
	v_mul_f32_e32 v157, 0xbfb8aa3b, v157
	v_rcp_f32_e32 v178, v156
	v_exp_f32_e32 v157, v157
	s_nop 0
	v_add_f32_e32 v157, 1.0, v157
	v_rcp_f32_e32 v155, v155
	v_rcp_f32_e32 v157, v157
	v_cvt_pk_bf16_f32 v154, v175, v176
	v_cvt_pk_bf16_f32 v155, v177, v155
	v_cvt_pk_bf16_f32 v156, v158, v159
	v_pk_add_f32 v[158:159], v[36:37], v[132:133]
	v_cvt_pk_bf16_f32 v157, v178, v157
	global_store_dwordx4 v[160:161], v[154:157], off offset:256
	v_mul_f32_e32 v158, 0xbfb8aa3b, v158
	v_exp_f32_e32 v158, v158
	v_pk_add_f32 v[160:161], v[32:33], v[128:129]
	v_mul_f32_e32 v159, 0xbfb8aa3b, v159
	v_mul_f32_e32 v160, 0xbfb8aa3b, v160
	v_add_f32_e32 v158, 1.0, v158
	v_exp_f32_e32 v160, v160
	v_exp_f32_e32 v159, v159
	v_mul_f32_e32 v161, 0xbfb8aa3b, v161
	v_add_f32_e32 v160, 1.0, v160
	v_rcp_f32_e32 v158, v158
	v_add_f32_e32 v159, 1.0, v159
	v_rcp_f32_e32 v160, v160
	v_exp_f32_e32 v161, v161
	s_nop 0
	v_add_f32_e32 v161, 1.0, v161
	v_pk_add_f32 v[154:155], v[38:39], v[134:135]
	v_mul_f32_e32 v154, 0xbfb8aa3b, v154
	v_rcp_f32_e32 v159, v159
	v_exp_f32_e32 v154, v154
	s_nop 0
	v_add_f32_e32 v154, 1.0, v154
	v_pk_add_f32 v[156:157], v[34:35], v[130:131]
	v_mul_f32_e32 v156, 0xbfb8aa3b, v156
	v_rcp_f32_e32 v161, v161
	v_exp_f32_e32 v156, v156
	s_nop 0
	v_add_f32_e32 v156, 1.0, v156
	v_mul_f32_e32 v155, 0xbfb8aa3b, v155
	v_rcp_f32_e32 v175, v154
	v_exp_f32_e32 v155, v155
	s_nop 0
	v_add_f32_e32 v155, 1.0, v155
	v_mul_f32_e32 v157, 0xbfb8aa3b, v157
	v_rcp_f32_e32 v176, v156
	v_exp_f32_e32 v157, v157
	s_nop 0
	v_add_f32_e32 v157, 1.0, v157
	v_rcp_f32_e32 v155, v155
	v_rcp_f32_e32 v157, v157
	v_cvt_pk_bf16_f32 v154, v158, v159
	v_pk_add_f32 v[158:159], v[28:29], v[132:133]
	v_cvt_pk_bf16_f32 v155, v175, v155
	v_cvt_pk_bf16_f32 v156, v160, v161
	v_cvt_pk_bf16_f32 v157, v176, v157
	global_store_dwordx4 v[162:163], v[154:157], off offset:256
	v_mul_f32_e32 v158, 0xbfb8aa3b, v158
	v_exp_f32_e32 v158, v158
	v_pk_add_f32 v[160:161], v[24:25], v[128:129]
	v_mul_f32_e32 v159, 0xbfb8aa3b, v159
	v_mul_f32_e32 v160, 0xbfb8aa3b, v160
	v_add_f32_e32 v158, 1.0, v158
	v_exp_f32_e32 v160, v160
	v_exp_f32_e32 v159, v159
	v_mul_f32_e32 v161, 0xbfb8aa3b, v161
	v_add_f32_e32 v160, 1.0, v160
	v_rcp_f32_e32 v158, v158
	v_add_f32_e32 v159, 1.0, v159
	v_rcp_f32_e32 v160, v160
	v_exp_f32_e32 v161, v161
	s_nop 0
	v_add_f32_e32 v161, 1.0, v161
	v_pk_add_f32 v[154:155], v[30:31], v[134:135]
	v_mul_f32_e32 v154, 0xbfb8aa3b, v154
	v_rcp_f32_e32 v159, v159
	v_exp_f32_e32 v154, v154
	s_nop 0
	v_add_f32_e32 v154, 1.0, v154
	v_pk_add_f32 v[156:157], v[26:27], v[130:131]
	v_mul_f32_e32 v156, 0xbfb8aa3b, v156
	v_rcp_f32_e32 v161, v161
	v_exp_f32_e32 v156, v156
	s_nop 0
	v_add_f32_e32 v156, 1.0, v156
	v_mul_f32_e32 v155, 0xbfb8aa3b, v155
	v_rcp_f32_e32 v162, v154
	v_exp_f32_e32 v155, v155
	s_nop 0
	v_add_f32_e32 v155, 1.0, v155
	v_mul_f32_e32 v157, 0xbfb8aa3b, v157
	v_rcp_f32_e32 v163, v156
	v_exp_f32_e32 v157, v157
	s_nop 0
	v_add_f32_e32 v157, 1.0, v157
	v_rcp_f32_e32 v155, v155
	v_rcp_f32_e32 v157, v157
	v_cvt_pk_bf16_f32 v154, v158, v159
	v_pk_add_f32 v[158:159], v[20:21], v[132:133]
	v_cvt_pk_bf16_f32 v155, v162, v155
	v_cvt_pk_bf16_f32 v156, v160, v161
	v_cvt_pk_bf16_f32 v157, v163, v157
	v_pk_add_f32 v[160:161], v[16:17], v[128:129]
	v_mul_f32_e32 v158, 0xbfb8aa3b, v158
	v_exp_f32_e32 v158, v158
	v_mul_f32_e32 v160, 0xbfb8aa3b, v160
	global_store_dwordx4 v[164:165], v[154:157], off offset:256
	v_exp_f32_e32 v160, v160
	v_add_f32_e32 v158, 1.0, v158
	v_add_f32_e32 v160, 1.0, v160
	v_mul_f32_e32 v159, 0xbfb8aa3b, v159
	v_exp_f32_e32 v159, v159
	v_rcp_f32_e32 v158, v158
	v_add_f32_e32 v159, 1.0, v159
	v_mul_f32_e32 v161, 0xbfb8aa3b, v161
	v_rcp_f32_e32 v160, v160
	v_exp_f32_e32 v161, v161
; DI v4u pack8(const f4& a, const f4& b) { v4u w; w.x = cvt_pk_bf16(a[0], a[1]); w.y = cvt_pk_bf16(a[2], a[3]); w.z = cvt_pk_bf16(b[0], b[1]); w.w = cvt_pk_bf16(b[2], b[3]); return w; }
; DI float sigmoidf_(float z) { return 1.0f / (1.0f + __expf(-z)); }
;     DI void operator()(f4 (&acc)[2][2][4][2], const Unit& u, int wr, int wc, int fr, int fq) const {
;     ...
;         } else if (which == 1) {
; #pragma unroll
;             for (int bj = 0; bj < 2; ++bj) { const int col = col0 + bj * HALF; const f4 z0 = *(const f4*)(a0 + col), z1 = *(const f4*)(a0 + col + 4);
; #pragma unroll
;                 for (int ai = 0; ai < 2; ++ai)
; #pragma unroll
;                     for (int m = 0; m < 4; ++m) { const size_t off = (size_t)(row0 + ai * HALF + m * 16) * DB + col;
;                         f4 x0 = acc[ai][bj][m][0] + z0, x1 = acc[ai][bj][m][1] + z1;
; #pragma unroll
;                         for (int e = 0; e < 4; ++e) { x0[e] = sigmoidf_(x0[e]); x1[e] = sigmoidf_(x1[e]); }
;                         *(v4u*)(aout + off) = pack8(x0, x1);
;                         asm volatile("" ::: "memory"); } }
	s_nop 0
	v_add_f32_e32 v161, 1.0, v161
	v_pk_add_f32 v[154:155], v[22:23], v[134:135]
	v_mul_f32_e32 v154, 0xbfb8aa3b, v154
	v_rcp_f32_e32 v159, v159
	v_exp_f32_e32 v154, v154
	s_nop 0
	v_add_f32_e32 v154, 1.0, v154
	v_pk_add_f32 v[156:157], v[18:19], v[130:131]
	v_mul_f32_e32 v156, 0xbfb8aa3b, v156
	v_rcp_f32_e32 v161, v161
	v_exp_f32_e32 v156, v156
	s_nop 0
	v_add_f32_e32 v156, 1.0, v156
	v_mul_f32_e32 v155, 0xbfb8aa3b, v155
	v_rcp_f32_e32 v162, v154
	v_exp_f32_e32 v155, v155
	s_nop 0
	v_add_f32_e32 v155, 1.0, v155
	v_mul_f32_e32 v157, 0xbfb8aa3b, v157
	v_rcp_f32_e32 v163, v156
	v_exp_f32_e32 v157, v157
	s_nop 0
	v_add_f32_e32 v157, 1.0, v157
	v_rcp_f32_e32 v155, v155
	v_rcp_f32_e32 v157, v157
	v_cvt_pk_bf16_f32 v154, v158, v159
	v_pk_add_f32 v[158:159], v[12:13], v[132:133]
	v_cvt_pk_bf16_f32 v155, v162, v155
	v_cvt_pk_bf16_f32 v156, v160, v161
	v_cvt_pk_bf16_f32 v157, v163, v157
	v_pk_add_f32 v[160:161], v[8:9], v[128:129]
	v_mul_f32_e32 v158, 0xbfb8aa3b, v158
	v_exp_f32_e32 v158, v158
	v_mul_f32_e32 v160, 0xbfb8aa3b, v160
	v_exp_f32_e32 v160, v160
	global_store_dwordx4 v[166:167], v[154:157], off offset:256
	v_add_f32_e32 v158, 1.0, v158
	v_add_f32_e32 v160, 1.0, v160
	v_mul_f32_e32 v159, 0xbfb8aa3b, v159
	v_exp_f32_e32 v159, v159
	v_rcp_f32_e32 v158, v158
	v_add_f32_e32 v159, 1.0, v159
	v_mul_f32_e32 v161, 0xbfb8aa3b, v161
	v_rcp_f32_e32 v160, v160
	v_exp_f32_e32 v161, v161
	s_nop 0
	v_add_f32_e32 v161, 1.0, v161
	v_pk_add_f32 v[154:155], v[14:15], v[134:135]
	v_mul_f32_e32 v154, 0xbfb8aa3b, v154
	v_rcp_f32_e32 v159, v159
	v_exp_f32_e32 v154, v154
	s_nop 0
	v_add_f32_e32 v154, 1.0, v154
	v_pk_add_f32 v[156:157], v[10:11], v[130:131]
	v_mul_f32_e32 v156, 0xbfb8aa3b, v156
	v_rcp_f32_e32 v161, v161
	v_exp_f32_e32 v156, v156
	s_nop 0
	v_add_f32_e32 v156, 1.0, v156
	v_mul_f32_e32 v155, 0xbfb8aa3b, v155
	v_rcp_f32_e32 v162, v154
	v_exp_f32_e32 v155, v155
	s_nop 0
	v_add_f32_e32 v155, 1.0, v155
	v_mul_f32_e32 v157, 0xbfb8aa3b, v157
	v_rcp_f32_e32 v163, v156
	v_exp_f32_e32 v157, v157
	s_nop 0
	v_add_f32_e32 v157, 1.0, v157
	v_rcp_f32_e32 v155, v155
	v_pk_add_f32 v[132:133], v[4:5], v[132:133]
	v_mul_f32_e32 v132, 0xbfb8aa3b, v132
	v_exp_f32_e32 v132, v132
	v_rcp_f32_e32 v157, v157
	v_cvt_pk_bf16_f32 v154, v158, v159
	v_add_f32_e32 v132, 1.0, v132
	v_cvt_pk_bf16_f32 v155, v162, v155
	v_cvt_pk_bf16_f32 v156, v160, v161
	v_cvt_pk_bf16_f32 v157, v163, v157
	global_store_dwordx4 v[168:169], v[154:157], off offset:256
	v_pk_add_f32 v[128:129], v[0:1], v[128:129]
	v_mul_f32_e32 v133, 0xbfb8aa3b, v133
	v_mul_f32_e32 v128, 0xbfb8aa3b, v128
	v_exp_f32_e32 v128, v128
	v_exp_f32_e32 v133, v133
	v_add_f32_e32 v128, 1.0, v128
	v_rcp_f32_e32 v132, v132
	v_add_f32_e32 v133, 1.0, v133
	v_mul_f32_e32 v129, 0xbfb8aa3b, v129
	v_rcp_f32_e32 v154, v128
	v_exp_f32_e32 v129, v129
	s_nop 0
	v_add_f32_e32 v129, 1.0, v129
	v_pk_add_f32 v[134:135], v[6:7], v[134:135]
	v_mul_f32_e32 v134, 0xbfb8aa3b, v134
	v_rcp_f32_e32 v128, v133
	v_exp_f32_e32 v134, v134
	s_nop 0
	v_add_f32_e32 v134, 1.0, v134
	v_pk_add_f32 v[130:131], v[2:3], v[130:131]
	v_mul_f32_e32 v130, 0xbfb8aa3b, v130
	v_rcp_f32_e32 v133, v129
	v_exp_f32_e32 v130, v130
	s_nop 0
	v_add_f32_e32 v130, 1.0, v130
	v_mul_f32_e32 v135, 0xbfb8aa3b, v135
	v_rcp_f32_e32 v129, v134
	v_exp_f32_e32 v135, v135
	s_nop 0
	v_add_f32_e32 v135, 1.0, v135
	v_mul_f32_e32 v131, 0xbfb8aa3b, v131
	v_rcp_f32_e32 v134, v130
	v_exp_f32_e32 v131, v131
	s_nop 0
	v_add_f32_e32 v131, 1.0, v131
	v_rcp_f32_e32 v130, v135
	v_rcp_f32_e32 v131, v131
	v_cvt_pk_bf16_f32 v128, v132, v128
	v_cvt_pk_bf16_f32 v129, v129, v130
	v_cvt_pk_bf16_f32 v130, v154, v133
	v_cvt_pk_bf16_f32 v131, v134, v131
	global_store_dwordx4 v[152:153], v[128:131], off offset:256

; DI float sigmoidf_(float z) { return 1.0f / (1.0f + __expf(-z)); }
;     DI void operator()(f4 (&acc)[2][2][4][2], const Unit& u, int wr, int wc, int fr, int fq) const {
;     ...
;         if (which == 0) {
; #pragma unroll
;             for (int bj = 0; bj < 2; ++bj) { const int col = col0 + bj * HALF; const f4 z0 = *(const f4*)(w0 + col), z1 = *(const f4*)(w0 + col + 4);
; #pragma unroll
;                 for (int ai = 0; ai < 2; ++ai)
; #pragma unroll
;                     for (int m = 0; m < 4; ++m) { const size_t off = (size_t)(row0 + ai * HALF + m * 16) * DB + col;
;                         f4 x0 = acc[ai][bj][m][0] + z0, x1 = acc[ai][bj][m][1] + z1;
; #pragma unroll
;                         for (int e = 0; e < 4; ++e) { x0[e] = __expf(-0.6065306597126334f * sigmoidf_(x0[e])); x1[e] = __expf(-0.6065306597126334f * sigmoidf_(x1[e])); }
;                         { typedef _Float16 h2_ __attribute__((ext_vector_type(2)));
;                           const h2_ q0 = {(_Float16)x0[0], (_Float16)x0[1]}, q1 = {(_Float16)x0[2], (_Float16)x0[3]}, q2 = {(_Float16)x1[0], (_Float16)x1[1]}, q3 = {(_Float16)x1[2], (_Float16)x1[3]};
;                           v4u w_; w_.x = __builtin_bit_cast(unsigned, q0); w_.y = __builtin_bit_cast(unsigned, q1); w_.z = __builtin_bit_cast(unsigned, q2); w_.w = __builtin_bit_cast(unsigned, q3);
;                           *(v4u*)((_Float16*)decay + off) = w_; }
;                         asm volatile("" ::: "memory"); } }
.LBB0_2072:
	v_lshl_add_u64 v[152:153], v[150:151], 2, s[20:21]
	global_load_dwordx4 v[132:135], v[152:153], off
	global_load_dwordx4 v[128:131], v[152:153], off offset:16
	s_waitcnt vmcnt(0)
	v_pk_add_f32 v[124:125], v[124:125], v[132:133]
	v_pk_add_f32 v[120:121], v[120:121], v[128:129]
	v_mul_f32_e32 v124, 0xbfb8aa3b, v124
	v_mul_f32_e32 v120, 0xbfb8aa3b, v120
	v_exp_f32_e32 v124, v124
	v_mul_f32_e32 v125, 0xbfb8aa3b, v125
	v_exp_f32_e32 v120, v120
	v_pk_add_f32 v[126:127], v[126:127], v[134:135]
	v_mul_f32_e32 v121, 0xbfb8aa3b, v121
	v_exp_f32_e32 v125, v125
	v_mul_f32_e32 v126, 0xbfb8aa3b, v126
	v_exp_f32_e32 v121, v121
	v_exp_f32_e32 v126, v126
	v_add_f32_e32 v124, 1.0, v124
	v_add_f32_e32 v120, 1.0, v120
	v_add_f32_e32 v125, 1.0, v125
	v_add_f32_e32 v121, 1.0, v121
	v_add_f32_e32 v126, 1.0, v126
	v_pk_add_f32 v[122:123], v[122:123], v[130:131]
	v_mul_f32_e32 v122, 0xbfb8aa3b, v122
	v_exp_f32_e32 v122, v122
	v_rcp_f32_e32 v124, v124
	v_rcp_f32_e32 v120, v120
	v_rcp_f32_e32 v125, v125
	v_add_f32_e32 v122, 1.0, v122
	v_rcp_f32_e32 v121, v121
	v_rcp_f32_e32 v126, v126
	v_mul_f32_e32 v127, 0xbfb8aa3b, v127
	v_exp_f32_e32 v127, v127
	v_mul_f32_e32 v123, 0xbfb8aa3b, v123
	v_add_f32_e32 v127, 1.0, v127
	v_rcp_f32_e32 v122, v122
	v_exp_f32_e32 v123, v123
	v_mul_f32_e32 v124, 0xbf1b4598, v124
	v_mul_f32_e32 v120, 0xbf1b4598, v120
	v_add_f32_e32 v123, 1.0, v123
	v_rcp_f32_e32 v127, v127
	v_mul_f32_e32 v125, 0xbf1b4598, v125
	v_mul_f32_e32 v121, 0xbf1b4598, v121
	v_mul_f32_e32 v126, 0xbf1b4598, v126
	v_mul_f32_e32 v127, 0xbf1b4598, v127
	v_rcp_f32_e32 v123, v123
	v_mul_f32_e32 v124, 0x3fb8aa3b, v124
	v_mul_f32_e32 v120, 0x3fb8aa3b, v120
	v_mul_f32_e32 v125, 0x3fb8aa3b, v125
	v_mul_f32_e32 v121, 0x3fb8aa3b, v121
	v_mul_f32_e32 v126, 0x3fb8aa3b, v126
	v_mul_f32_e32 v122, 0xbf1b4598, v122
	v_mul_f32_e32 v127, 0x3fb8aa3b, v127
	v_mul_f32_e32 v123, 0xbf1b4598, v123
	v_exp_f32_e32 v124, v124
	v_exp_f32_e32 v120, v120
	v_exp_f32_e32 v125, v125
	v_exp_f32_e32 v121, v121
	v_exp_f32_e32 v126, v126
	v_mul_f32_e32 v122, 0x3fb8aa3b, v122
	v_exp_f32_e32 v127, v127
	v_mul_f32_e32 v123, 0x3fb8aa3b, v123
	v_pk_add_f32 v[116:117], v[116:117], v[132:133]
	v_exp_f32_e32 v122, v122
	v_exp_f32_e32 v123, v123
	v_mul_f32_e32 v116, 0xbfb8aa3b, v116
	v_exp_f32_e32 v116, v116
	v_cvt_pk_f16_f32 v124, v124, v125
	v_cvt_pk_f16_f32 v125, v126, v127
	v_cvt_pk_f16_f32 v126, v120, v121
	v_lshlrev_b64 v[120:121], 12, v[144:145]
	v_cvt_pk_f16_f32 v127, v122, v123
	v_lshl_add_u64 v[120:121], s[26:27], 0, v[120:121]
	v_lshlrev_b64 v[122:123], 1, v[150:151]
	v_lshl_add_u64 v[120:121], v[120:121], 0, v[122:123]
	v_add_f32_e32 v116, 1.0, v116
	global_store_dwordx4 v[120:121], v[124:127], off
	v_pk_add_f32 v[112:113], v[112:113], v[128:129]
	v_mul_f32_e32 v117, 0xbfb8aa3b, v117
	v_mul_f32_e32 v112, 0xbfb8aa3b, v112
	v_exp_f32_e32 v112, v112
	v_exp_f32_e32 v117, v117
	v_add_f32_e32 v112, 1.0, v112
	v_rcp_f32_e32 v116, v116
	v_add_f32_e32 v117, 1.0, v117
	v_mul_f32_e32 v113, 0xbfb8aa3b, v113
	v_exp_f32_e32 v113, v113
	v_rcp_f32_e32 v112, v112
	v_add_f32_e32 v113, 1.0, v113
	v_pk_add_f32 v[118:119], v[118:119], v[134:135]
	v_pk_add_f32 v[114:115], v[114:115], v[130:131]
	v_rcp_f32_e32 v117, v117
	v_mul_f32_e32 v118, 0xbfb8aa3b, v118
	v_exp_f32_e32 v118, v118
	v_mul_f32_e32 v114, 0xbfb8aa3b, v114
	v_add_f32_e32 v118, 1.0, v118
	v_rcp_f32_e32 v113, v113
	v_exp_f32_e32 v114, v114
	v_mul_f32_e32 v119, 0xbfb8aa3b, v119
	v_exp_f32_e32 v119, v119
	v_add_f32_e32 v114, 1.0, v114
	v_rcp_f32_e32 v118, v118
	v_add_f32_e32 v119, 1.0, v119
	v_mul_f32_e32 v115, 0xbfb8aa3b, v115
	v_exp_f32_e32 v115, v115
	v_rcp_f32_e32 v114, v114
	s_nop 0
	v_mul_f32_e32 v114, 0xbf1b4598, v114
	v_mul_f32_e32 v114, 0x3fb8aa3b, v114
	v_exp_f32_e32 v127, v114
	v_add_f32_e32 v115, 1.0, v115
	v_rcp_f32_e32 v114, v119
	s_nop 0
	v_mul_f32_e32 v114, 0xbf1b4598, v114
	v_mul_f32_e32 v114, 0x3fb8aa3b, v114
	v_exp_f32_e32 v126, v114
	v_mul_f32_e32 v116, 0xbf1b4598, v116
	v_mul_f32_e32 v112, 0xbf1b4598, v112
	v_mul_f32_e32 v117, 0xbf1b4598, v117
	v_mul_f32_e32 v113, 0xbf1b4598, v113
	v_mul_f32_e32 v116, 0x3fb8aa3b, v116
	v_mul_f32_e32 v112, 0x3fb8aa3b, v112
	v_mul_f32_e32 v117, 0x3fb8aa3b, v117
	v_mul_f32_e32 v113, 0x3fb8aa3b, v113
	v_rcp_f32_e32 v114, v115
	v_exp_f32_e32 v116, v116
	v_exp_f32_e32 v112, v112
	v_exp_f32_e32 v117, v117
	v_exp_f32_e32 v113, v113
	v_mul_f32_e32 v118, 0xbf1b4598, v118
	v_mul_f32_e32 v114, 0xbf1b4598, v114
	v_pk_add_f32 v[108:109], v[108:109], v[132:133]
	v_mul_f32_e32 v118, 0x3fb8aa3b, v118
	v_mul_f32_e32 v114, 0x3fb8aa3b, v114
	v_mul_f32_e32 v108, 0xbfb8aa3b, v108
	v_exp_f32_e32 v118, v118
	v_exp_f32_e32 v119, v114
	v_exp_f32_e32 v108, v108
	v_or_b32_e32 v124, 16, v144
	v_mov_b32_e32 v125, v145
	v_cvt_pk_f16_f32 v114, v116, v117
	v_cvt_pk_f16_f32 v116, v112, v113
	v_lshlrev_b64 v[112:113], 12, v[124:125]
	v_lshl_add_u64 v[112:113], s[26:27], 0, v[112:113]
	v_cvt_pk_f16_f32 v115, v118, v126
	v_cvt_pk_f16_f32 v117, v127, v119
	v_lshl_add_u64 v[112:113], v[112:113], 0, v[122:123]
	v_add_f32_e32 v108, 1.0, v108
	global_store_dwordx4 v[112:113], v[114:117], off
	v_pk_add_f32 v[104:105], v[104:105], v[128:129]
	v_mul_f32_e32 v109, 0xbfb8aa3b, v109
	v_mul_f32_e32 v104, 0xbfb8aa3b, v104
	v_exp_f32_e32 v104, v104
	v_exp_f32_e32 v109, v109
	v_add_f32_e32 v104, 1.0, v104
	v_rcp_f32_e32 v108, v108
	v_add_f32_e32 v109, 1.0, v109
	v_mul_f32_e32 v105, 0xbfb8aa3b, v105
	v_exp_f32_e32 v105, v105
	v_rcp_f32_e32 v104, v104
	v_add_f32_e32 v105, 1.0, v105
	v_pk_add_f32 v[110:111], v[110:111], v[134:135]
	v_pk_add_f32 v[106:107], v[106:107], v[130:131]
	v_rcp_f32_e32 v109, v109
	v_mul_f32_e32 v110, 0xbfb8aa3b, v110
; DI float sigmoidf_(float z) { return 1.0f / (1.0f + __expf(-z)); }
;     DI void operator()(f4 (&acc)[2][2][4][2], const Unit& u, int wr, int wc, int fr, int fq) const {
;     ...
;         if (which == 0) {
; #pragma unroll
;             for (int bj = 0; bj < 2; ++bj) { const int col = col0 + bj * HALF; const f4 z0 = *(const f4*)(w0 + col), z1 = *(const f4*)(w0 + col + 4);
; #pragma unroll
;                 for (int ai = 0; ai < 2; ++ai)
; #pragma unroll
;                     for (int m = 0; m < 4; ++m) { const size_t off = (size_t)(row0 + ai * HALF + m * 16) * DB + col;
;                         f4 x0 = acc[ai][bj][m][0] + z0, x1 = acc[ai][bj][m][1] + z1;
; #pragma unroll
;                         for (int e = 0; e < 4; ++e) { x0[e] = __expf(-0.6065306597126334f * sigmoidf_(x0[e])); x1[e] = __expf(-0.6065306597126334f * sigmoidf_(x1[e])); }
;                         { typedef _Float16 h2_ __attribute__((ext_vector_type(2)));
;                           const h2_ q0 = {(_Float16)x0[0], (_Float16)x0[1]}, q1 = {(_Float16)x0[2], (_Float16)x0[3]}, q2 = {(_Float16)x1[0], (_Float16)x1[1]}, q3 = {(_Float16)x1[2], (_Float16)x1[3]};
;                           v4u w_; w_.x = __builtin_bit_cast(unsigned, q0); w_.y = __builtin_bit_cast(unsigned, q1); w_.z = __builtin_bit_cast(unsigned, q2); w_.w = __builtin_bit_cast(unsigned, q3);
;                           *(v4u*)((_Float16*)decay + off) = w_; }
;                         asm volatile("" ::: "memory"); } }
	v_exp_f32_e32 v110, v110
	v_mul_f32_e32 v106, 0xbfb8aa3b, v106
	v_add_f32_e32 v110, 1.0, v110
	v_rcp_f32_e32 v105, v105
	v_exp_f32_e32 v106, v106
	v_mul_f32_e32 v111, 0xbfb8aa3b, v111
	v_exp_f32_e32 v111, v111
	v_add_f32_e32 v106, 1.0, v106
	v_rcp_f32_e32 v110, v110
	v_add_f32_e32 v111, 1.0, v111
	v_mul_f32_e32 v107, 0xbfb8aa3b, v107
	v_exp_f32_e32 v107, v107
	v_rcp_f32_e32 v106, v106
	s_nop 0
	v_mul_f32_e32 v106, 0xbf1b4598, v106
	v_mul_f32_e32 v106, 0x3fb8aa3b, v106
	v_exp_f32_e32 v117, v106
	v_add_f32_e32 v107, 1.0, v107
	v_rcp_f32_e32 v106, v111
	s_nop 0
	v_mul_f32_e32 v106, 0xbf1b4598, v106
	v_mul_f32_e32 v106, 0x3fb8aa3b, v106
	v_exp_f32_e32 v116, v106
	v_mul_f32_e32 v108, 0xbf1b4598, v108
	v_mul_f32_e32 v104, 0xbf1b4598, v104
	v_mul_f32_e32 v109, 0xbf1b4598, v109
	v_mul_f32_e32 v105, 0xbf1b4598, v105
	v_mul_f32_e32 v108, 0x3fb8aa3b, v108
	v_mul_f32_e32 v104, 0x3fb8aa3b, v104
	v_mul_f32_e32 v109, 0x3fb8aa3b, v109
	v_mul_f32_e32 v105, 0x3fb8aa3b, v105
	v_rcp_f32_e32 v106, v107
	v_exp_f32_e32 v108, v108
	v_exp_f32_e32 v104, v104
	v_exp_f32_e32 v109, v109
	v_exp_f32_e32 v105, v105
	v_mul_f32_e32 v110, 0xbf1b4598, v110
	v_mul_f32_e32 v106, 0xbf1b4598, v106
	v_pk_add_f32 v[100:101], v[100:101], v[132:133]
	v_mul_f32_e32 v110, 0x3fb8aa3b, v110
	v_mul_f32_e32 v106, 0x3fb8aa3b, v106
	v_mul_f32_e32 v100, 0xbfb8aa3b, v100
	v_exp_f32_e32 v110, v110
	v_exp_f32_e32 v111, v106
	v_exp_f32_e32 v100, v100
	v_or_b32_e32 v114, 32, v144
	v_mov_b32_e32 v115, v145
	v_cvt_pk_f16_f32 v106, v108, v109
	v_cvt_pk_f16_f32 v108, v104, v105
	v_lshlrev_b64 v[104:105], 12, v[114:115]
	v_lshl_add_u64 v[104:105], s[26:27], 0, v[104:105]
	v_cvt_pk_f16_f32 v107, v110, v116
	v_cvt_pk_f16_f32 v109, v117, v111
	v_lshl_add_u64 v[104:105], v[104:105], 0, v[122:123]
	v_add_f32_e32 v100, 1.0, v100
	global_store_dwordx4 v[104:105], v[106:109], off
	v_pk_add_f32 v[96:97], v[96:97], v[128:129]
	v_mul_f32_e32 v101, 0xbfb8aa3b, v101
	v_mul_f32_e32 v96, 0xbfb8aa3b, v96
	v_exp_f32_e32 v96, v96
	v_exp_f32_e32 v101, v101
	v_add_f32_e32 v96, 1.0, v96
	v_rcp_f32_e32 v100, v100
	v_add_f32_e32 v101, 1.0, v101
	v_mul_f32_e32 v97, 0xbfb8aa3b, v97
	v_exp_f32_e32 v97, v97
	v_rcp_f32_e32 v96, v96
	v_add_f32_e32 v97, 1.0, v97
	v_pk_add_f32 v[102:103], v[102:103], v[134:135]
	v_pk_add_f32 v[98:99], v[98:99], v[130:131]
	v_rcp_f32_e32 v101, v101
	v_mul_f32_e32 v102, 0xbfb8aa3b, v102
	v_exp_f32_e32 v102, v102
	v_mul_f32_e32 v98, 0xbfb8aa3b, v98
	v_add_f32_e32 v102, 1.0, v102
	v_rcp_f32_e32 v97, v97
	v_exp_f32_e32 v98, v98
	v_mul_f32_e32 v103, 0xbfb8aa3b, v103
	v_exp_f32_e32 v103, v103
	v_add_f32_e32 v98, 1.0, v98
	v_rcp_f32_e32 v102, v102
	v_add_f32_e32 v103, 1.0, v103
	v_mul_f32_e32 v99, 0xbfb8aa3b, v99
	v_exp_f32_e32 v99, v99
	v_rcp_f32_e32 v98, v98
	s_nop 0
	v_mul_f32_e32 v98, 0xbf1b4598, v98
	v_mul_f32_e32 v98, 0x3fb8aa3b, v98
	v_exp_f32_e32 v109, v98
	v_add_f32_e32 v99, 1.0, v99
	v_rcp_f32_e32 v98, v103
	s_nop 0
	v_mul_f32_e32 v98, 0xbf1b4598, v98
	v_mul_f32_e32 v98, 0x3fb8aa3b, v98
	v_exp_f32_e32 v108, v98
	v_mul_f32_e32 v100, 0xbf1b4598, v100
	v_mul_f32_e32 v96, 0xbf1b4598, v96
	v_mul_f32_e32 v101, 0xbf1b4598, v101
	v_mul_f32_e32 v97, 0xbf1b4598, v97
	v_mul_f32_e32 v100, 0x3fb8aa3b, v100
	v_mul_f32_e32 v96, 0x3fb8aa3b, v96
	v_mul_f32_e32 v101, 0x3fb8aa3b, v101
	v_mul_f32_e32 v97, 0x3fb8aa3b, v97
	v_rcp_f32_e32 v98, v99
	v_exp_f32_e32 v100, v100
	v_exp_f32_e32 v96, v96
	v_exp_f32_e32 v101, v101
	v_exp_f32_e32 v97, v97
	v_mul_f32_e32 v102, 0xbf1b4598, v102
	v_mul_f32_e32 v98, 0xbf1b4598, v98
	v_pk_add_f32 v[92:93], v[92:93], v[132:133]
	v_mul_f32_e32 v102, 0x3fb8aa3b, v102
	v_mul_f32_e32 v98, 0x3fb8aa3b, v98
	v_mul_f32_e32 v92, 0xbfb8aa3b, v92
	v_exp_f32_e32 v102, v102
	v_exp_f32_e32 v103, v98
	v_exp_f32_e32 v92, v92
	v_or_b32_e32 v106, 48, v144
	v_mov_b32_e32 v107, v145
	v_cvt_pk_f16_f32 v98, v100, v101
	v_cvt_pk_f16_f32 v100, v96, v97
	v_lshlrev_b64 v[96:97], 12, v[106:107]
	v_lshl_add_u64 v[96:97], s[26:27], 0, v[96:97]
	v_cvt_pk_f16_f32 v99, v102, v108
	v_cvt_pk_f16_f32 v101, v109, v103
	v_lshl_add_u64 v[96:97], v[96:97], 0, v[122:123]
	v_add_f32_e32 v92, 1.0, v92
	global_store_dwordx4 v[96:97], v[98:101], off
	v_pk_add_f32 v[88:89], v[88:89], v[128:129]
	v_mul_f32_e32 v93, 0xbfb8aa3b, v93
	v_mul_f32_e32 v88, 0xbfb8aa3b, v88
	v_exp_f32_e32 v88, v88
	v_exp_f32_e32 v93, v93
	v_add_f32_e32 v88, 1.0, v88
	v_rcp_f32_e32 v92, v92
	v_add_f32_e32 v93, 1.0, v93
	v_mul_f32_e32 v89, 0xbfb8aa3b, v89
	v_exp_f32_e32 v89, v89
	v_rcp_f32_e32 v88, v88
	v_add_f32_e32 v89, 1.0, v89
	v_pk_add_f32 v[94:95], v[94:95], v[134:135]
	v_pk_add_f32 v[90:91], v[90:91], v[130:131]
	v_rcp_f32_e32 v93, v93
	v_mul_f32_e32 v94, 0xbfb8aa3b, v94
	v_exp_f32_e32 v94, v94
	v_mul_f32_e32 v90, 0xbfb8aa3b, v90
	v_add_f32_e32 v94, 1.0, v94
	v_rcp_f32_e32 v89, v89
	v_exp_f32_e32 v90, v90
	v_mul_f32_e32 v95, 0xbfb8aa3b, v95
	v_exp_f32_e32 v95, v95
	v_add_f32_e32 v90, 1.0, v90
	v_rcp_f32_e32 v94, v94
	v_add_f32_e32 v95, 1.0, v95
	v_mul_f32_e32 v91, 0xbfb8aa3b, v91
	v_exp_f32_e32 v91, v91
	v_rcp_f32_e32 v90, v90
	s_nop 0
	v_mul_f32_e32 v90, 0xbf1b4598, v90
	v_mul_f32_e32 v90, 0x3fb8aa3b, v90
	v_exp_f32_e32 v101, v90
	v_add_f32_e32 v91, 1.0, v91
	v_rcp_f32_e32 v90, v95
	s_nop 0
	v_mul_f32_e32 v90, 0xbf1b4598, v90
	v_mul_f32_e32 v90, 0x3fb8aa3b, v90
	v_exp_f32_e32 v100, v90
	v_mul_f32_e32 v92, 0xbf1b4598, v92
	v_mul_f32_e32 v88, 0xbf1b4598, v88
	v_mul_f32_e32 v93, 0xbf1b4598, v93
	v_mul_f32_e32 v89, 0xbf1b4598, v89
	v_mul_f32_e32 v92, 0x3fb8aa3b, v92
	v_mul_f32_e32 v88, 0x3fb8aa3b, v88
	v_mul_f32_e32 v93, 0x3fb8aa3b, v93
	v_mul_f32_e32 v89, 0x3fb8aa3b, v89
	v_rcp_f32_e32 v90, v91
	v_exp_f32_e32 v92, v92
	v_exp_f32_e32 v88, v88
; DI float sigmoidf_(float z) { return 1.0f / (1.0f + __expf(-z)); }
;     DI void operator()(f4 (&acc)[2][2][4][2], const Unit& u, int wr, int wc, int fr, int fq) const {
;     ...
;         if (which == 0) {
; #pragma unroll
;             for (int bj = 0; bj < 2; ++bj) { const int col = col0 + bj * HALF; const f4 z0 = *(const f4*)(w0 + col), z1 = *(const f4*)(w0 + col + 4);
; #pragma unroll
;                 for (int ai = 0; ai < 2; ++ai)
; #pragma unroll
;                     for (int m = 0; m < 4; ++m) { const size_t off = (size_t)(row0 + ai * HALF + m * 16) * DB + col;
;                         f4 x0 = acc[ai][bj][m][0] + z0, x1 = acc[ai][bj][m][1] + z1;
; #pragma unroll
;                         for (int e = 0; e < 4; ++e) { x0[e] = __expf(-0.6065306597126334f * sigmoidf_(x0[e])); x1[e] = __expf(-0.6065306597126334f * sigmoidf_(x1[e])); }
;                         { typedef _Float16 h2_ __attribute__((ext_vector_type(2)));
;                           const h2_ q0 = {(_Float16)x0[0], (_Float16)x0[1]}, q1 = {(_Float16)x0[2], (_Float16)x0[3]}, q2 = {(_Float16)x1[0], (_Float16)x1[1]}, q3 = {(_Float16)x1[2], (_Float16)x1[3]};
;                           v4u w_; w_.x = __builtin_bit_cast(unsigned, q0); w_.y = __builtin_bit_cast(unsigned, q1); w_.z = __builtin_bit_cast(unsigned, q2); w_.w = __builtin_bit_cast(unsigned, q3);
;                           *(v4u*)((_Float16*)decay + off) = w_; }
;                         asm volatile("" ::: "memory"); } }
	v_exp_f32_e32 v93, v93
	v_exp_f32_e32 v89, v89
	v_mul_f32_e32 v94, 0xbf1b4598, v94
	v_mul_f32_e32 v90, 0xbf1b4598, v90
	v_pk_add_f32 v[84:85], v[84:85], v[132:133]
	v_mul_f32_e32 v94, 0x3fb8aa3b, v94
	v_mul_f32_e32 v90, 0x3fb8aa3b, v90
	v_mul_f32_e32 v84, 0xbfb8aa3b, v84
	v_exp_f32_e32 v94, v94
	v_exp_f32_e32 v95, v90
	v_exp_f32_e32 v84, v84
	v_add_u32_e32 v98, 0x80, v144
	v_mov_b32_e32 v99, v145
	v_cvt_pk_f16_f32 v90, v92, v93
	v_cvt_pk_f16_f32 v92, v88, v89
	v_lshlrev_b64 v[88:89], 12, v[98:99]
	v_lshl_add_u64 v[88:89], s[26:27], 0, v[88:89]
	v_cvt_pk_f16_f32 v91, v94, v100
	v_cvt_pk_f16_f32 v93, v101, v95
	v_lshl_add_u64 v[88:89], v[88:89], 0, v[122:123]
	v_add_f32_e32 v84, 1.0, v84
	global_store_dwordx4 v[88:89], v[90:93], off
	v_pk_add_f32 v[80:81], v[80:81], v[128:129]
	v_mul_f32_e32 v85, 0xbfb8aa3b, v85
	v_mul_f32_e32 v80, 0xbfb8aa3b, v80
	v_exp_f32_e32 v80, v80
	v_exp_f32_e32 v85, v85
	v_add_f32_e32 v80, 1.0, v80
	v_rcp_f32_e32 v84, v84
	v_add_f32_e32 v85, 1.0, v85
	v_mul_f32_e32 v81, 0xbfb8aa3b, v81
	v_exp_f32_e32 v81, v81
	v_rcp_f32_e32 v80, v80
	v_add_f32_e32 v81, 1.0, v81
	v_pk_add_f32 v[86:87], v[86:87], v[134:135]
	v_pk_add_f32 v[82:83], v[82:83], v[130:131]
	v_rcp_f32_e32 v85, v85
	v_mul_f32_e32 v86, 0xbfb8aa3b, v86
	v_exp_f32_e32 v86, v86
	v_mul_f32_e32 v82, 0xbfb8aa3b, v82
	v_add_f32_e32 v86, 1.0, v86
	v_rcp_f32_e32 v81, v81
	v_exp_f32_e32 v82, v82
	v_mul_f32_e32 v87, 0xbfb8aa3b, v87
	v_exp_f32_e32 v87, v87
	v_add_f32_e32 v82, 1.0, v82
	v_rcp_f32_e32 v86, v86
	v_add_f32_e32 v87, 1.0, v87
	v_mul_f32_e32 v83, 0xbfb8aa3b, v83
	v_exp_f32_e32 v83, v83
	v_rcp_f32_e32 v82, v82
	s_nop 0
	v_mul_f32_e32 v82, 0xbf1b4598, v82
	v_mul_f32_e32 v82, 0x3fb8aa3b, v82
	v_exp_f32_e32 v93, v82
	v_add_f32_e32 v83, 1.0, v83
	v_rcp_f32_e32 v82, v87
	s_nop 0
	v_mul_f32_e32 v82, 0xbf1b4598, v82
	v_mul_f32_e32 v82, 0x3fb8aa3b, v82
	v_exp_f32_e32 v92, v82
	v_mul_f32_e32 v84, 0xbf1b4598, v84
	v_mul_f32_e32 v80, 0xbf1b4598, v80
	v_mul_f32_e32 v85, 0xbf1b4598, v85
	v_mul_f32_e32 v81, 0xbf1b4598, v81
	v_mul_f32_e32 v84, 0x3fb8aa3b, v84
	v_mul_f32_e32 v80, 0x3fb8aa3b, v80
	v_mul_f32_e32 v85, 0x3fb8aa3b, v85
	v_mul_f32_e32 v81, 0x3fb8aa3b, v81
	v_rcp_f32_e32 v82, v83
	v_exp_f32_e32 v84, v84
	v_exp_f32_e32 v80, v80
	v_exp_f32_e32 v85, v85
	v_exp_f32_e32 v81, v81
	v_mul_f32_e32 v86, 0xbf1b4598, v86
	v_mul_f32_e32 v82, 0xbf1b4598, v82
	v_pk_add_f32 v[76:77], v[76:77], v[132:133]
	v_mul_f32_e32 v86, 0x3fb8aa3b, v86
	v_mul_f32_e32 v82, 0x3fb8aa3b, v82
	v_mul_f32_e32 v76, 0xbfb8aa3b, v76
	v_exp_f32_e32 v86, v86
	v_exp_f32_e32 v87, v82
	v_exp_f32_e32 v76, v76
	v_add_u32_e32 v90, 0x90, v144
	v_mov_b32_e32 v91, v145
	v_cvt_pk_f16_f32 v82, v84, v85
	v_cvt_pk_f16_f32 v84, v80, v81
	v_lshlrev_b64 v[80:81], 12, v[90:91]
	v_lshl_add_u64 v[80:81], s[26:27], 0, v[80:81]
	v_cvt_pk_f16_f32 v83, v86, v92
	v_cvt_pk_f16_f32 v85, v93, v87
	v_lshl_add_u64 v[80:81], v[80:81], 0, v[122:123]
	v_add_f32_e32 v76, 1.0, v76
	global_store_dwordx4 v[80:81], v[82:85], off
	v_pk_add_f32 v[72:73], v[72:73], v[128:129]
	v_mul_f32_e32 v77, 0xbfb8aa3b, v77
	v_mul_f32_e32 v72, 0xbfb8aa3b, v72
	v_exp_f32_e32 v72, v72
	v_exp_f32_e32 v77, v77
	v_add_f32_e32 v72, 1.0, v72
	v_rcp_f32_e32 v76, v76
	v_add_f32_e32 v77, 1.0, v77
	v_mul_f32_e32 v73, 0xbfb8aa3b, v73
	v_exp_f32_e32 v73, v73
	v_rcp_f32_e32 v72, v72
	v_add_f32_e32 v73, 1.0, v73
	v_pk_add_f32 v[78:79], v[78:79], v[134:135]
	v_pk_add_f32 v[74:75], v[74:75], v[130:131]
	v_rcp_f32_e32 v77, v77
	v_mul_f32_e32 v78, 0xbfb8aa3b, v78
	v_exp_f32_e32 v78, v78
	v_mul_f32_e32 v74, 0xbfb8aa3b, v74
	v_add_f32_e32 v78, 1.0, v78
	v_rcp_f32_e32 v73, v73
	v_exp_f32_e32 v74, v74
	v_mul_f32_e32 v79, 0xbfb8aa3b, v79
	v_exp_f32_e32 v79, v79
	v_add_f32_e32 v74, 1.0, v74
	v_rcp_f32_e32 v78, v78
	v_add_f32_e32 v79, 1.0, v79
	v_mul_f32_e32 v75, 0xbfb8aa3b, v75
	v_exp_f32_e32 v75, v75
	v_rcp_f32_e32 v74, v74
	s_nop 0
	v_mul_f32_e32 v74, 0xbf1b4598, v74
	v_mul_f32_e32 v74, 0x3fb8aa3b, v74
	v_exp_f32_e32 v85, v74
	v_add_f32_e32 v75, 1.0, v75
	v_rcp_f32_e32 v74, v79
	s_nop 0
	v_mul_f32_e32 v74, 0xbf1b4598, v74
	v_mul_f32_e32 v74, 0x3fb8aa3b, v74
	v_exp_f32_e32 v84, v74
	v_mul_f32_e32 v76, 0xbf1b4598, v76
	v_mul_f32_e32 v72, 0xbf1b4598, v72
	v_mul_f32_e32 v77, 0xbf1b4598, v77
	v_mul_f32_e32 v73, 0xbf1b4598, v73
	v_mul_f32_e32 v76, 0x3fb8aa3b, v76
	v_mul_f32_e32 v72, 0x3fb8aa3b, v72
	v_mul_f32_e32 v77, 0x3fb8aa3b, v77
	v_mul_f32_e32 v73, 0x3fb8aa3b, v73
	v_rcp_f32_e32 v74, v75
	v_exp_f32_e32 v76, v76
	v_exp_f32_e32 v72, v72
	v_exp_f32_e32 v77, v77
	v_exp_f32_e32 v73, v73
	v_mul_f32_e32 v78, 0xbf1b4598, v78
	v_mul_f32_e32 v74, 0xbf1b4598, v74
	v_pk_add_f32 v[68:69], v[68:69], v[132:133]
	v_mul_f32_e32 v78, 0x3fb8aa3b, v78
	v_mul_f32_e32 v74, 0x3fb8aa3b, v74
	v_mul_f32_e32 v68, 0xbfb8aa3b, v68
	v_exp_f32_e32 v78, v78
	v_exp_f32_e32 v79, v74
	v_exp_f32_e32 v68, v68
	v_add_u32_e32 v82, 0xa0, v144
	v_mov_b32_e32 v83, v145
	v_cvt_pk_f16_f32 v74, v76, v77
	v_cvt_pk_f16_f32 v76, v72, v73
	v_lshlrev_b64 v[72:73], 12, v[82:83]
	v_lshl_add_u64 v[72:73], s[26:27], 0, v[72:73]
	v_cvt_pk_f16_f32 v75, v78, v84
	v_cvt_pk_f16_f32 v77, v85, v79
	v_lshl_add_u64 v[72:73], v[72:73], 0, v[122:123]
	v_add_f32_e32 v68, 1.0, v68
	global_store_dwordx4 v[72:73], v[74:77], off
	v_pk_add_f32 v[64:65], v[64:65], v[128:129]
	v_mul_f32_e32 v69, 0xbfb8aa3b, v69
	v_mul_f32_e32 v64, 0xbfb8aa3b, v64
	v_exp_f32_e32 v64, v64
	v_exp_f32_e32 v69, v69
	v_add_f32_e32 v64, 1.0, v64
	v_rcp_f32_e32 v68, v68
	v_add_f32_e32 v69, 1.0, v69
	v_mul_f32_e32 v65, 0xbfb8aa3b, v65
	v_exp_f32_e32 v65, v65
	v_rcp_f32_e32 v64, v64
	s_nop 0
	v_mul_f32_e32 v64, 0xbf1b4598, v64
	v_mul_f32_e32 v64, 0x3fb8aa3b, v64
	v_exp_f32_e32 v76, v64
; DI float sigmoidf_(float z) { return 1.0f / (1.0f + __expf(-z)); }
;     DI void operator()(f4 (&acc)[2][2][4][2], const Unit& u, int wr, int wc, int fr, int fq) const {
;     ...
;             for (int bj = 0; bj < 2; ++bj) { const int col = col0 + bj * HALF; const f4 z0 = *(const f4*)(w0 + col), z1 = *(const f4*)(w0 + col + 4);
; #pragma unroll
;                 for (int ai = 0; ai < 2; ++ai)
; #pragma unroll
;                     for (int m = 0; m < 4; ++m) { const size_t off = (size_t)(row0 + ai * HALF + m * 16) * DB + col;
;                         f4 x0 = acc[ai][bj][m][0] + z0, x1 = acc[ai][bj][m][1] + z1;
; #pragma unroll
;                         for (int e = 0; e < 4; ++e) { x0[e] = __expf(-0.6065306597126334f * sigmoidf_(x0[e])); x1[e] = __expf(-0.6065306597126334f * sigmoidf_(x1[e])); }
;                         { typedef _Float16 h2_ __attribute__((ext_vector_type(2)));
;                           const h2_ q0 = {(_Float16)x0[0], (_Float16)x0[1]}, q1 = {(_Float16)x0[2], (_Float16)x0[3]}, q2 = {(_Float16)x1[0], (_Float16)x1[1]}, q3 = {(_Float16)x1[2], (_Float16)x1[3]};
;                           v4u w_; w_.x = __builtin_bit_cast(unsigned, q0); w_.y = __builtin_bit_cast(unsigned, q1); w_.z = __builtin_bit_cast(unsigned, q2); w_.w = __builtin_bit_cast(unsigned, q3);
;                           *(v4u*)((_Float16*)decay + off) = w_; }
;                         asm volatile("" ::: "memory"); } }
	v_add_f32_e32 v65, 1.0, v65
	v_rcp_f32_e32 v64, v69
	v_pk_add_f32 v[70:71], v[70:71], v[134:135]
	v_pk_add_f32 v[66:67], v[66:67], v[130:131]
	v_mul_f32_e32 v70, 0xbfb8aa3b, v70
	v_exp_f32_e32 v70, v70
	v_rcp_f32_e32 v65, v65
	v_add_f32_e32 v69, 1.0, v70
	v_mul_f32_e32 v65, 0xbf1b4598, v65
	v_mul_f32_e32 v65, 0x3fb8aa3b, v65
	v_exp_f32_e32 v75, v65
	v_mul_f32_e32 v66, 0xbfb8aa3b, v66
	v_exp_f32_e32 v66, v66
	s_nop 0
	v_add_f32_e32 v66, 1.0, v66
	v_rcp_f32_e32 v65, v69
	v_mul_f32_e32 v71, 0xbfb8aa3b, v71
	v_exp_f32_e32 v71, v71
	v_mul_f32_e32 v67, 0xbfb8aa3b, v67
	v_rcp_f32_e32 v66, v66
	v_add_f32_e32 v69, 1.0, v71
	v_mul_f32_e32 v66, 0xbf1b4598, v66
	v_mul_f32_e32 v66, 0x3fb8aa3b, v66
	v_exp_f32_e32 v74, v66
	v_exp_f32_e32 v67, v67
	s_nop 0
	v_add_f32_e32 v67, 1.0, v67
	v_rcp_f32_e32 v66, v69
	v_mul_f32_e32 v68, 0xbf1b4598, v68
	v_mul_f32_e32 v64, 0xbf1b4598, v64
	v_mul_f32_e32 v68, 0x3fb8aa3b, v68
	v_mul_f32_e32 v64, 0x3fb8aa3b, v64
	v_rcp_f32_e32 v67, v67
	v_exp_f32_e32 v68, v68
	v_exp_f32_e32 v64, v64
	v_mul_f32_e32 v65, 0xbf1b4598, v65
	v_mul_f32_e32 v66, 0xbf1b4598, v66
	v_mul_f32_e32 v67, 0xbf1b4598, v67
	v_mul_f32_e32 v65, 0x3fb8aa3b, v65
	v_mul_f32_e32 v66, 0x3fb8aa3b, v66
	v_mul_f32_e32 v67, 0x3fb8aa3b, v67
	v_exp_f32_e32 v65, v65
	v_exp_f32_e32 v66, v66
	v_exp_f32_e32 v67, v67
	v_add_u32_e32 v144, 0xb0, v144
	v_cvt_pk_f16_f32 v64, v68, v64
	v_lshlrev_b64 v[68:69], 12, v[144:145]
	v_lshl_add_u64 v[68:69], s[26:27], 0, v[68:69]
	v_cvt_pk_f16_f32 v65, v65, v66
	v_cvt_pk_f16_f32 v66, v76, v75
	v_cvt_pk_f16_f32 v67, v74, v67
	v_lshl_add_u64 v[74:75], v[68:69], 0, v[122:123]
	global_store_dwordx4 v[74:75], v[64:67], off
	global_load_dwordx4 v[68:71], v[152:153], off offset:512
	global_load_dwordx4 v[64:67], v[152:153], off offset:528
	s_waitcnt vmcnt(0)
	v_pk_add_f32 v[60:61], v[60:61], v[68:69]
	s_nop 0
	v_mul_f32_e32 v60, 0xbfb8aa3b, v60
	v_exp_f32_e32 v60, v60
	v_pk_add_f32 v[56:57], v[56:57], v[64:65]
	v_mul_f32_e32 v61, 0xbfb8aa3b, v61
	v_mul_f32_e32 v56, 0xbfb8aa3b, v56
	v_add_f32_e32 v60, 1.0, v60
	v_exp_f32_e32 v56, v56
	v_exp_f32_e32 v61, v61
	v_mul_f32_e32 v57, 0xbfb8aa3b, v57
	v_add_f32_e32 v56, 1.0, v56
	v_rcp_f32_e32 v60, v60
	v_add_f32_e32 v61, 1.0, v61
	v_exp_f32_e32 v57, v57
	v_pk_add_f32 v[62:63], v[62:63], v[70:71]
	v_rcp_f32_e32 v56, v56
	s_nop 0
	v_mul_f32_e32 v56, 0xbf1b4598, v56
	v_mul_f32_e32 v56, 0x3fb8aa3b, v56
	v_exp_f32_e32 v78, v56
	v_add_f32_e32 v57, 1.0, v57
	v_rcp_f32_e32 v56, v61
	v_mul_f32_e32 v62, 0xbfb8aa3b, v62
	v_exp_f32_e32 v62, v62
	v_pk_add_f32 v[58:59], v[58:59], v[66:67]
	v_rcp_f32_e32 v57, v57
	v_add_f32_e32 v61, 1.0, v62
	v_mul_f32_e32 v57, 0xbf1b4598, v57
	v_mul_f32_e32 v57, 0x3fb8aa3b, v57
	v_exp_f32_e32 v77, v57
	v_mul_f32_e32 v58, 0xbfb8aa3b, v58
	v_exp_f32_e32 v58, v58
	s_nop 0
	v_add_f32_e32 v58, 1.0, v58
	v_rcp_f32_e32 v57, v61
	v_mul_f32_e32 v63, 0xbfb8aa3b, v63
	v_exp_f32_e32 v63, v63
	v_mul_f32_e32 v59, 0xbfb8aa3b, v59
	v_rcp_f32_e32 v58, v58
	v_add_f32_e32 v61, 1.0, v63
	v_mul_f32_e32 v58, 0xbf1b4598, v58
	v_mul_f32_e32 v58, 0x3fb8aa3b, v58
	v_exp_f32_e32 v76, v58
	v_exp_f32_e32 v59, v59
	s_nop 0
	v_add_f32_e32 v59, 1.0, v59
	v_rcp_f32_e32 v58, v61
	v_mul_f32_e32 v60, 0xbf1b4598, v60
	v_mul_f32_e32 v56, 0xbf1b4598, v56
	v_mul_f32_e32 v57, 0xbf1b4598, v57
	v_rcp_f32_e32 v59, v59
	v_mul_f32_e32 v58, 0xbf1b4598, v58
	v_mul_f32_e32 v59, 0xbf1b4598, v59
	v_pk_add_f32 v[52:53], v[52:53], v[68:69]
	v_mul_f32_e32 v60, 0x3fb8aa3b, v60
	v_mul_f32_e32 v56, 0x3fb8aa3b, v56
	v_mul_f32_e32 v57, 0x3fb8aa3b, v57
	v_mul_f32_e32 v58, 0x3fb8aa3b, v58
	v_mul_f32_e32 v59, 0x3fb8aa3b, v59
	v_mul_f32_e32 v52, 0xbfb8aa3b, v52
	v_exp_f32_e32 v60, v60
	v_exp_f32_e32 v56, v56
	v_exp_f32_e32 v57, v57
	v_exp_f32_e32 v58, v58
	v_exp_f32_e32 v59, v59
	v_exp_f32_e32 v52, v52
	v_cvt_pk_f16_f32 v56, v60, v56
	v_cvt_pk_f16_f32 v57, v57, v58
	v_cvt_pk_f16_f32 v58, v78, v77
	v_cvt_pk_f16_f32 v59, v76, v59
	v_add_f32_e32 v52, 1.0, v52
	global_store_dwordx4 v[120:121], v[56:59], off offset:256
	v_pk_add_f32 v[48:49], v[48:49], v[64:65]
	v_mul_f32_e32 v53, 0xbfb8aa3b, v53
	v_mul_f32_e32 v48, 0xbfb8aa3b, v48
	v_exp_f32_e32 v48, v48
	v_exp_f32_e32 v53, v53
	v_add_f32_e32 v48, 1.0, v48
	v_rcp_f32_e32 v52, v52
	v_add_f32_e32 v53, 1.0, v53
	v_mul_f32_e32 v49, 0xbfb8aa3b, v49
	v_exp_f32_e32 v49, v49
	v_rcp_f32_e32 v48, v48
	s_nop 0
	v_mul_f32_e32 v48, 0xbf1b4598, v48
	v_mul_f32_e32 v48, 0x3fb8aa3b, v48
	v_exp_f32_e32 v58, v48
	v_add_f32_e32 v49, 1.0, v49
	v_rcp_f32_e32 v48, v53
	v_pk_add_f32 v[54:55], v[54:55], v[70:71]
	v_pk_add_f32 v[50:51], v[50:51], v[66:67]
	v_mul_f32_e32 v54, 0xbfb8aa3b, v54
	v_exp_f32_e32 v54, v54
	v_rcp_f32_e32 v49, v49
	v_add_f32_e32 v53, 1.0, v54
	v_mul_f32_e32 v49, 0xbf1b4598, v49
	v_mul_f32_e32 v49, 0x3fb8aa3b, v49
	v_exp_f32_e32 v57, v49
	v_mul_f32_e32 v50, 0xbfb8aa3b, v50
	v_exp_f32_e32 v50, v50
	s_nop 0
	v_add_f32_e32 v50, 1.0, v50
	v_rcp_f32_e32 v49, v53
	v_mul_f32_e32 v55, 0xbfb8aa3b, v55
	v_exp_f32_e32 v55, v55
	v_mul_f32_e32 v51, 0xbfb8aa3b, v51
	v_rcp_f32_e32 v50, v50
	v_add_f32_e32 v53, 1.0, v55
	v_mul_f32_e32 v50, 0xbf1b4598, v50
	v_mul_f32_e32 v50, 0x3fb8aa3b, v50
	v_exp_f32_e32 v56, v50
	v_exp_f32_e32 v51, v51
	s_nop 0
	v_add_f32_e32 v51, 1.0, v51
	v_rcp_f32_e32 v50, v53
	v_mul_f32_e32 v52, 0xbf1b4598, v52
	v_mul_f32_e32 v48, 0xbf1b4598, v48
	v_mul_f32_e32 v49, 0xbf1b4598, v49
	v_rcp_f32_e32 v51, v51
	v_mul_f32_e32 v50, 0xbf1b4598, v50
	v_mul_f32_e32 v51, 0xbf1b4598, v51
	v_pk_add_f32 v[44:45], v[44:45], v[68:69]
	v_mul_f32_e32 v52, 0x3fb8aa3b, v52
	v_mul_f32_e32 v48, 0x3fb8aa3b, v48
	v_mul_f32_e32 v49, 0x3fb8aa3b, v49
	v_mul_f32_e32 v50, 0x3fb8aa3b, v50
	v_mul_f32_e32 v51, 0x3fb8aa3b, v51
; DI float sigmoidf_(float z) { return 1.0f / (1.0f + __expf(-z)); }
;     DI void operator()(f4 (&acc)[2][2][4][2], const Unit& u, int wr, int wc, int fr, int fq) const {
;     ...
;             for (int bj = 0; bj < 2; ++bj) { const int col = col0 + bj * HALF; const f4 z0 = *(const f4*)(w0 + col), z1 = *(const f4*)(w0 + col + 4);
; #pragma unroll
;                 for (int ai = 0; ai < 2; ++ai)
; #pragma unroll
;                     for (int m = 0; m < 4; ++m) { const size_t off = (size_t)(row0 + ai * HALF + m * 16) * DB + col;
;                         f4 x0 = acc[ai][bj][m][0] + z0, x1 = acc[ai][bj][m][1] + z1;
; #pragma unroll
;                         for (int e = 0; e < 4; ++e) { x0[e] = __expf(-0.6065306597126334f * sigmoidf_(x0[e])); x1[e] = __expf(-0.6065306597126334f * sigmoidf_(x1[e])); }
;                         { typedef _Float16 h2_ __attribute__((ext_vector_type(2)));
;                           const h2_ q0 = {(_Float16)x0[0], (_Float16)x0[1]}, q1 = {(_Float16)x0[2], (_Float16)x0[3]}, q2 = {(_Float16)x1[0], (_Float16)x1[1]}, q3 = {(_Float16)x1[2], (_Float16)x1[3]};
;                           v4u w_; w_.x = __builtin_bit_cast(unsigned, q0); w_.y = __builtin_bit_cast(unsigned, q1); w_.z = __builtin_bit_cast(unsigned, q2); w_.w = __builtin_bit_cast(unsigned, q3);
;                           *(v4u*)((_Float16*)decay + off) = w_; }
;                         asm volatile("" ::: "memory"); } }
	v_mul_f32_e32 v44, 0xbfb8aa3b, v44
	v_exp_f32_e32 v52, v52
	v_exp_f32_e32 v48, v48
	v_exp_f32_e32 v49, v49
	v_exp_f32_e32 v50, v50
	v_exp_f32_e32 v51, v51
	v_exp_f32_e32 v44, v44
	v_cvt_pk_f16_f32 v48, v52, v48
	v_cvt_pk_f16_f32 v49, v49, v50
	v_cvt_pk_f16_f32 v50, v58, v57
	v_cvt_pk_f16_f32 v51, v56, v51
	v_add_f32_e32 v44, 1.0, v44
	global_store_dwordx4 v[112:113], v[48:51], off offset:256
	v_pk_add_f32 v[40:41], v[40:41], v[64:65]
	v_mul_f32_e32 v45, 0xbfb8aa3b, v45
	v_mul_f32_e32 v40, 0xbfb8aa3b, v40
	v_exp_f32_e32 v40, v40
	v_exp_f32_e32 v45, v45
	v_add_f32_e32 v40, 1.0, v40
	v_rcp_f32_e32 v44, v44
	v_add_f32_e32 v45, 1.0, v45
	v_mul_f32_e32 v41, 0xbfb8aa3b, v41
	v_exp_f32_e32 v41, v41
	v_rcp_f32_e32 v40, v40
	s_nop 0
	v_mul_f32_e32 v40, 0xbf1b4598, v40
	v_mul_f32_e32 v40, 0x3fb8aa3b, v40
	v_exp_f32_e32 v50, v40
	v_add_f32_e32 v41, 1.0, v41
	v_rcp_f32_e32 v40, v45
	v_pk_add_f32 v[46:47], v[46:47], v[70:71]
	v_pk_add_f32 v[42:43], v[42:43], v[66:67]
	v_mul_f32_e32 v46, 0xbfb8aa3b, v46
	v_exp_f32_e32 v46, v46
	v_rcp_f32_e32 v41, v41
	v_add_f32_e32 v45, 1.0, v46
	v_mul_f32_e32 v41, 0xbf1b4598, v41
	v_mul_f32_e32 v41, 0x3fb8aa3b, v41
	v_exp_f32_e32 v49, v41
	v_mul_f32_e32 v42, 0xbfb8aa3b, v42
	v_exp_f32_e32 v42, v42
	s_nop 0
	v_add_f32_e32 v42, 1.0, v42
	v_rcp_f32_e32 v41, v45
	v_mul_f32_e32 v47, 0xbfb8aa3b, v47
	v_exp_f32_e32 v47, v47
	v_mul_f32_e32 v43, 0xbfb8aa3b, v43
	v_rcp_f32_e32 v42, v42
	v_add_f32_e32 v45, 1.0, v47
	v_mul_f32_e32 v42, 0xbf1b4598, v42
	v_mul_f32_e32 v42, 0x3fb8aa3b, v42
	v_exp_f32_e32 v48, v42
	v_exp_f32_e32 v43, v43
	s_nop 0
	v_add_f32_e32 v43, 1.0, v43
	v_rcp_f32_e32 v42, v45
	v_mul_f32_e32 v44, 0xbf1b4598, v44
	v_mul_f32_e32 v40, 0xbf1b4598, v40
	v_mul_f32_e32 v41, 0xbf1b4598, v41
	v_rcp_f32_e32 v43, v43
	v_mul_f32_e32 v42, 0xbf1b4598, v42
	v_mul_f32_e32 v43, 0xbf1b4598, v43
	v_pk_add_f32 v[36:37], v[36:37], v[68:69]
	v_mul_f32_e32 v44, 0x3fb8aa3b, v44
	v_mul_f32_e32 v40, 0x3fb8aa3b, v40
	v_mul_f32_e32 v41, 0x3fb8aa3b, v41
	v_mul_f32_e32 v42, 0x3fb8aa3b, v42
	v_mul_f32_e32 v43, 0x3fb8aa3b, v43
	v_mul_f32_e32 v36, 0xbfb8aa3b, v36
	v_exp_f32_e32 v44, v44
	v_exp_f32_e32 v40, v40
	v_exp_f32_e32 v41, v41
	v_exp_f32_e32 v42, v42
	v_exp_f32_e32 v43, v43
	v_exp_f32_e32 v36, v36
	v_cvt_pk_f16_f32 v40, v44, v40
	v_cvt_pk_f16_f32 v41, v41, v42
	v_cvt_pk_f16_f32 v42, v50, v49
	v_cvt_pk_f16_f32 v43, v48, v43
	v_add_f32_e32 v36, 1.0, v36
	global_store_dwordx4 v[104:105], v[40:43], off offset:256
	v_pk_add_f32 v[32:33], v[32:33], v[64:65]
	v_mul_f32_e32 v37, 0xbfb8aa3b, v37
	v_mul_f32_e32 v32, 0xbfb8aa3b, v32
	v_exp_f32_e32 v32, v32
	v_exp_f32_e32 v37, v37
	v_add_f32_e32 v32, 1.0, v32
	v_rcp_f32_e32 v36, v36
	v_add_f32_e32 v37, 1.0, v37
	v_mul_f32_e32 v33, 0xbfb8aa3b, v33
	v_exp_f32_e32 v33, v33
	v_rcp_f32_e32 v32, v32
	s_nop 0
	v_mul_f32_e32 v32, 0xbf1b4598, v32
	v_mul_f32_e32 v32, 0x3fb8aa3b, v32
	v_exp_f32_e32 v42, v32
	v_add_f32_e32 v33, 1.0, v33
	v_rcp_f32_e32 v32, v37
	v_pk_add_f32 v[38:39], v[38:39], v[70:71]
	v_pk_add_f32 v[34:35], v[34:35], v[66:67]
	v_mul_f32_e32 v38, 0xbfb8aa3b, v38
	v_exp_f32_e32 v38, v38
	v_rcp_f32_e32 v33, v33
	v_add_f32_e32 v37, 1.0, v38
	v_mul_f32_e32 v33, 0xbf1b4598, v33
	v_mul_f32_e32 v33, 0x3fb8aa3b, v33
	v_exp_f32_e32 v41, v33
	v_mul_f32_e32 v34, 0xbfb8aa3b, v34
	v_exp_f32_e32 v34, v34
	s_nop 0
	v_add_f32_e32 v34, 1.0, v34
	v_rcp_f32_e32 v33, v37
	v_mul_f32_e32 v39, 0xbfb8aa3b, v39
	v_exp_f32_e32 v39, v39
	v_mul_f32_e32 v35, 0xbfb8aa3b, v35
	v_rcp_f32_e32 v34, v34
	v_add_f32_e32 v37, 1.0, v39
	v_mul_f32_e32 v34, 0xbf1b4598, v34
	v_mul_f32_e32 v34, 0x3fb8aa3b, v34
	v_exp_f32_e32 v40, v34
	v_exp_f32_e32 v35, v35
	s_nop 0
	v_add_f32_e32 v35, 1.0, v35
	v_rcp_f32_e32 v34, v37
	v_mul_f32_e32 v36, 0xbf1b4598, v36
	v_mul_f32_e32 v32, 0xbf1b4598, v32
	v_mul_f32_e32 v33, 0xbf1b4598, v33
	v_rcp_f32_e32 v35, v35
	v_mul_f32_e32 v34, 0xbf1b4598, v34
	v_mul_f32_e32 v35, 0xbf1b4598, v35
	v_pk_add_f32 v[28:29], v[28:29], v[68:69]
	v_mul_f32_e32 v36, 0x3fb8aa3b, v36
	v_mul_f32_e32 v32, 0x3fb8aa3b, v32
	v_mul_f32_e32 v33, 0x3fb8aa3b, v33
	v_mul_f32_e32 v34, 0x3fb8aa3b, v34
	v_mul_f32_e32 v35, 0x3fb8aa3b, v35
	v_mul_f32_e32 v28, 0xbfb8aa3b, v28
	v_exp_f32_e32 v36, v36
	v_exp_f32_e32 v32, v32
	v_exp_f32_e32 v33, v33
	v_exp_f32_e32 v34, v34
	v_exp_f32_e32 v35, v35
	v_exp_f32_e32 v28, v28
	v_cvt_pk_f16_f32 v32, v36, v32
	v_cvt_pk_f16_f32 v33, v33, v34
	v_cvt_pk_f16_f32 v34, v42, v41
	v_cvt_pk_f16_f32 v35, v40, v35
	v_add_f32_e32 v28, 1.0, v28
	global_store_dwordx4 v[96:97], v[32:35], off offset:256
	v_pk_add_f32 v[24:25], v[24:25], v[64:65]
	v_mul_f32_e32 v29, 0xbfb8aa3b, v29
	v_mul_f32_e32 v24, 0xbfb8aa3b, v24
	v_exp_f32_e32 v24, v24
	v_exp_f32_e32 v29, v29
	v_add_f32_e32 v24, 1.0, v24
	v_rcp_f32_e32 v28, v28
	v_add_f32_e32 v29, 1.0, v29
	v_mul_f32_e32 v25, 0xbfb8aa3b, v25
	v_exp_f32_e32 v25, v25
	v_rcp_f32_e32 v24, v24
	s_nop 0
	v_mul_f32_e32 v24, 0xbf1b4598, v24
	v_mul_f32_e32 v24, 0x3fb8aa3b, v24
	v_exp_f32_e32 v34, v24
	v_add_f32_e32 v25, 1.0, v25
	v_rcp_f32_e32 v24, v29
	v_pk_add_f32 v[30:31], v[30:31], v[70:71]
	v_pk_add_f32 v[26:27], v[26:27], v[66:67]
	v_mul_f32_e32 v30, 0xbfb8aa3b, v30
	v_exp_f32_e32 v30, v30
	v_rcp_f32_e32 v25, v25
	v_add_f32_e32 v29, 1.0, v30
	v_mul_f32_e32 v25, 0xbf1b4598, v25
	v_mul_f32_e32 v25, 0x3fb8aa3b, v25
	v_exp_f32_e32 v33, v25
	v_mul_f32_e32 v26, 0xbfb8aa3b, v26
	v_exp_f32_e32 v26, v26
	s_nop 0
	v_add_f32_e32 v26, 1.0, v26
	v_rcp_f32_e32 v25, v29
	v_mul_f32_e32 v31, 0xbfb8aa3b, v31
	v_exp_f32_e32 v31, v31
	v_mul_f32_e32 v27, 0xbfb8aa3b, v27
	v_rcp_f32_e32 v26, v26
	v_add_f32_e32 v29, 1.0, v31
	v_mul_f32_e32 v26, 0xbf1b4598, v26
	v_mul_f32_e32 v26, 0x3fb8aa3b, v26
; DI float sigmoidf_(float z) { return 1.0f / (1.0f + __expf(-z)); }
;     DI void operator()(f4 (&acc)[2][2][4][2], const Unit& u, int wr, int wc, int fr, int fq) const {
;     ...
;             for (int bj = 0; bj < 2; ++bj) { const int col = col0 + bj * HALF; const f4 z0 = *(const f4*)(w0 + col), z1 = *(const f4*)(w0 + col + 4);
; #pragma unroll
;                 for (int ai = 0; ai < 2; ++ai)
; #pragma unroll
;                     for (int m = 0; m < 4; ++m) { const size_t off = (size_t)(row0 + ai * HALF + m * 16) * DB + col;
;                         f4 x0 = acc[ai][bj][m][0] + z0, x1 = acc[ai][bj][m][1] + z1;
; #pragma unroll
;                         for (int e = 0; e < 4; ++e) { x0[e] = __expf(-0.6065306597126334f * sigmoidf_(x0[e])); x1[e] = __expf(-0.6065306597126334f * sigmoidf_(x1[e])); }
;                         { typedef _Float16 h2_ __attribute__((ext_vector_type(2)));
;                           const h2_ q0 = {(_Float16)x0[0], (_Float16)x0[1]}, q1 = {(_Float16)x0[2], (_Float16)x0[3]}, q2 = {(_Float16)x1[0], (_Float16)x1[1]}, q3 = {(_Float16)x1[2], (_Float16)x1[3]};
;                           v4u w_; w_.x = __builtin_bit_cast(unsigned, q0); w_.y = __builtin_bit_cast(unsigned, q1); w_.z = __builtin_bit_cast(unsigned, q2); w_.w = __builtin_bit_cast(unsigned, q3);
;                           *(v4u*)((_Float16*)decay + off) = w_; }
;                         asm volatile("" ::: "memory"); } }
	v_exp_f32_e32 v32, v26
	v_exp_f32_e32 v27, v27
	s_nop 0
	v_add_f32_e32 v27, 1.0, v27
	v_rcp_f32_e32 v26, v29
	v_mul_f32_e32 v28, 0xbf1b4598, v28
	v_mul_f32_e32 v24, 0xbf1b4598, v24
	v_mul_f32_e32 v25, 0xbf1b4598, v25
	v_rcp_f32_e32 v27, v27
	v_mul_f32_e32 v26, 0xbf1b4598, v26
	v_mul_f32_e32 v27, 0xbf1b4598, v27
	v_pk_add_f32 v[20:21], v[20:21], v[68:69]
	v_mul_f32_e32 v28, 0x3fb8aa3b, v28
	v_mul_f32_e32 v24, 0x3fb8aa3b, v24
	v_mul_f32_e32 v25, 0x3fb8aa3b, v25
	v_mul_f32_e32 v26, 0x3fb8aa3b, v26
	v_mul_f32_e32 v27, 0x3fb8aa3b, v27
	v_mul_f32_e32 v20, 0xbfb8aa3b, v20
	v_exp_f32_e32 v28, v28
	v_exp_f32_e32 v24, v24
	v_exp_f32_e32 v25, v25
	v_exp_f32_e32 v26, v26
	v_exp_f32_e32 v27, v27
	v_exp_f32_e32 v20, v20
	v_cvt_pk_f16_f32 v24, v28, v24
	v_cvt_pk_f16_f32 v25, v25, v26
	v_cvt_pk_f16_f32 v26, v34, v33
	v_cvt_pk_f16_f32 v27, v32, v27
	v_add_f32_e32 v20, 1.0, v20
	global_store_dwordx4 v[88:89], v[24:27], off offset:256
	v_pk_add_f32 v[16:17], v[16:17], v[64:65]
	v_mul_f32_e32 v21, 0xbfb8aa3b, v21
	v_mul_f32_e32 v16, 0xbfb8aa3b, v16
	v_exp_f32_e32 v16, v16
	v_exp_f32_e32 v21, v21
	v_add_f32_e32 v16, 1.0, v16
	v_rcp_f32_e32 v20, v20
	v_add_f32_e32 v21, 1.0, v21
	v_mul_f32_e32 v17, 0xbfb8aa3b, v17
	v_exp_f32_e32 v17, v17
	v_rcp_f32_e32 v16, v16
	s_nop 0
	v_mul_f32_e32 v16, 0xbf1b4598, v16
	v_mul_f32_e32 v16, 0x3fb8aa3b, v16
	v_exp_f32_e32 v26, v16
	v_add_f32_e32 v17, 1.0, v17
	v_rcp_f32_e32 v16, v21
	v_pk_add_f32 v[22:23], v[22:23], v[70:71]
	v_pk_add_f32 v[18:19], v[18:19], v[66:67]
	v_mul_f32_e32 v22, 0xbfb8aa3b, v22
	v_exp_f32_e32 v22, v22
	v_rcp_f32_e32 v17, v17
	v_add_f32_e32 v21, 1.0, v22
	v_mul_f32_e32 v17, 0xbf1b4598, v17
	v_mul_f32_e32 v17, 0x3fb8aa3b, v17
	v_exp_f32_e32 v25, v17
	v_mul_f32_e32 v18, 0xbfb8aa3b, v18
	v_exp_f32_e32 v18, v18
	s_nop 0
	v_add_f32_e32 v18, 1.0, v18
	v_rcp_f32_e32 v17, v21
	v_mul_f32_e32 v23, 0xbfb8aa3b, v23
	v_exp_f32_e32 v23, v23
	v_mul_f32_e32 v19, 0xbfb8aa3b, v19
	v_rcp_f32_e32 v18, v18
	v_add_f32_e32 v21, 1.0, v23
	v_mul_f32_e32 v18, 0xbf1b4598, v18
	v_mul_f32_e32 v18, 0x3fb8aa3b, v18
	v_exp_f32_e32 v24, v18
	v_exp_f32_e32 v19, v19
	s_nop 0
	v_add_f32_e32 v19, 1.0, v19
	v_rcp_f32_e32 v18, v21
	v_mul_f32_e32 v20, 0xbf1b4598, v20
	v_mul_f32_e32 v16, 0xbf1b4598, v16
	v_mul_f32_e32 v17, 0xbf1b4598, v17
	v_rcp_f32_e32 v19, v19
	v_mul_f32_e32 v18, 0xbf1b4598, v18
	v_mul_f32_e32 v19, 0xbf1b4598, v19
	v_pk_add_f32 v[12:13], v[12:13], v[68:69]
	v_mul_f32_e32 v20, 0x3fb8aa3b, v20
	v_mul_f32_e32 v16, 0x3fb8aa3b, v16
	v_mul_f32_e32 v17, 0x3fb8aa3b, v17
	v_mul_f32_e32 v18, 0x3fb8aa3b, v18
	v_mul_f32_e32 v19, 0x3fb8aa3b, v19
	v_mul_f32_e32 v12, 0xbfb8aa3b, v12
	v_exp_f32_e32 v20, v20
	v_exp_f32_e32 v16, v16
	v_exp_f32_e32 v17, v17
	v_exp_f32_e32 v18, v18
	v_exp_f32_e32 v19, v19
	v_exp_f32_e32 v12, v12
	v_cvt_pk_f16_f32 v16, v20, v16
	v_cvt_pk_f16_f32 v17, v17, v18
	v_cvt_pk_f16_f32 v18, v26, v25
	v_cvt_pk_f16_f32 v19, v24, v19
	v_add_f32_e32 v12, 1.0, v12
	global_store_dwordx4 v[80:81], v[16:19], off offset:256
	v_pk_add_f32 v[8:9], v[8:9], v[64:65]
	v_mul_f32_e32 v13, 0xbfb8aa3b, v13
	v_mul_f32_e32 v8, 0xbfb8aa3b, v8
	v_exp_f32_e32 v8, v8
	v_exp_f32_e32 v13, v13
	v_add_f32_e32 v8, 1.0, v8
	v_rcp_f32_e32 v12, v12
	v_add_f32_e32 v13, 1.0, v13
	v_mul_f32_e32 v9, 0xbfb8aa3b, v9
	v_exp_f32_e32 v9, v9
	v_rcp_f32_e32 v8, v8
	s_nop 0
	v_mul_f32_e32 v8, 0xbf1b4598, v8
	v_mul_f32_e32 v8, 0x3fb8aa3b, v8
	v_exp_f32_e32 v18, v8
	v_add_f32_e32 v9, 1.0, v9
	v_rcp_f32_e32 v8, v13
	v_pk_add_f32 v[14:15], v[14:15], v[70:71]
	v_pk_add_f32 v[10:11], v[10:11], v[66:67]
	v_mul_f32_e32 v14, 0xbfb8aa3b, v14
	v_exp_f32_e32 v14, v14
	v_rcp_f32_e32 v9, v9
	v_add_f32_e32 v13, 1.0, v14
	v_mul_f32_e32 v9, 0xbf1b4598, v9
	v_mul_f32_e32 v9, 0x3fb8aa3b, v9
	v_exp_f32_e32 v17, v9
	v_mul_f32_e32 v10, 0xbfb8aa3b, v10
	v_exp_f32_e32 v10, v10
	s_nop 0
	v_add_f32_e32 v10, 1.0, v10
	v_rcp_f32_e32 v9, v13
	v_mul_f32_e32 v15, 0xbfb8aa3b, v15
	v_exp_f32_e32 v15, v15
	v_mul_f32_e32 v11, 0xbfb8aa3b, v11
	v_rcp_f32_e32 v10, v10
	v_add_f32_e32 v13, 1.0, v15
	v_mul_f32_e32 v10, 0xbf1b4598, v10
	v_mul_f32_e32 v10, 0x3fb8aa3b, v10
	v_exp_f32_e32 v16, v10
	v_exp_f32_e32 v11, v11
	s_nop 0
	v_add_f32_e32 v11, 1.0, v11
	v_rcp_f32_e32 v10, v13
	v_mul_f32_e32 v12, 0xbf1b4598, v12
	v_mul_f32_e32 v8, 0xbf1b4598, v8
	v_mul_f32_e32 v9, 0xbf1b4598, v9
	v_rcp_f32_e32 v11, v11
	v_mul_f32_e32 v10, 0xbf1b4598, v10
	v_mul_f32_e32 v11, 0xbf1b4598, v11
	v_pk_add_f32 v[4:5], v[4:5], v[68:69]
	v_mul_f32_e32 v12, 0x3fb8aa3b, v12
	v_mul_f32_e32 v8, 0x3fb8aa3b, v8
	v_mul_f32_e32 v9, 0x3fb8aa3b, v9
	v_mul_f32_e32 v10, 0x3fb8aa3b, v10
	v_mul_f32_e32 v11, 0x3fb8aa3b, v11
	v_mul_f32_e32 v4, 0xbfb8aa3b, v4
	v_exp_f32_e32 v12, v12
	v_exp_f32_e32 v8, v8
	v_exp_f32_e32 v9, v9
	v_exp_f32_e32 v10, v10
	v_exp_f32_e32 v11, v11
	v_exp_f32_e32 v4, v4
	v_cvt_pk_f16_f32 v8, v12, v8
	v_cvt_pk_f16_f32 v9, v9, v10
	v_cvt_pk_f16_f32 v10, v18, v17
	v_cvt_pk_f16_f32 v11, v16, v11
	v_add_f32_e32 v4, 1.0, v4
	global_store_dwordx4 v[72:73], v[8:11], off offset:256
	v_pk_add_f32 v[0:1], v[0:1], v[64:65]
	v_mul_f32_e32 v5, 0xbfb8aa3b, v5
	v_mul_f32_e32 v0, 0xbfb8aa3b, v0
	v_exp_f32_e32 v0, v0
	v_exp_f32_e32 v5, v5
	v_add_f32_e32 v0, 1.0, v0
	v_rcp_f32_e32 v4, v4
	v_add_f32_e32 v5, 1.0, v5
	v_mul_f32_e32 v1, 0xbfb8aa3b, v1
	v_exp_f32_e32 v1, v1
	v_rcp_f32_e32 v0, v0
	s_nop 0
	v_mul_f32_e32 v0, 0xbf1b4598, v0
	v_mul_f32_e32 v0, 0x3fb8aa3b, v0
	v_exp_f32_e32 v10, v0
	v_add_f32_e32 v1, 1.0, v1
	v_rcp_f32_e32 v0, v5
	v_pk_add_f32 v[6:7], v[6:7], v[70:71]
	v_pk_add_f32 v[2:3], v[2:3], v[66:67]
	v_mul_f32_e32 v6, 0xbfb8aa3b, v6
	v_exp_f32_e32 v6, v6
	v_rcp_f32_e32 v1, v1
	v_add_f32_e32 v5, 1.0, v6
	v_mul_f32_e32 v1, 0xbf1b4598, v1
	v_mul_f32_e32 v1, 0x3fb8aa3b, v1
	v_exp_f32_e32 v9, v1
	v_mul_f32_e32 v2, 0xbfb8aa3b, v2
	v_exp_f32_e32 v2, v2
	s_nop 0
	v_add_f32_e32 v2, 1.0, v2
	v_rcp_f32_e32 v1, v5
	v_mul_f32_e32 v7, 0xbfb8aa3b, v7
	v_exp_f32_e32 v7, v7
	v_mul_f32_e32 v3, 0xbfb8aa3b, v3
	v_rcp_f32_e32 v2, v2
	v_add_f32_e32 v5, 1.0, v7
	v_mul_f32_e32 v2, 0xbf1b4598, v2
	v_mul_f32_e32 v2, 0x3fb8aa3b, v2
	v_exp_f32_e32 v8, v2
	v_exp_f32_e32 v3, v3
	s_nop 0
	v_add_f32_e32 v3, 1.0, v3
	v_rcp_f32_e32 v2, v5
	v_mul_f32_e32 v4, 0xbf1b4598, v4
	v_mul_f32_e32 v0, 0xbf1b4598, v0
	v_mul_f32_e32 v1, 0xbf1b4598, v1
	v_rcp_f32_e32 v3, v3
	v_mul_f32_e32 v2, 0xbf1b4598, v2
	v_mul_f32_e32 v3, 0xbf1b4598, v3
	v_mul_f32_e32 v4, 0x3fb8aa3b, v4
	v_mul_f32_e32 v0, 0x3fb8aa3b, v0
	v_mul_f32_e32 v1, 0x3fb8aa3b, v1
	v_mul_f32_e32 v2, 0x3fb8aa3b, v2
	v_mul_f32_e32 v3, 0x3fb8aa3b, v3
	v_exp_f32_e32 v4, v4
	v_exp_f32_e32 v0, v0
	v_exp_f32_e32 v1, v1
	v_exp_f32_e32 v2, v2
	v_exp_f32_e32 v3, v3
	v_cvt_pk_f16_f32 v0, v4, v0
	v_cvt_pk_f16_f32 v1, v1, v2
	v_cvt_pk_f16_f32 v2, v10, v9
	v_cvt_pk_f16_f32 v3, v8, v3
	global_store_dwordx4 v[74:75], v[0:3], off offset:256
	s_and_b64 vcc, exec, s[6:7]
	s_mov_b64 s[0:1], -1
	s_cbranch_vccnz .LBB0_2052

.LBB0_2155:
	s_or_b64 exec, exec, s[0:1]
	s_waitcnt lgkmcnt(1)
	v_mov_b32_e32 v126, v108
	v_mov_b32_e32 v127, v100
	v_mov_b32_e32 v128, v109
	v_mov_b32_e32 v129, v101
	v_pk_add_f32 v[126:127], v[126:127], v[128:129]
	v_mov_b32_e32 v128, v110
	v_mov_b32_e32 v129, v102
	v_mov_b32_e32 v130, v111
	v_mov_b32_e32 v131, v103
	v_pk_add_f32 v[128:129], v[128:129], v[130:131]
	v_mov_b32_e32 v130, v105
	v_pk_add_f32 v[126:127], v[126:127], v[128:129]
	v_mov_b32_e32 v128, v104
	v_mov_b32_e32 v129, v96
	v_mov_b32_e32 v131, v97
	v_pk_add_f32 v[128:129], v[128:129], v[130:131]
	v_mov_b32_e32 v130, v106
	v_mov_b32_e32 v131, v98
	v_mov_b32_e32 v134, v107
	v_mov_b32_e32 v135, v99
	v_pk_add_f32 v[130:131], v[130:131], v[134:135]
	s_lshl_b32 s31, s29, 4
	v_pk_add_f32 v[128:129], v[128:129], v[130:131]
	s_add_i32 s30, s29, 2
	v_pk_add_f32 v[126:127], v[126:127], v[128:129]
	s_cmpk_gt_u32 s29, 0x1fd
	v_add_f32_e32 v126, v126, v127
	s_cselect_b64 s[14:15], -1, 0
	s_nop 0
	v_add_f32_dpp v126, v126, v126 quad_perm:[1,0,3,2] row_mask:0xf bank_mask:0xf bound_ctrl:1
	s_nop 1
	v_add_f32_dpp v133, v126, v126 quad_perm:[2,3,0,1] row_mask:0xf bank_mask:0xf bound_ctrl:1
	v_fmamk_f32 v109, v133, 0xbc800000, v109
	v_fmamk_f32 v108, v133, 0xbc800000, v108
	v_fmamk_f32 v111, v133, 0xbc800000, v111
	v_fmac_f32_e32 v110, 0xbc800000, v133
	v_pk_mul_f32 v[126:127], v[110:111], v[110:111]
	v_pk_mul_f32 v[128:129], v[108:109], v[108:109]
	v_fmamk_f32 v107, v133, 0xbc800000, v107
	v_pk_mov_b32 v[130:131], v[128:129], v[126:127] op_sel:[1,0]
	v_mov_b32_e32 v129, v127
	v_pk_add_f32 v[126:127], v[130:131], v[128:129]
	v_fmamk_f32 v129, v133, 0xbc800000, v105
	v_fmamk_f32 v128, v133, 0xbc800000, v104
	v_fmac_f32_e32 v106, 0xbc800000, v133
	v_pk_mul_f32 v[104:105], v[106:107], v[106:107]
	v_pk_mul_f32 v[130:131], v[128:129], v[128:129]
	v_fmamk_f32 v101, v133, 0xbc800000, v101
	v_pk_mov_b32 v[134:135], v[130:131], v[104:105] op_sel:[1,0]
	v_mov_b32_e32 v131, v105
	v_pk_add_f32 v[104:105], v[134:135], v[130:131]
	v_fmamk_f32 v100, v133, 0xbc800000, v100
	v_fmamk_f32 v103, v133, 0xbc800000, v103
	v_fmac_f32_e32 v102, 0xbc800000, v133
	v_fmamk_f32 v137, v133, 0xbc800000, v97
	v_fmamk_f32 v136, v133, 0xbc800000, v96
	v_fmamk_f32 v99, v133, 0xbc800000, v99
	v_fmac_f32_e32 v98, 0xbc800000, v133
	v_pk_add_f32 v[126:127], v[126:127], v[126:127] op_sel_hi:[0,1]
	v_pk_add_f32 v[104:105], v[104:105], v[104:105] op_sel_hi:[0,1]
	v_pk_mul_f32 v[130:131], v[102:103], v[102:103]
	v_pk_mul_f32 v[134:135], v[100:101], v[100:101]
	v_pk_mul_f32 v[96:97], v[98:99], v[98:99]
	v_pk_mul_f32 v[138:139], v[136:137], v[136:137]
	v_add_f32_e32 v135, v134, v135
	v_add_f32_e32 v131, v130, v131
	v_mov_b32_e32 v134, v138
	v_mov_b32_e32 v130, v139
	v_mov_b32_e32 v126, v96
	v_mov_b32_e32 v104, v97
	v_pk_add_f32 v[130:131], v[134:135], v[130:131]
	v_pk_add_f32 v[96:97], v[126:127], v[104:105]
	s_waitcnt vmcnt(2)
	v_and_b32_e32 v133, 0xffff0000, v72
	v_pk_add_f32 v[96:97], v[130:131], v[96:97]
	v_lshlrev_b32_e32 v130, 16, v73
	v_add_f32_e32 v96, v96, v97
	v_and_b32_e32 v131, 0xffff0000, v73
	s_nop 0
	v_add_f32_dpp v96, v96, v96 quad_perm:[1,0,3,2] row_mask:0xf bank_mask:0xf bound_ctrl:1
	s_nop 1
	v_add_f32_dpp v96, v96, v96 quad_perm:[2,3,0,1] row_mask:0xf bank_mask:0xf bound_ctrl:1
	v_fmamk_f32 v96, v96, 0x3c800000, v123
	v_mul_f32_e32 v97, 0x4f800000, v96
	v_cmp_gt_f32_e32 vcc, s26, v96
	s_nop 1
	v_cndmask_b32_e32 v96, v96, v97, vcc
	v_sqrt_f32_e32 v97, v96
	s_nop 0
	v_add_u32_e32 v104, -1, v97
	v_fma_f32 v105, -v104, v97, v96
	v_cmp_ge_f32_e64 s[0:1], 0, v105
	v_add_u32_e32 v105, 1, v97
	s_nop 0
	v_cndmask_b32_e64 v104, v97, v104, s[0:1]
	v_fma_f32 v97, -v105, v97, v96
	v_cmp_lt_f32_e64 s[0:1], 0, v97
	s_nop 1
	v_cndmask_b32_e64 v97, v104, v105, s[0:1]
	v_mul_f32_e32 v104, 0x37800000, v97
	v_cndmask_b32_e32 v97, v97, v104, vcc
	v_cmp_class_f32_e32 vcc, v96, v124
	s_nop 1
	v_cndmask_b32_e32 v96, v97, v96, vcc
	s_nop 0
	v_rcp_f32_e32 v126, v96
	s_nop 0
	v_pk_mul_f32 v[96:97], v[110:111], v[126:127] op_sel_hi:[1,0]
	v_lshlrev_b32_e32 v110, 16, v53
	v_and_b32_e32 v111, 0xffff0000, v53
	v_pk_mul_f32 v[104:105], v[108:109], v[126:127] op_sel_hi:[1,0]
	v_lshlrev_b32_e32 v127, 16, v72
	v_lshlrev_b32_e32 v108, 16, v52
	v_and_b32_e32 v109, 0xffff0000, v52
	v_sub_f32_e32 v131, v131, v111
	v_sub_f32_e32 v130, v130, v110
	v_pk_fma_f32 v[96:97], v[14:15], v[96:97], v[30:31]
	v_sub_f32_e32 v135, v133, v109
	v_sub_f32_e32 v134, v127, v108
	v_pk_fma_f32 v[110:111], v[46:47], v[130:131], v[110:111]
	v_pk_fma_f32 v[104:105], v[12:13], v[104:105], v[28:29]
	v_pk_fma_f32 v[108:109], v[44:45], v[134:135], v[108:109]
	s_waitcnt lgkmcnt(0)
	v_pk_fma_f32 v[96:97], v[110:111], v[118:119], v[96:97] op_sel_hi:[1,0,1]
	v_lshlrev_b32_e32 v110, 16, v61
	v_and_b32_e32 v111, 0xffff0000, v61
	v_pk_fma_f32 v[104:105], v[108:109], v[118:119], v[104:105] op_sel_hi:[1,0,1]
	v_lshlrev_b32_e32 v108, 16, v60
	v_and_b32_e32 v109, 0xffff0000, v60
	v_pk_mul_f32 v[96:97], v[96:97], v[110:111]
	v_pk_mul_f32 v[108:109], v[104:105], v[108:109]
	v_bfe_u32 v104, v97, 16, 1
	v_add3_u32 v97, v97, v104, s28
	v_bfe_u32 v104, v96, 16, 1
	v_add3_u32 v96, v96, v104, s28
	v_lshrrev_b32_e32 v96, 16, v96
	v_and_or_b32 v105, v97, s27, v96
	v_bfe_u32 v97, v108, 16, 1
	v_bfe_u32 v96, v109, 16, 1
	v_add3_u32 v97, v108, v97, s28
	v_add3_u32 v96, v109, v96, s28
	v_lshrrev_b32_e32 v97, 16, v97
	v_and_or_b32 v104, v96, s27, v97
	v_pk_mul_f32 v[96:97], v[106:107], v[126:127] op_sel_hi:[1,0]
	v_pk_mul_f32 v[106:107], v[128:129], v[126:127] op_sel_hi:[1,0]
	v_lshlrev_b32_e32 v128, 16, v75
	v_and_b32_e32 v129, 0xffff0000, v75
	v_lshlrev_b32_e32 v110, 16, v55
	v_and_b32_e32 v111, 0xffff0000, v55
	v_lshlrev_b32_e32 v127, 16, v74
	v_and_b32_e32 v130, 0xffff0000, v74
	v_lshlrev_b32_e32 v108, 16, v54
	v_and_b32_e32 v109, 0xffff0000, v54
	v_sub_f32_e32 v129, v129, v111
	v_sub_f32_e32 v128, v128, v110
	v_pk_fma_f32 v[96:97], v[10:11], v[96:97], v[26:27]
	v_sub_f32_e32 v131, v130, v109
	v_sub_f32_e32 v130, v127, v108
	v_pk_fma_f32 v[110:111], v[42:43], v[128:129], v[110:111]
	v_pk_fma_f32 v[106:107], v[8:9], v[106:107], v[24:25]
	v_pk_fma_f32 v[108:109], v[40:41], v[130:131], v[108:109]
	v_pk_fma_f32 v[96:97], v[110:111], v[118:119], v[96:97] op_sel_hi:[1,0,1]
	v_lshlrev_b32_e32 v110, 16, v63
	v_and_b32_e32 v111, 0xffff0000, v63
	v_pk_fma_f32 v[106:107], v[108:109], v[118:119], v[106:107] op_sel_hi:[1,0,1]
	v_lshlrev_b32_e32 v108, 16, v62
	v_and_b32_e32 v109, 0xffff0000, v62
	v_pk_mul_f32 v[96:97], v[96:97], v[110:111]
	v_pk_mul_f32 v[108:109], v[106:107], v[108:109]
	v_bfe_u32 v106, v97, 16, 1
	v_add3_u32 v97, v97, v106, s28
	v_bfe_u32 v106, v96, 16, 1
	v_add3_u32 v96, v96, v106, s28
	v_lshrrev_b32_e32 v96, 16, v96
	v_and_or_b32 v107, v97, s27, v96
	v_bfe_u32 v97, v108, 16, 1
	v_bfe_u32 v96, v109, 16, 1
	v_add3_u32 v97, v108, v97, s28
	v_add3_u32 v96, v109, v96, s28
	v_lshrrev_b32_e32 v97, 16, v97
	v_lshlrev_b32_e32 v110, 16, v69
	v_and_b32_e32 v111, 0xffff0000, v69
	v_lshlrev_b32_e32 v108, 16, v49
	v_and_b32_e32 v109, 0xffff0000, v49
	v_and_or_b32 v106, v96, s27, v97
	v_pk_mul_f32 v[96:97], v[102:103], v[126:127] op_sel_hi:[1,0]
	v_pk_mul_f32 v[100:101], v[100:101], v[126:127] op_sel_hi:[1,0]
	v_lshlrev_b32_e32 v127, 16, v68
	v_and_b32_e32 v128, 0xffff0000, v68
	v_lshlrev_b32_e32 v102, 16, v48
	v_and_b32_e32 v103, 0xffff0000, v48
	v_sub_f32_e32 v111, v111, v109
	v_sub_f32_e32 v110, v110, v108
	v_pk_fma_f32 v[96:97], v[6:7], v[96:97], v[22:23]
	v_sub_f32_e32 v129, v128, v103
	v_sub_f32_e32 v128, v127, v102
	v_pk_fma_f32 v[108:109], v[38:39], v[110:111], v[108:109]
	v_pk_fma_f32 v[100:101], v[4:5], v[100:101], v[20:21]
	v_pk_fma_f32 v[102:103], v[36:37], v[128:129], v[102:103]
	v_pk_fma_f32 v[96:97], v[108:109], v[118:119], v[96:97] op_sel_hi:[1,0,1]
	v_lshlrev_b32_e32 v108, 16, v57
	v_and_b32_e32 v109, 0xffff0000, v57
	v_pk_fma_f32 v[100:101], v[102:103], v[118:119], v[100:101] op_sel_hi:[1,0,1]
	v_lshlrev_b32_e32 v102, 16, v56
	v_and_b32_e32 v103, 0xffff0000, v56
	v_pk_mul_f32 v[96:97], v[96:97], v[108:109]
	v_pk_mul_f32 v[100:101], v[100:101], v[102:103]
	v_bfe_u32 v102, v97, 16, 1
	v_add3_u32 v97, v97, v102, s28
	v_bfe_u32 v102, v96, 16, 1
	v_add3_u32 v96, v96, v102, s28
	v_lshrrev_b32_e32 v96, 16, v96
	v_and_or_b32 v97, v97, s27, v96
	v_bfe_u32 v96, v101, 16, 1
	v_add3_u32 v96, v101, v96, s28
	v_bfe_u32 v101, v100, 16, 1
	v_add3_u32 v100, v100, v101, s28
	v_lshrrev_b32_e32 v100, 16, v100
	v_and_or_b32 v96, v96, s27, v100
	v_pk_mul_f32 v[100:101], v[136:137], v[126:127] op_sel_hi:[1,0]
	v_pk_mul_f32 v[98:99], v[98:99], v[126:127] op_sel_hi:[1,0]
	v_lshlrev_b32_e32 v110, 16, v70
	v_and_b32_e32 v111, 0xffff0000, v70
	v_lshlrev_b32_e32 v126, 16, v71
	v_and_b32_e32 v127, 0xffff0000, v71
	v_lshlrev_b32_e32 v102, 16, v50
	v_and_b32_e32 v103, 0xffff0000, v50
	v_lshlrev_b32_e32 v108, 16, v51
	v_and_b32_e32 v109, 0xffff0000, v51
	v_sub_f32_e32 v111, v111, v103
	v_sub_f32_e32 v110, v110, v102
	v_sub_f32_e32 v127, v127, v109
	v_sub_f32_e32 v126, v126, v108
	v_pk_fma_f32 v[98:99], v[2:3], v[98:99], v[18:19]
	v_pk_fma_f32 v[100:101], v[0:1], v[100:101], v[16:17]
	v_pk_fma_f32 v[108:109], v[34:35], v[126:127], v[108:109]
	v_pk_fma_f32 v[102:103], v[32:33], v[110:111], v[102:103]
	v_pk_fma_f32 v[98:99], v[108:109], v[118:119], v[98:99] op_sel_hi:[1,0,1]
	v_pk_fma_f32 v[100:101], v[102:103], v[118:119], v[100:101] op_sel_hi:[1,0,1]
	v_lshlrev_b32_e32 v102, 16, v58
	v_and_b32_e32 v103, 0xffff0000, v58
	v_lshlrev_b32_e32 v108, 16, v59
	v_and_b32_e32 v109, 0xffff0000, v59
	v_pk_mul_f32 v[108:109], v[98:99], v[108:109]
	v_pk_mul_f32 v[98:99], v[100:101], v[102:103]
	s_and_b64 vcc, exec, s[14:15]
	v_bfe_u32 v100, v99, 16, 1
	v_add3_u32 v99, v99, v100, s28
	v_bfe_u32 v100, v98, 16, 1
	v_add3_u32 v98, v98, v100, s28
	v_lshrrev_b32_e32 v98, 16, v98
	v_bfe_u32 v100, v108, 16, 1
	v_and_or_b32 v98, v99, s27, v98
	v_bfe_u32 v99, v109, 16, 1
	v_add3_u32 v100, v108, v100, s28
	v_add3_u32 v99, v109, v99, s28
	v_lshrrev_b32_e32 v100, 16, v100
	v_and_or_b32 v99, v99, s27, v100
	v_add_u32_e32 v100, s31, v112
	v_ashrrev_i32_e32 v101, 31, v100
	v_lshlrev_b64 v[100:101], 12, v[100:101]
	v_lshl_add_u64 v[100:101], v[116:117], 0, v[100:101]
	global_store_dwordx4 v[100:101], v[104:107], off
	global_store_dwordx4 v[100:101], v[96:99], off offset:16
	s_cbranch_vccnz .LBB0_2159
	v_lshl_add_u32 v68, s30, 4, v120
	v_add_u32_e32 v48, s74, v68
	v_ashrrev_i32_e32 v49, 31, v48
	v_lshlrev_b64 v[56:57], 12, v[48:49]
	v_lshl_or_b32 v56, v119, 1, v56
	v_lshl_add_u64 v[96:97], s[2:3], 0, v[56:57]
	v_lshl_add_u64 v[60:61], s[18:19], 0, v[56:57]
	global_load_dwordx4 v[48:51], v[96:97], off offset:16
	global_load_dwordx4 v[52:55], v[96:97], off
	global_load_dwordx4 v[56:59], v[60:61], off offset:16
	s_nop 0
	global_load_dwordx4 v[60:63], v[60:61], off
	v_mov_b32_e32 v75, 0
	v_cmp_lt_i32_e32 vcc, 0, v68
	v_mov_b32_e32 v74, 0
	v_mov_b32_e32 v73, 0
	v_mov_b32_e32 v72, 0
	v_mov_b32_e32 v71, 0
	v_mov_b32_e32 v70, 0
	v_mov_b32_e32 v69, 0
	v_mov_b32_e32 v68, 0
	s_and_saveexec_b64 s[0:1], vcc
	s_cbranch_execz .LBB0_2158
	global_load_dwordx4 v[68:71], v[96:97], off offset:-4080
	global_load_dwordx4 v[72:75], v[96:97], off offset:-4096

; DI float sigmoidf_(float z) { return 1.0f / (1.0f + __expf(-z)); }
; DI v4u pack8(const f4& a, const f4& b) { v4u w; w.x = cvt_pk_bf16(a[0], a[1]); w.y = cvt_pk_bf16(a[2], a[3]); w.z = cvt_pk_bf16(b[0], b[1]); w.w = cvt_pk_bf16(b[2], b[3]); return w; }
;     DI void operator()(f4 (&acc)[2][2][4][2], const Unit& u, int wr, int wc, int fr, int fq) const {
;     ...
;             for (int m = 0; m < 4; ++m) rr[ai][m] = ss[row0 + ai * HALF + m * 16];
; #pragma unroll
;         for (int ai = 0; ai < 2; ++ai)
; #pragma unroll
;             for (int m = 0; m < 4; ++m) { const int row = row0 + ai * HALF + m * 16; const float r = __builtin_amdgcn_rsqf(rr[ai][m] * (1.0f / D) + RMS_EPS);
;                 f4 o0, o1;
; #pragma unroll
;                 for (int e = 0; e < 4; ++e) { const float a0 = acc[ai][0][m][0][e] * r, a1 = acc[ai][0][m][1][e] * r;
;                     o0[e] = a0 * sigmoidf_(a0) * (acc[ai][1][m][0][e] * r); o1[e] = a1 * sigmoidf_(a1) * (acc[ai][1][m][1][e] * r); }
;                 *(v4u*)(uout + (size_t)row * DFF + col0) = pack8(o0, o1); }
.LBB0_2813:
	s_lshl_b32 s0, s0, 8
	s_add_i32 s0, s0, s36
	v_mbcnt_lo_u32_b32 v144, -1, 0
	v_mbcnt_hi_u32_b32 v144, -1, v144
	v_mov_b32_e32 v164, v112
	v_and_or_b32 v148, v144, 15, s0
	v_ashrrev_i32_e32 v149, 31, v148
	v_lshl_add_u64 v[160:161], v[148:149], 2, s[10:11]
	global_load_dword v170, v[160:161], off
	v_ashrrev_i32_e32 v112, 1, v144
	v_or_b32_e32 v146, 16, v148
	v_or_b32_e32 v144, 32, v148
	v_mov_b32_e32 v162, v120
	v_or_b32_e32 v120, 48, v148
	v_ashrrev_i32_e32 v147, 31, v146
	v_ashrrev_i32_e32 v145, 31, v144
	v_mov_b32_e32 v163, v124
	v_mov_b32_e32 v165, v116
	v_mov_b32_e32 v124, v121
	v_mov_b32_e32 v116, v113
	v_and_b32_e32 v171, -8, v112
	v_ashrrev_i32_e32 v121, 31, v120
	v_lshl_add_u64 v[112:113], v[146:147], 2, s[10:11]
	v_lshl_add_u64 v[166:167], v[144:145], 2, s[10:11]
	v_lshl_add_u64 v[168:169], v[120:121], 2, s[10:11]
	global_load_dword v158, v[160:161], off offset:512
	global_load_dword v157, v[160:161], off offset:576
	global_load_dword v147, v[160:161], off offset:640
	global_load_dword v172, v[112:113], off
	s_nop 0
	global_load_dword v166, v[166:167], off
	s_nop 0
	global_load_dword v159, v[168:169], off
	global_load_dword v145, v[160:161], off offset:704
	s_lshl_b32 s0, s1, 7
	s_or_b32 s0, s0, s37
	v_add_u32_e32 v160, s0, v171
	v_ashrrev_i32_e32 v161, 31, v160
	v_add_u32_e32 v156, 0x80, v148
	v_add_u32_e32 v155, 0x90, v148
	v_add_u32_e32 v149, 0xa0, v148
	v_add_u32_e32 v121, 0xb0, v148
	s_waitcnt vmcnt(0)
	v_fmamk_f32 v112, v170, 0x39800000, v154
	v_rsq_f32_e32 v112, v112
	s_nop 0
	v_pk_mul_f32 v[162:163], v[162:163], v[112:113] op_sel_hi:[1,0]
	v_pk_mul_f32 v[164:165], v[164:165], v[112:113] op_sel_hi:[1,0]
	v_pk_mul_f32 v[124:125], v[124:125], v[112:113] op_sel_hi:[1,0]
	v_pk_mul_f32 v[116:117], v[116:117], v[112:113] op_sel_hi:[1,0]
	v_mul_f32_e32 v113, 0xbfb8aa3b, v163
	v_mul_f32_e32 v167, 0xbfb8aa3b, v165
	v_exp_f32_e32 v113, v113
	v_mul_f32_e32 v168, 0xbfb8aa3b, v125
	v_exp_f32_e32 v167, v167
	v_exp_f32_e32 v168, v168
	v_add_f32_e32 v113, 1.0, v113
	v_add_f32_e32 v167, 1.0, v167
	v_add_f32_e32 v168, 1.0, v168
	v_mul_f32_e32 v169, 0xbfb8aa3b, v117
	v_exp_f32_e32 v169, v169
	v_rcp_f32_e32 v113, v113
	s_nop 0
	v_mul_f32_e32 v113, v163, v113
	v_rcp_f32_e32 v163, v167
	v_add_f32_e32 v169, 1.0, v169
	v_mul_f32_e32 v162, v162, v113
	v_mul_f32_e32 v113, v165, v163
	v_rcp_f32_e32 v163, v168
	v_mul_f32_e32 v164, v164, v113
	v_mul_f32_e32 v113, v125, v163
	v_mul_f32_e32 v163, v124, v113
	v_mov_b32_e32 v124, v122
	v_mov_b32_e32 v125, v126
	v_pk_mul_f32 v[124:125], v[124:125], v[112:113] op_sel_hi:[1,0]
	v_mul_f32_e32 v113, 0xbfb8aa3b, v125
	v_exp_f32_e32 v113, v113
	s_nop 0
	v_add_f32_e32 v113, 1.0, v113
	v_rcp_f32_e32 v122, v169
	s_nop 0
	v_mul_f32_e32 v117, v117, v122
	v_mul_f32_e32 v167, v116, v117
	v_mov_b32_e32 v116, v114
	v_mov_b32_e32 v117, v118
	v_pk_mul_f32 v[116:117], v[116:117], v[112:113] op_sel_hi:[1,0]
	v_mul_f32_e32 v114, 0xbfb8aa3b, v117
	v_exp_f32_e32 v114, v114
	v_rcp_f32_e32 v113, v113
	s_nop 0
	v_mul_f32_e32 v113, v125, v113
	v_add_f32_e32 v114, 1.0, v114
	v_mul_f32_e32 v124, v124, v113
	v_mov_b32_e32 v126, v123
	v_pk_mul_f32 v[122:123], v[126:127], v[112:113] op_sel_hi:[1,0]
	v_mul_f32_e32 v125, 0xbfb8aa3b, v123
	v_exp_f32_e32 v125, v125
	v_rcp_f32_e32 v113, v114
	s_nop 0
	v_mul_f32_e32 v113, v117, v113
	v_add_f32_e32 v125, 1.0, v125
	v_mul_f32_e32 v114, v116, v113
	v_mov_b32_e32 v118, v115
	v_pk_mul_f32 v[112:113], v[118:119], v[112:113] op_sel_hi:[1,0]
	v_mul_f32_e32 v115, 0xbfb8aa3b, v113
	v_exp_f32_e32 v115, v115
	v_rcp_f32_e32 v116, v125
	s_nop 0
	v_mul_f32_e32 v116, v123, v116
	v_add_f32_e32 v115, 1.0, v115
	v_mul_f32_e32 v119, v122, v116
	v_rcp_f32_e32 v115, v115
	s_nop 0
	v_mul_f32_e32 v113, v113, v115
	v_mul_f32_e32 v112, v112, v113
	v_fmamk_f32 v113, v172, 0x39800000, v154
	v_rsq_f32_e32 v122, v113
	v_cvt_pk_bf16_f32 v116, v162, v163
	v_cvt_pk_bf16_f32 v117, v124, v119
	v_cvt_pk_bf16_f32 v118, v164, v167
	v_cvt_pk_bf16_f32 v119, v114, v112
	v_mov_b32_e32 v112, v104
	v_mov_b32_e32 v113, v108
	v_pk_mul_f32 v[124:125], v[112:113], v[122:123] op_sel_hi:[1,0]
	v_mov_b64_e32 v[112:113], s[14:15]
	v_mul_f32_e32 v104, 0xbfb8aa3b, v125
	v_exp_f32_e32 v104, v104
	v_mad_i64_i32 v[126:127], s[0:1], v148, s52, v[112:113]
	v_lshlrev_b64 v[114:115], 1, v[160:161]
	v_add_f32_e32 v104, 1.0, v104
	v_lshl_add_u64 v[126:127], v[126:127], 0, v[114:115]
	global_store_dwordx4 v[126:127], v[116:119], off
	s_nop 1
	v_mov_b32_e32 v116, v96
	v_mov_b32_e32 v117, v100
	v_pk_mul_f32 v[116:117], v[116:117], v[122:123] op_sel_hi:[1,0]
	v_mul_f32_e32 v96, 0xbfb8aa3b, v117
	v_exp_f32_e32 v96, v96
	v_rcp_f32_e32 v100, v104
	s_nop 0
	v_mul_f32_e32 v100, v125, v100
	v_add_f32_e32 v96, 1.0, v96
	v_mul_f32_e32 v123, v124, v100
	v_mov_b32_e32 v108, v105
	v_pk_mul_f32 v[104:105], v[108:109], v[122:123] op_sel_hi:[1,0]
	v_mul_f32_e32 v108, 0xbfb8aa3b, v105
	v_exp_f32_e32 v108, v108
	v_rcp_f32_e32 v96, v96
	s_nop 0
	v_mul_f32_e32 v96, v117, v96
	v_add_f32_e32 v108, 1.0, v108
	v_mul_f32_e32 v116, v116, v96
	v_mov_b32_e32 v100, v97
	v_pk_mul_f32 v[96:97], v[100:101], v[122:123] op_sel_hi:[1,0]
	v_mul_f32_e32 v100, 0xbfb8aa3b, v97
	v_exp_f32_e32 v100, v100
	s_nop 0
	v_add_f32_e32 v109, 1.0, v100
	v_rcp_f32_e32 v100, v108
	s_nop 0
	v_mul_f32_e32 v100, v105, v100
	v_mul_f32_e32 v104, v104, v100
	v_mov_b32_e32 v100, v106
	v_mov_b32_e32 v101, v110
	v_pk_mul_f32 v[100:101], v[100:101], v[122:123] op_sel_hi:[1,0]
	v_mul_f32_e32 v106, 0xbfb8aa3b, v101
	v_exp_f32_e32 v106, v106
	v_rcp_f32_e32 v105, v109
	s_nop 0
	v_mul_f32_e32 v97, v97, v105
	v_add_f32_e32 v106, 1.0, v106
	v_mul_f32_e32 v105, v96, v97
	v_mov_b32_e32 v96, v98
	v_mov_b32_e32 v97, v102
; DI float sigmoidf_(float z) { return 1.0f / (1.0f + __expf(-z)); }
; DI v4u pack8(const f4& a, const f4& b) { v4u w; w.x = cvt_pk_bf16(a[0], a[1]); w.y = cvt_pk_bf16(a[2], a[3]); w.z = cvt_pk_bf16(b[0], b[1]); w.w = cvt_pk_bf16(b[2], b[3]); return w; }
;     DI void operator()(f4 (&acc)[2][2][4][2], const Unit& u, int wr, int wc, int fr, int fq) const {
;     ...
;             for (int m = 0; m < 4; ++m) rr[ai][m] = ss[row0 + ai * HALF + m * 16];
; #pragma unroll
;         for (int ai = 0; ai < 2; ++ai)
; #pragma unroll
;             for (int m = 0; m < 4; ++m) { const int row = row0 + ai * HALF + m * 16; const float r = __builtin_amdgcn_rsqf(rr[ai][m] * (1.0f / D) + RMS_EPS);
;                 f4 o0, o1;
; #pragma unroll
;                 for (int e = 0; e < 4; ++e) { const float a0 = acc[ai][0][m][0][e] * r, a1 = acc[ai][0][m][1][e] * r;
;                     o0[e] = a0 * sigmoidf_(a0) * (acc[ai][1][m][0][e] * r); o1[e] = a1 * sigmoidf_(a1) * (acc[ai][1][m][1][e] * r); }
;                 *(v4u*)(uout + (size_t)row * DFF + col0) = pack8(o0, o1); }
	v_pk_mul_f32 v[96:97], v[96:97], v[122:123] op_sel_hi:[1,0]
	v_mul_f32_e32 v98, 0xbfb8aa3b, v97
	v_exp_f32_e32 v98, v98
	v_rcp_f32_e32 v102, v106
	s_nop 0
	v_mul_f32_e32 v101, v101, v102
	v_add_f32_e32 v98, 1.0, v98
	v_mul_f32_e32 v106, v100, v101
	v_mov_b32_e32 v110, v107
	v_pk_mul_f32 v[100:101], v[110:111], v[122:123] op_sel_hi:[1,0]
	v_mul_f32_e32 v107, 0xbfb8aa3b, v101
	v_exp_f32_e32 v107, v107
	v_rcp_f32_e32 v98, v98
	s_nop 0
	v_mul_f32_e32 v97, v97, v98
	v_add_f32_e32 v107, 1.0, v107
	v_mul_f32_e32 v110, v96, v97
	v_mov_b32_e32 v102, v99
	v_pk_mul_f32 v[96:97], v[102:103], v[122:123] op_sel_hi:[1,0]
	v_mul_f32_e32 v99, 0xbfb8aa3b, v97
	v_exp_f32_e32 v99, v99
	v_rcp_f32_e32 v98, v107
	s_nop 0
	v_mul_f32_e32 v98, v101, v98
	v_add_f32_e32 v99, 1.0, v99
	v_mul_f32_e32 v101, v100, v98
	v_rcp_f32_e32 v98, v99
	s_nop 0
	v_mul_f32_e32 v97, v97, v98
	v_mul_f32_e32 v107, v96, v97
	v_fmamk_f32 v96, v166, 0x39800000, v154
	v_rsq_f32_e32 v100, v96
	v_mov_b32_e32 v98, v88
	v_mov_b32_e32 v99, v92
	v_cvt_pk_bf16_f32 v96, v123, v104
	v_pk_mul_f32 v[102:103], v[98:99], v[100:101] op_sel_hi:[1,0]
	v_cvt_pk_bf16_f32 v97, v106, v101
	v_cvt_pk_bf16_f32 v98, v116, v105
	v_mad_i64_i32 v[104:105], s[0:1], v146, s52, v[112:113]
	v_mul_f32_e32 v88, 0xbfb8aa3b, v103
	v_exp_f32_e32 v88, v88
	v_lshl_add_u64 v[104:105], v[104:105], 0, v[114:115]
	v_cvt_pk_bf16_f32 v99, v110, v107
	global_store_dwordx4 v[104:105], v[96:99], off
	v_add_f32_e32 v88, 1.0, v88
	s_nop 0
	v_mov_b32_e32 v97, v84
	v_mov_b32_e32 v96, v80
	v_pk_mul_f32 v[96:97], v[96:97], v[100:101] op_sel_hi:[1,0]
	v_mul_f32_e32 v80, 0xbfb8aa3b, v97
	v_exp_f32_e32 v80, v80
	v_rcp_f32_e32 v84, v88
	s_nop 0
	v_mul_f32_e32 v84, v103, v84
	v_add_f32_e32 v80, 1.0, v80
	v_mul_f32_e32 v101, v102, v84
	v_mov_b32_e32 v92, v89
	v_pk_mul_f32 v[88:89], v[92:93], v[100:101] op_sel_hi:[1,0]
	v_mul_f32_e32 v92, 0xbfb8aa3b, v89
	v_exp_f32_e32 v92, v92
	v_rcp_f32_e32 v80, v80
	s_nop 0
	v_mul_f32_e32 v80, v97, v80
	v_add_f32_e32 v92, 1.0, v92
	v_mul_f32_e32 v96, v96, v80
	v_mov_b32_e32 v84, v81
	v_pk_mul_f32 v[80:81], v[84:85], v[100:101] op_sel_hi:[1,0]
	v_mul_f32_e32 v84, 0xbfb8aa3b, v81
	v_exp_f32_e32 v84, v84
	s_nop 0
	v_add_f32_e32 v93, 1.0, v84
	v_rcp_f32_e32 v84, v92
	s_nop 0
	v_mul_f32_e32 v84, v89, v84
	v_mul_f32_e32 v88, v88, v84
	v_mov_b32_e32 v84, v90
	v_mov_b32_e32 v85, v94
	v_pk_mul_f32 v[84:85], v[84:85], v[100:101] op_sel_hi:[1,0]
	v_mul_f32_e32 v90, 0xbfb8aa3b, v85
	v_exp_f32_e32 v90, v90
	v_rcp_f32_e32 v89, v93
	s_nop 0
	v_mul_f32_e32 v81, v81, v89
	v_add_f32_e32 v90, 1.0, v90
	v_mul_f32_e32 v89, v80, v81
	v_mov_b32_e32 v80, v82
	v_mov_b32_e32 v81, v86
	v_pk_mul_f32 v[80:81], v[80:81], v[100:101] op_sel_hi:[1,0]
	v_mul_f32_e32 v82, 0xbfb8aa3b, v81
	v_exp_f32_e32 v82, v82
	v_rcp_f32_e32 v86, v90
	s_nop 0
	v_mul_f32_e32 v85, v85, v86
	v_add_f32_e32 v82, 1.0, v82
	v_mul_f32_e32 v90, v84, v85
	v_mov_b32_e32 v94, v91
	v_pk_mul_f32 v[84:85], v[94:95], v[100:101] op_sel_hi:[1,0]
	v_mul_f32_e32 v91, 0xbfb8aa3b, v85
	v_exp_f32_e32 v91, v91
	v_rcp_f32_e32 v82, v82
	s_nop 0
	v_mul_f32_e32 v81, v81, v82
	v_add_f32_e32 v91, 1.0, v91
	v_mul_f32_e32 v94, v80, v81
	v_mov_b32_e32 v86, v83
	v_pk_mul_f32 v[80:81], v[86:87], v[100:101] op_sel_hi:[1,0]
	v_mul_f32_e32 v83, 0xbfb8aa3b, v81
	v_exp_f32_e32 v83, v83
	v_rcp_f32_e32 v82, v91
	s_nop 0
	v_mul_f32_e32 v82, v85, v82
	v_add_f32_e32 v83, 1.0, v83
	v_mul_f32_e32 v85, v84, v82
	v_rcp_f32_e32 v82, v83
	s_nop 0
	v_mul_f32_e32 v81, v81, v82
	v_mul_f32_e32 v91, v80, v81
	v_fmamk_f32 v80, v159, 0x39800000, v154
	v_rsq_f32_e32 v84, v80
	v_mov_b32_e32 v82, v72
	v_mov_b32_e32 v83, v76
	v_cvt_pk_bf16_f32 v80, v101, v88
	v_pk_mul_f32 v[86:87], v[82:83], v[84:85] op_sel_hi:[1,0]
	v_cvt_pk_bf16_f32 v81, v90, v85
	v_cvt_pk_bf16_f32 v82, v96, v89
	v_mad_i64_i32 v[88:89], s[0:1], v144, s52, v[112:113]
	v_mul_f32_e32 v72, 0xbfb8aa3b, v87
	v_exp_f32_e32 v72, v72
	v_lshl_add_u64 v[88:89], v[88:89], 0, v[114:115]
	v_cvt_pk_bf16_f32 v83, v94, v91
	global_store_dwordx4 v[88:89], v[80:83], off
	v_add_f32_e32 v72, 1.0, v72
	s_nop 0
	v_mov_b32_e32 v81, v68
	v_mov_b32_e32 v80, v64
	v_pk_mul_f32 v[80:81], v[80:81], v[84:85] op_sel_hi:[1,0]
	v_mul_f32_e32 v64, 0xbfb8aa3b, v81
	v_exp_f32_e32 v64, v64
	v_rcp_f32_e32 v68, v72
	s_nop 0
	v_mul_f32_e32 v68, v87, v68
	v_add_f32_e32 v64, 1.0, v64
	v_mul_f32_e32 v85, v86, v68
	v_mov_b32_e32 v76, v73
	v_pk_mul_f32 v[72:73], v[76:77], v[84:85] op_sel_hi:[1,0]
	v_mul_f32_e32 v76, 0xbfb8aa3b, v73
	v_exp_f32_e32 v76, v76
	v_rcp_f32_e32 v64, v64
	s_nop 0
	v_mul_f32_e32 v64, v81, v64
	v_add_f32_e32 v76, 1.0, v76
	v_mul_f32_e32 v80, v80, v64
	v_mov_b32_e32 v68, v65
	v_pk_mul_f32 v[64:65], v[68:69], v[84:85] op_sel_hi:[1,0]
	v_mul_f32_e32 v68, 0xbfb8aa3b, v65
	v_exp_f32_e32 v68, v68
	s_nop 0
	v_add_f32_e32 v77, 1.0, v68
	v_rcp_f32_e32 v68, v76
	s_nop 0
	v_mul_f32_e32 v68, v73, v68
	v_mul_f32_e32 v72, v72, v68
	v_mov_b32_e32 v68, v74
	v_mov_b32_e32 v69, v78
	v_pk_mul_f32 v[68:69], v[68:69], v[84:85] op_sel_hi:[1,0]
	v_mul_f32_e32 v74, 0xbfb8aa3b, v69
	v_exp_f32_e32 v74, v74
	v_rcp_f32_e32 v73, v77
	s_nop 0
	v_mul_f32_e32 v65, v65, v73
	v_add_f32_e32 v74, 1.0, v74
	v_mul_f32_e32 v73, v64, v65
	v_mov_b32_e32 v64, v66
	v_mov_b32_e32 v65, v70
	v_pk_mul_f32 v[64:65], v[64:65], v[84:85] op_sel_hi:[1,0]
	v_mul_f32_e32 v66, 0xbfb8aa3b, v65
	v_exp_f32_e32 v66, v66
	v_rcp_f32_e32 v70, v74
	s_nop 0
	v_mul_f32_e32 v69, v69, v70
	v_add_f32_e32 v66, 1.0, v66
	v_mul_f32_e32 v74, v68, v69
	v_mov_b32_e32 v78, v75
	v_pk_mul_f32 v[68:69], v[78:79], v[84:85] op_sel_hi:[1,0]
	v_mul_f32_e32 v75, 0xbfb8aa3b, v69
	v_exp_f32_e32 v75, v75
	v_rcp_f32_e32 v66, v66
	s_nop 0
	v_mul_f32_e32 v65, v65, v66
; DI float sigmoidf_(float z) { return 1.0f / (1.0f + __expf(-z)); }
; DI v4u pack8(const f4& a, const f4& b) { v4u w; w.x = cvt_pk_bf16(a[0], a[1]); w.y = cvt_pk_bf16(a[2], a[3]); w.z = cvt_pk_bf16(b[0], b[1]); w.w = cvt_pk_bf16(b[2], b[3]); return w; }
;     DI void operator()(f4 (&acc)[2][2][4][2], const Unit& u, int wr, int wc, int fr, int fq) const {
;     ...
;             for (int m = 0; m < 4; ++m) rr[ai][m] = ss[row0 + ai * HALF + m * 16];
; #pragma unroll
;         for (int ai = 0; ai < 2; ++ai)
; #pragma unroll
;             for (int m = 0; m < 4; ++m) { const int row = row0 + ai * HALF + m * 16; const float r = __builtin_amdgcn_rsqf(rr[ai][m] * (1.0f / D) + RMS_EPS);
;                 f4 o0, o1;
; #pragma unroll
;                 for (int e = 0; e < 4; ++e) { const float a0 = acc[ai][0][m][0][e] * r, a1 = acc[ai][0][m][1][e] * r;
;                     o0[e] = a0 * sigmoidf_(a0) * (acc[ai][1][m][0][e] * r); o1[e] = a1 * sigmoidf_(a1) * (acc[ai][1][m][1][e] * r); }
;                 *(v4u*)(uout + (size_t)row * DFF + col0) = pack8(o0, o1); }
	v_add_f32_e32 v75, 1.0, v75
	v_mul_f32_e32 v78, v64, v65
	v_mov_b32_e32 v70, v67
	v_pk_mul_f32 v[64:65], v[70:71], v[84:85] op_sel_hi:[1,0]
	v_mul_f32_e32 v67, 0xbfb8aa3b, v65
	v_exp_f32_e32 v67, v67
	v_rcp_f32_e32 v66, v75
	s_nop 0
	v_mul_f32_e32 v66, v69, v66
	v_add_f32_e32 v67, 1.0, v67
	v_mul_f32_e32 v69, v68, v66
	v_rcp_f32_e32 v66, v67
	s_nop 0
	v_mul_f32_e32 v65, v65, v66
	v_mul_f32_e32 v75, v64, v65
	v_fmamk_f32 v64, v158, 0x39800000, v154
	v_rsq_f32_e32 v68, v64
	v_mov_b32_e32 v66, v56
	v_mov_b32_e32 v67, v60
	v_cvt_pk_bf16_f32 v64, v85, v72
	v_pk_mul_f32 v[70:71], v[66:67], v[68:69] op_sel_hi:[1,0]
	v_cvt_pk_bf16_f32 v65, v74, v69
	v_cvt_pk_bf16_f32 v66, v80, v73
	v_mad_i64_i32 v[72:73], s[0:1], v120, s52, v[112:113]
	v_mul_f32_e32 v56, 0xbfb8aa3b, v71
	v_exp_f32_e32 v56, v56
	v_lshl_add_u64 v[72:73], v[72:73], 0, v[114:115]
	v_cvt_pk_bf16_f32 v67, v78, v75
	global_store_dwordx4 v[72:73], v[64:67], off
	v_add_f32_e32 v56, 1.0, v56
	s_nop 0
	v_mov_b32_e32 v65, v52
	v_mov_b32_e32 v64, v48
	v_pk_mul_f32 v[64:65], v[64:65], v[68:69] op_sel_hi:[1,0]
	v_mul_f32_e32 v48, 0xbfb8aa3b, v65
	v_exp_f32_e32 v48, v48
	v_rcp_f32_e32 v52, v56
	s_nop 0
	v_mul_f32_e32 v52, v71, v52
	v_add_f32_e32 v48, 1.0, v48
	v_mul_f32_e32 v69, v70, v52
	v_mov_b32_e32 v60, v57
	v_pk_mul_f32 v[56:57], v[60:61], v[68:69] op_sel_hi:[1,0]
	v_mul_f32_e32 v60, 0xbfb8aa3b, v57
	v_exp_f32_e32 v60, v60
	v_rcp_f32_e32 v48, v48
	s_nop 0
	v_mul_f32_e32 v48, v65, v48
	v_add_f32_e32 v60, 1.0, v60
	v_mul_f32_e32 v64, v64, v48
	v_mov_b32_e32 v52, v49
	v_pk_mul_f32 v[48:49], v[52:53], v[68:69] op_sel_hi:[1,0]
	v_mul_f32_e32 v52, 0xbfb8aa3b, v49
	v_exp_f32_e32 v52, v52
	s_nop 0
	v_add_f32_e32 v61, 1.0, v52
	v_rcp_f32_e32 v52, v60
	s_nop 0
	v_mul_f32_e32 v52, v57, v52
	v_mul_f32_e32 v56, v56, v52
	v_mov_b32_e32 v52, v58
	v_mov_b32_e32 v53, v62
	v_pk_mul_f32 v[52:53], v[52:53], v[68:69] op_sel_hi:[1,0]
	v_mul_f32_e32 v58, 0xbfb8aa3b, v53
	v_exp_f32_e32 v58, v58
	v_rcp_f32_e32 v57, v61
	s_nop 0
	v_mul_f32_e32 v49, v49, v57
	v_add_f32_e32 v58, 1.0, v58
	v_mul_f32_e32 v57, v48, v49
	v_mov_b32_e32 v48, v50
	v_mov_b32_e32 v49, v54
	v_pk_mul_f32 v[48:49], v[48:49], v[68:69] op_sel_hi:[1,0]
	v_mul_f32_e32 v50, 0xbfb8aa3b, v49
	v_exp_f32_e32 v50, v50
	v_rcp_f32_e32 v54, v58
	s_nop 0
	v_mul_f32_e32 v53, v53, v54
	v_add_f32_e32 v50, 1.0, v50
	v_mul_f32_e32 v58, v52, v53
	v_mov_b32_e32 v62, v59
	v_pk_mul_f32 v[52:53], v[62:63], v[68:69] op_sel_hi:[1,0]
	v_mul_f32_e32 v59, 0xbfb8aa3b, v53
	v_exp_f32_e32 v59, v59
	v_rcp_f32_e32 v50, v50
	s_nop 0
	v_mul_f32_e32 v49, v49, v50
	v_add_f32_e32 v59, 1.0, v59
	v_mul_f32_e32 v62, v48, v49
	v_mov_b32_e32 v54, v51
	v_pk_mul_f32 v[48:49], v[54:55], v[68:69] op_sel_hi:[1,0]
	v_mul_f32_e32 v51, 0xbfb8aa3b, v49
	v_exp_f32_e32 v51, v51
	v_rcp_f32_e32 v50, v59
	s_nop 0
	v_mul_f32_e32 v50, v53, v50
	v_add_f32_e32 v51, 1.0, v51
	v_mul_f32_e32 v53, v52, v50
	v_rcp_f32_e32 v50, v51
	s_nop 0
	v_mul_f32_e32 v49, v49, v50
	v_mul_f32_e32 v59, v48, v49
	v_fmamk_f32 v48, v157, 0x39800000, v154
	v_rsq_f32_e32 v52, v48
	v_mov_b32_e32 v50, v40
	v_mov_b32_e32 v51, v44
	v_cvt_pk_bf16_f32 v48, v69, v56
	v_pk_mul_f32 v[54:55], v[50:51], v[52:53] op_sel_hi:[1,0]
	v_cvt_pk_bf16_f32 v49, v58, v53
	v_cvt_pk_bf16_f32 v50, v64, v57
	v_mad_i64_i32 v[56:57], s[0:1], v156, s52, v[112:113]
	v_mul_f32_e32 v40, 0xbfb8aa3b, v55
	v_exp_f32_e32 v40, v40
	v_lshl_add_u64 v[56:57], v[56:57], 0, v[114:115]
	v_cvt_pk_bf16_f32 v51, v62, v59
	global_store_dwordx4 v[56:57], v[48:51], off
	v_add_f32_e32 v40, 1.0, v40
	s_nop 0
	v_mov_b32_e32 v49, v36
	v_mov_b32_e32 v48, v32
	v_pk_mul_f32 v[48:49], v[48:49], v[52:53] op_sel_hi:[1,0]
	v_mul_f32_e32 v32, 0xbfb8aa3b, v49
	v_exp_f32_e32 v32, v32
	v_rcp_f32_e32 v36, v40
	s_nop 0
	v_mul_f32_e32 v36, v55, v36
	v_add_f32_e32 v32, 1.0, v32
	v_mul_f32_e32 v53, v54, v36
	v_mov_b32_e32 v44, v41
	v_pk_mul_f32 v[40:41], v[44:45], v[52:53] op_sel_hi:[1,0]
	v_mul_f32_e32 v44, 0xbfb8aa3b, v41
	v_exp_f32_e32 v44, v44
	v_rcp_f32_e32 v32, v32
	s_nop 0
	v_mul_f32_e32 v32, v49, v32
	v_add_f32_e32 v44, 1.0, v44
	v_mul_f32_e32 v48, v48, v32
	v_mov_b32_e32 v36, v33
	v_pk_mul_f32 v[32:33], v[36:37], v[52:53] op_sel_hi:[1,0]
	v_mul_f32_e32 v36, 0xbfb8aa3b, v33
	v_exp_f32_e32 v36, v36
	s_nop 0
	v_add_f32_e32 v45, 1.0, v36
	v_rcp_f32_e32 v36, v44
	s_nop 0
	v_mul_f32_e32 v36, v41, v36
	v_mul_f32_e32 v40, v40, v36
	v_mov_b32_e32 v36, v42
	v_mov_b32_e32 v37, v46
	v_pk_mul_f32 v[36:37], v[36:37], v[52:53] op_sel_hi:[1,0]
	v_mul_f32_e32 v42, 0xbfb8aa3b, v37
	v_exp_f32_e32 v42, v42
	v_rcp_f32_e32 v41, v45
	s_nop 0
	v_mul_f32_e32 v33, v33, v41
	v_add_f32_e32 v42, 1.0, v42
	v_mul_f32_e32 v41, v32, v33
	v_mov_b32_e32 v32, v34
	v_mov_b32_e32 v33, v38
	v_pk_mul_f32 v[32:33], v[32:33], v[52:53] op_sel_hi:[1,0]
	v_mul_f32_e32 v34, 0xbfb8aa3b, v33
	v_exp_f32_e32 v34, v34
	v_rcp_f32_e32 v38, v42
	s_nop 0
	v_mul_f32_e32 v37, v37, v38
	v_add_f32_e32 v34, 1.0, v34
	v_mul_f32_e32 v42, v36, v37
	v_mov_b32_e32 v46, v43
	v_pk_mul_f32 v[36:37], v[46:47], v[52:53] op_sel_hi:[1,0]
	v_mul_f32_e32 v43, 0xbfb8aa3b, v37
	v_exp_f32_e32 v43, v43
	v_rcp_f32_e32 v34, v34
	s_nop 0
	v_mul_f32_e32 v33, v33, v34
	v_add_f32_e32 v43, 1.0, v43
	v_mul_f32_e32 v46, v32, v33
	v_mov_b32_e32 v38, v35
	v_pk_mul_f32 v[32:33], v[38:39], v[52:53] op_sel_hi:[1,0]
	v_mul_f32_e32 v35, 0xbfb8aa3b, v33
	v_exp_f32_e32 v35, v35
	v_rcp_f32_e32 v34, v43
	s_nop 0
	v_mul_f32_e32 v34, v37, v34
	v_add_f32_e32 v35, 1.0, v35
	v_mul_f32_e32 v37, v36, v34
	v_rcp_f32_e32 v34, v35
	s_nop 0
; DI float sigmoidf_(float z) { return 1.0f / (1.0f + __expf(-z)); }
; DI v4u pack8(const f4& a, const f4& b) { v4u w; w.x = cvt_pk_bf16(a[0], a[1]); w.y = cvt_pk_bf16(a[2], a[3]); w.z = cvt_pk_bf16(b[0], b[1]); w.w = cvt_pk_bf16(b[2], b[3]); return w; }
;     DI void operator()(f4 (&acc)[2][2][4][2], const Unit& u, int wr, int wc, int fr, int fq) const {
;     ...
;             for (int m = 0; m < 4; ++m) rr[ai][m] = ss[row0 + ai * HALF + m * 16];
; #pragma unroll
;         for (int ai = 0; ai < 2; ++ai)
; #pragma unroll
;             for (int m = 0; m < 4; ++m) { const int row = row0 + ai * HALF + m * 16; const float r = __builtin_amdgcn_rsqf(rr[ai][m] * (1.0f / D) + RMS_EPS);
;                 f4 o0, o1;
; #pragma unroll
;                 for (int e = 0; e < 4; ++e) { const float a0 = acc[ai][0][m][0][e] * r, a1 = acc[ai][0][m][1][e] * r;
;                     o0[e] = a0 * sigmoidf_(a0) * (acc[ai][1][m][0][e] * r); o1[e] = a1 * sigmoidf_(a1) * (acc[ai][1][m][1][e] * r); }
;                 *(v4u*)(uout + (size_t)row * DFF + col0) = pack8(o0, o1); }
	v_mul_f32_e32 v33, v33, v34
	v_mul_f32_e32 v43, v32, v33
	v_fmamk_f32 v32, v147, 0x39800000, v154
	v_rsq_f32_e32 v36, v32
	v_mov_b32_e32 v34, v24
	v_mov_b32_e32 v35, v28
	v_cvt_pk_bf16_f32 v32, v53, v40
	v_pk_mul_f32 v[38:39], v[34:35], v[36:37] op_sel_hi:[1,0]
	v_cvt_pk_bf16_f32 v33, v42, v37
	v_cvt_pk_bf16_f32 v34, v48, v41
	v_mad_i64_i32 v[40:41], s[0:1], v155, s52, v[112:113]
	v_mul_f32_e32 v24, 0xbfb8aa3b, v39
	v_exp_f32_e32 v24, v24
	v_lshl_add_u64 v[40:41], v[40:41], 0, v[114:115]
	v_cvt_pk_bf16_f32 v35, v46, v43
	global_store_dwordx4 v[40:41], v[32:35], off
	v_add_f32_e32 v24, 1.0, v24
	s_nop 0
	v_mov_b32_e32 v33, v20
	v_mov_b32_e32 v32, v16
	v_pk_mul_f32 v[32:33], v[32:33], v[36:37] op_sel_hi:[1,0]
	v_mul_f32_e32 v16, 0xbfb8aa3b, v33
	v_exp_f32_e32 v16, v16
	v_rcp_f32_e32 v20, v24
	s_nop 0
	v_mul_f32_e32 v20, v39, v20
	v_add_f32_e32 v16, 1.0, v16
	v_mul_f32_e32 v37, v38, v20
	v_mov_b32_e32 v28, v25
	v_pk_mul_f32 v[24:25], v[28:29], v[36:37] op_sel_hi:[1,0]
	v_mul_f32_e32 v28, 0xbfb8aa3b, v25
	v_exp_f32_e32 v28, v28
	v_rcp_f32_e32 v16, v16
	s_nop 0
	v_mul_f32_e32 v16, v33, v16
	v_add_f32_e32 v28, 1.0, v28
	v_mul_f32_e32 v32, v32, v16
	v_mov_b32_e32 v20, v17
	v_pk_mul_f32 v[16:17], v[20:21], v[36:37] op_sel_hi:[1,0]
	v_mul_f32_e32 v20, 0xbfb8aa3b, v17
	v_exp_f32_e32 v20, v20
	s_nop 0
	v_add_f32_e32 v29, 1.0, v20
	v_rcp_f32_e32 v20, v28
	s_nop 0
	v_mul_f32_e32 v20, v25, v20
	v_mul_f32_e32 v24, v24, v20
	v_mov_b32_e32 v20, v26
	v_mov_b32_e32 v21, v30
	v_pk_mul_f32 v[20:21], v[20:21], v[36:37] op_sel_hi:[1,0]
	v_mul_f32_e32 v26, 0xbfb8aa3b, v21
	v_exp_f32_e32 v26, v26
	v_rcp_f32_e32 v25, v29
	s_nop 0
	v_mul_f32_e32 v17, v17, v25
	v_add_f32_e32 v26, 1.0, v26
	v_mul_f32_e32 v25, v16, v17
	v_mov_b32_e32 v16, v18
	v_mov_b32_e32 v17, v22
	v_pk_mul_f32 v[16:17], v[16:17], v[36:37] op_sel_hi:[1,0]
	v_mul_f32_e32 v18, 0xbfb8aa3b, v17
	v_exp_f32_e32 v18, v18
	v_rcp_f32_e32 v22, v26
	s_nop 0
	v_mul_f32_e32 v21, v21, v22
	v_add_f32_e32 v18, 1.0, v18
	v_mul_f32_e32 v26, v20, v21
	v_mov_b32_e32 v30, v27
	v_pk_mul_f32 v[20:21], v[30:31], v[36:37] op_sel_hi:[1,0]
	v_mul_f32_e32 v27, 0xbfb8aa3b, v21
	v_exp_f32_e32 v27, v27
	v_rcp_f32_e32 v18, v18
	s_nop 0
	v_mul_f32_e32 v17, v17, v18
	v_add_f32_e32 v27, 1.0, v27
	v_mul_f32_e32 v30, v16, v17
	v_mov_b32_e32 v22, v19
	v_pk_mul_f32 v[16:17], v[22:23], v[36:37] op_sel_hi:[1,0]
	v_mul_f32_e32 v19, 0xbfb8aa3b, v17
	v_exp_f32_e32 v19, v19
	v_rcp_f32_e32 v18, v27
	s_nop 0
	v_mul_f32_e32 v18, v21, v18
	v_add_f32_e32 v19, 1.0, v19
	v_mul_f32_e32 v21, v20, v18
	v_rcp_f32_e32 v18, v19
	s_nop 0
	v_mul_f32_e32 v17, v17, v18
	v_mul_f32_e32 v27, v16, v17
	v_fmamk_f32 v16, v145, 0x39800000, v154
	v_rsq_f32_e32 v20, v16
	v_mov_b32_e32 v18, v8
	v_mov_b32_e32 v19, v12
	v_cvt_pk_bf16_f32 v16, v37, v24
	v_pk_mul_f32 v[22:23], v[18:19], v[20:21] op_sel_hi:[1,0]
	v_cvt_pk_bf16_f32 v17, v26, v21
	v_cvt_pk_bf16_f32 v18, v32, v25
	v_mad_i64_i32 v[24:25], s[0:1], v149, s52, v[112:113]
	v_mul_f32_e32 v8, 0xbfb8aa3b, v23
	v_exp_f32_e32 v8, v8
	v_lshl_add_u64 v[24:25], v[24:25], 0, v[114:115]
	v_cvt_pk_bf16_f32 v19, v30, v27
	global_store_dwordx4 v[24:25], v[16:19], off
	v_add_f32_e32 v8, 1.0, v8
	s_nop 0
	v_mov_b32_e32 v17, v4
	v_mov_b32_e32 v16, v0
	v_pk_mul_f32 v[16:17], v[16:17], v[20:21] op_sel_hi:[1,0]
	v_mul_f32_e32 v0, 0xbfb8aa3b, v17
	v_exp_f32_e32 v0, v0
	v_rcp_f32_e32 v4, v8
	s_nop 0
	v_mul_f32_e32 v4, v23, v4
	v_add_f32_e32 v0, 1.0, v0
	v_mul_f32_e32 v21, v22, v4
	v_mov_b32_e32 v12, v9
	v_pk_mul_f32 v[8:9], v[12:13], v[20:21] op_sel_hi:[1,0]
	v_mul_f32_e32 v12, 0xbfb8aa3b, v9
	v_exp_f32_e32 v12, v12
	v_rcp_f32_e32 v0, v0
	s_nop 0
	v_mul_f32_e32 v0, v17, v0
	v_add_f32_e32 v12, 1.0, v12
	v_mul_f32_e32 v16, v16, v0
	v_mov_b32_e32 v4, v1
	v_pk_mul_f32 v[0:1], v[4:5], v[20:21] op_sel_hi:[1,0]
	v_mul_f32_e32 v4, 0xbfb8aa3b, v1
	v_exp_f32_e32 v4, v4
	s_nop 0
	v_add_f32_e32 v13, 1.0, v4
	v_rcp_f32_e32 v4, v12
	s_nop 0
	v_mul_f32_e32 v4, v9, v4
	v_mul_f32_e32 v8, v8, v4
	v_mov_b32_e32 v4, v10
	v_mov_b32_e32 v5, v14
	v_pk_mul_f32 v[4:5], v[4:5], v[20:21] op_sel_hi:[1,0]
	v_mul_f32_e32 v10, 0xbfb8aa3b, v5
	v_exp_f32_e32 v10, v10
	v_rcp_f32_e32 v9, v13
	s_nop 0
	v_mul_f32_e32 v1, v1, v9
	v_add_f32_e32 v10, 1.0, v10
	v_mul_f32_e32 v9, v0, v1
	v_mov_b32_e32 v0, v2
	v_mov_b32_e32 v1, v6
	v_pk_mul_f32 v[0:1], v[0:1], v[20:21] op_sel_hi:[1,0]
	v_mul_f32_e32 v2, 0xbfb8aa3b, v1
	v_exp_f32_e32 v2, v2
	v_rcp_f32_e32 v6, v10
	s_nop 0
	v_mul_f32_e32 v5, v5, v6
	v_add_f32_e32 v2, 1.0, v2
	v_mul_f32_e32 v10, v4, v5
	v_mov_b32_e32 v14, v11
	v_pk_mul_f32 v[4:5], v[14:15], v[20:21] op_sel_hi:[1,0]
	v_mul_f32_e32 v11, 0xbfb8aa3b, v5
	v_exp_f32_e32 v11, v11
	v_rcp_f32_e32 v2, v2
	s_nop 0
	v_mul_f32_e32 v1, v1, v2
	v_add_f32_e32 v11, 1.0, v11
	v_mul_f32_e32 v14, v0, v1
	v_mov_b32_e32 v6, v3
	v_pk_mul_f32 v[0:1], v[6:7], v[20:21] op_sel_hi:[1,0]
	v_mul_f32_e32 v3, 0xbfb8aa3b, v1
	v_exp_f32_e32 v3, v3
	v_rcp_f32_e32 v2, v11
	s_nop 0
	v_mul_f32_e32 v2, v5, v2
	v_add_f32_e32 v3, 1.0, v3
	v_mul_f32_e32 v2, v4, v2
	v_rcp_f32_e32 v3, v3
	s_nop 0
	v_mul_f32_e32 v1, v1, v3
	v_mad_i64_i32 v[4:5], s[0:1], v121, s52, v[112:113]
	v_mul_f32_e32 v3, v0, v1
	v_lshl_add_u64 v[4:5], v[4:5], 0, v[114:115]
	s_andn2_b64 vcc, exec, s[4:5]
	s_mov_b64 s[0:1], -1
	v_cvt_pk_bf16_f32 v0, v21, v8
	v_cvt_pk_bf16_f32 v1, v10, v2
	v_cvt_pk_bf16_f32 v2, v16, v9
	v_cvt_pk_bf16_f32 v3, v14, v3
	global_store_dwordx4 v[4:5], v[0:3], off
	s_cbranch_vccnz .LBB0_2802
	s_andn2_b64 vcc, exec, s[12:13]
	s_cbranch_vccnz .LBB0_2801
	s_barrier
	s_branch .LBB0_2801

; DI float sigmoidf_(float z) { return 1.0f / (1.0f + __expf(-z)); }
; DI v4u pack8(const f4& a, const f4& b) { v4u w; w.x = cvt_pk_bf16(a[0], a[1]); w.y = cvt_pk_bf16(a[2], a[3]); w.z = cvt_pk_bf16(b[0], b[1]); w.w = cvt_pk_bf16(b[2], b[3]); return w; }
;     DI void operator()(f4 (&acc)[2][2][4][2], const Unit& u, int wr, int wc, int fr, int fq) const {
;     ...
;             for (int m = 0; m < 4; ++m) rr[ai][m] = ss[row0 + ai * HALF + m * 16];
; #pragma unroll
;         for (int ai = 0; ai < 2; ++ai)
; #pragma unroll
;             for (int m = 0; m < 4; ++m) { const int row = row0 + ai * HALF + m * 16; const float r = __builtin_amdgcn_rsqf(rr[ai][m] * (1.0f / D) + RMS_EPS);
;                 f4 o0, o1;
; #pragma unroll
;                 for (int e = 0; e < 4; ++e) { const float a0 = acc[ai][0][m][0][e] * r, a1 = acc[ai][0][m][1][e] * r;
;                     o0[e] = a0 * sigmoidf_(a0) * (acc[ai][1][m][0][e] * r); o1[e] = a1 * sigmoidf_(a1) * (acc[ai][1][m][1][e] * r); }
;                 *(v4u*)(uout + (size_t)row * DFF + col0) = pack8(o0, o1); }
.LBB0_2829:
	s_lshl_b32 s0, s0, 8
	s_add_i32 s0, s0, s36
	v_mbcnt_lo_u32_b32 v144, -1, 0
	v_mbcnt_hi_u32_b32 v144, -1, v144
	v_mov_b32_e32 v164, v112
	v_and_or_b32 v148, v144, 15, s0
	v_ashrrev_i32_e32 v149, 31, v148
	v_lshl_add_u64 v[160:161], v[148:149], 2, s[10:11]
	global_load_dword v170, v[160:161], off
	v_ashrrev_i32_e32 v112, 1, v144
	v_or_b32_e32 v146, 16, v148
	v_or_b32_e32 v144, 32, v148
	v_mov_b32_e32 v162, v120
	v_or_b32_e32 v120, 48, v148
	v_ashrrev_i32_e32 v147, 31, v146
	v_ashrrev_i32_e32 v145, 31, v144
	v_mov_b32_e32 v163, v124
	v_mov_b32_e32 v165, v116
	v_mov_b32_e32 v124, v121
	v_mov_b32_e32 v116, v113
	v_and_b32_e32 v171, -8, v112
	v_ashrrev_i32_e32 v121, 31, v120
	v_lshl_add_u64 v[112:113], v[146:147], 2, s[10:11]
	v_lshl_add_u64 v[166:167], v[144:145], 2, s[10:11]
	v_lshl_add_u64 v[168:169], v[120:121], 2, s[10:11]
	global_load_dword v158, v[160:161], off offset:512
	global_load_dword v157, v[160:161], off offset:576
	global_load_dword v147, v[160:161], off offset:640
	global_load_dword v172, v[112:113], off
	s_nop 0
	global_load_dword v166, v[166:167], off
	s_nop 0
	global_load_dword v159, v[168:169], off
	global_load_dword v145, v[160:161], off offset:704
	s_lshl_b32 s0, s1, 7
	s_or_b32 s0, s0, s37
	v_add_u32_e32 v160, s0, v171
	v_ashrrev_i32_e32 v161, 31, v160
	v_add_u32_e32 v156, 0x80, v148
	v_add_u32_e32 v155, 0x90, v148
	v_add_u32_e32 v149, 0xa0, v148
	v_add_u32_e32 v121, 0xb0, v148
	s_waitcnt vmcnt(0)
	v_fmamk_f32 v112, v170, 0x39800000, v154
	v_rsq_f32_e32 v112, v112
	s_nop 0
	v_pk_mul_f32 v[162:163], v[162:163], v[112:113] op_sel_hi:[1,0]
	v_pk_mul_f32 v[164:165], v[164:165], v[112:113] op_sel_hi:[1,0]
	v_pk_mul_f32 v[124:125], v[124:125], v[112:113] op_sel_hi:[1,0]
	v_pk_mul_f32 v[116:117], v[116:117], v[112:113] op_sel_hi:[1,0]
	v_mul_f32_e32 v113, 0xbfb8aa3b, v163
	v_mul_f32_e32 v167, 0xbfb8aa3b, v165
	v_exp_f32_e32 v113, v113
	v_mul_f32_e32 v168, 0xbfb8aa3b, v125
	v_exp_f32_e32 v167, v167
	v_exp_f32_e32 v168, v168
	v_add_f32_e32 v113, 1.0, v113
	v_add_f32_e32 v167, 1.0, v167
	v_add_f32_e32 v168, 1.0, v168
	v_mul_f32_e32 v169, 0xbfb8aa3b, v117
	v_exp_f32_e32 v169, v169
	v_rcp_f32_e32 v113, v113
	s_nop 0
	v_mul_f32_e32 v113, v163, v113
	v_rcp_f32_e32 v163, v167
	v_add_f32_e32 v169, 1.0, v169
	v_mul_f32_e32 v162, v162, v113
	v_mul_f32_e32 v113, v165, v163
	v_rcp_f32_e32 v163, v168
	v_mul_f32_e32 v164, v164, v113
	v_mul_f32_e32 v113, v125, v163
	v_mul_f32_e32 v163, v124, v113
	v_mov_b32_e32 v124, v122
	v_mov_b32_e32 v125, v126
	v_pk_mul_f32 v[124:125], v[124:125], v[112:113] op_sel_hi:[1,0]
	v_mul_f32_e32 v113, 0xbfb8aa3b, v125
	v_exp_f32_e32 v113, v113
	s_nop 0
	v_add_f32_e32 v113, 1.0, v113
	v_rcp_f32_e32 v122, v169
	s_nop 0
	v_mul_f32_e32 v117, v117, v122
	v_mul_f32_e32 v167, v116, v117
	v_mov_b32_e32 v116, v114
	v_mov_b32_e32 v117, v118
	v_pk_mul_f32 v[116:117], v[116:117], v[112:113] op_sel_hi:[1,0]
	v_mul_f32_e32 v114, 0xbfb8aa3b, v117
	v_exp_f32_e32 v114, v114
	v_rcp_f32_e32 v113, v113
	s_nop 0
	v_mul_f32_e32 v113, v125, v113
	v_add_f32_e32 v114, 1.0, v114
	v_mul_f32_e32 v124, v124, v113
	v_mov_b32_e32 v126, v123
	v_pk_mul_f32 v[122:123], v[126:127], v[112:113] op_sel_hi:[1,0]
	v_mul_f32_e32 v125, 0xbfb8aa3b, v123
	v_exp_f32_e32 v125, v125
	v_rcp_f32_e32 v113, v114
	s_nop 0
	v_mul_f32_e32 v113, v117, v113
	v_add_f32_e32 v125, 1.0, v125
	v_mul_f32_e32 v114, v116, v113
	v_mov_b32_e32 v118, v115
	v_pk_mul_f32 v[112:113], v[118:119], v[112:113] op_sel_hi:[1,0]
	v_mul_f32_e32 v115, 0xbfb8aa3b, v113
	v_exp_f32_e32 v115, v115
	v_rcp_f32_e32 v116, v125
	s_nop 0
	v_mul_f32_e32 v116, v123, v116
	v_add_f32_e32 v115, 1.0, v115
	v_mul_f32_e32 v119, v122, v116
	v_rcp_f32_e32 v115, v115
	s_nop 0
	v_mul_f32_e32 v113, v113, v115
	v_mul_f32_e32 v112, v112, v113
	v_fmamk_f32 v113, v172, 0x39800000, v154
	v_rsq_f32_e32 v122, v113
	v_cvt_pk_bf16_f32 v116, v162, v163
	v_cvt_pk_bf16_f32 v117, v124, v119
	v_cvt_pk_bf16_f32 v118, v164, v167
	v_cvt_pk_bf16_f32 v119, v114, v112
	v_mov_b32_e32 v112, v104
	v_mov_b32_e32 v113, v108
	v_pk_mul_f32 v[124:125], v[112:113], v[122:123] op_sel_hi:[1,0]
	v_mov_b64_e32 v[112:113], s[14:15]
	v_mul_f32_e32 v104, 0xbfb8aa3b, v125
	v_exp_f32_e32 v104, v104
	v_mad_i64_i32 v[126:127], s[0:1], v148, s53, v[112:113]
	v_lshlrev_b64 v[114:115], 1, v[160:161]
	v_add_f32_e32 v104, 1.0, v104
	v_lshl_add_u64 v[126:127], v[126:127], 0, v[114:115]
	global_store_dwordx4 v[126:127], v[116:119], off
	s_nop 1
	v_mov_b32_e32 v116, v96
	v_mov_b32_e32 v117, v100
	v_pk_mul_f32 v[116:117], v[116:117], v[122:123] op_sel_hi:[1,0]
	v_mul_f32_e32 v96, 0xbfb8aa3b, v117
	v_exp_f32_e32 v96, v96
	v_rcp_f32_e32 v100, v104
	s_nop 0
	v_mul_f32_e32 v100, v125, v100
	v_add_f32_e32 v96, 1.0, v96
	v_mul_f32_e32 v123, v124, v100
	v_mov_b32_e32 v108, v105
	v_pk_mul_f32 v[104:105], v[108:109], v[122:123] op_sel_hi:[1,0]
	v_mul_f32_e32 v108, 0xbfb8aa3b, v105
	v_exp_f32_e32 v108, v108
	v_rcp_f32_e32 v96, v96
	s_nop 0
	v_mul_f32_e32 v96, v117, v96
	v_add_f32_e32 v108, 1.0, v108
	v_mul_f32_e32 v116, v116, v96
	v_mov_b32_e32 v100, v97
	v_pk_mul_f32 v[96:97], v[100:101], v[122:123] op_sel_hi:[1,0]
	v_mul_f32_e32 v100, 0xbfb8aa3b, v97
	v_exp_f32_e32 v100, v100
	s_nop 0
	v_add_f32_e32 v109, 1.0, v100
	v_rcp_f32_e32 v100, v108
	s_nop 0
	v_mul_f32_e32 v100, v105, v100
	v_mul_f32_e32 v104, v104, v100
	v_mov_b32_e32 v100, v106
	v_mov_b32_e32 v101, v110
	v_pk_mul_f32 v[100:101], v[100:101], v[122:123] op_sel_hi:[1,0]
	v_mul_f32_e32 v106, 0xbfb8aa3b, v101
	v_exp_f32_e32 v106, v106
	v_rcp_f32_e32 v105, v109
	s_nop 0
	v_mul_f32_e32 v97, v97, v105
	v_add_f32_e32 v106, 1.0, v106
	v_mul_f32_e32 v105, v96, v97
	v_mov_b32_e32 v96, v98
	v_mov_b32_e32 v97, v102
; DI float sigmoidf_(float z) { return 1.0f / (1.0f + __expf(-z)); }
; DI v4u pack8(const f4& a, const f4& b) { v4u w; w.x = cvt_pk_bf16(a[0], a[1]); w.y = cvt_pk_bf16(a[2], a[3]); w.z = cvt_pk_bf16(b[0], b[1]); w.w = cvt_pk_bf16(b[2], b[3]); return w; }
;     DI void operator()(f4 (&acc)[2][2][4][2], const Unit& u, int wr, int wc, int fr, int fq) const {
;     ...
; #pragma unroll
;         for (int ai = 0; ai < 2; ++ai)
; #pragma unroll
;             for (int m = 0; m < 4; ++m) { const int row = row0 + ai * HALF + m * 16; const float r = __builtin_amdgcn_rsqf(rr[ai][m] * (1.0f / D) + RMS_EPS);
;                 f4 o0, o1;
; #pragma unroll
;                 for (int e = 0; e < 4; ++e) { const float a0 = acc[ai][0][m][0][e] * r, a1 = acc[ai][0][m][1][e] * r;
;                     o0[e] = a0 * sigmoidf_(a0) * (acc[ai][1][m][0][e] * r); o1[e] = a1 * sigmoidf_(a1) * (acc[ai][1][m][1][e] * r); }
;                 *(v4u*)(uout + (size_t)row * DFF + col0) = pack8(o0, o1); }
	v_pk_mul_f32 v[96:97], v[96:97], v[122:123] op_sel_hi:[1,0]
	v_mul_f32_e32 v98, 0xbfb8aa3b, v97
	v_exp_f32_e32 v98, v98
	v_rcp_f32_e32 v102, v106
	s_nop 0
	v_mul_f32_e32 v101, v101, v102
	v_add_f32_e32 v98, 1.0, v98
	v_mul_f32_e32 v106, v100, v101
	v_mov_b32_e32 v110, v107
	v_pk_mul_f32 v[100:101], v[110:111], v[122:123] op_sel_hi:[1,0]
	v_mul_f32_e32 v107, 0xbfb8aa3b, v101
	v_exp_f32_e32 v107, v107
	v_rcp_f32_e32 v98, v98
	s_nop 0
	v_mul_f32_e32 v97, v97, v98
	v_add_f32_e32 v107, 1.0, v107
	v_mul_f32_e32 v110, v96, v97
	v_mov_b32_e32 v102, v99
	v_pk_mul_f32 v[96:97], v[102:103], v[122:123] op_sel_hi:[1,0]
	v_mul_f32_e32 v99, 0xbfb8aa3b, v97
	v_exp_f32_e32 v99, v99
	v_rcp_f32_e32 v98, v107
	s_nop 0
	v_mul_f32_e32 v98, v101, v98
	v_add_f32_e32 v99, 1.0, v99
	v_mul_f32_e32 v101, v100, v98
	v_rcp_f32_e32 v98, v99
	s_nop 0
	v_mul_f32_e32 v97, v97, v98
	v_mul_f32_e32 v107, v96, v97
	v_fmamk_f32 v96, v166, 0x39800000, v154
	v_rsq_f32_e32 v100, v96
	v_mov_b32_e32 v98, v88
	v_mov_b32_e32 v99, v92
	v_cvt_pk_bf16_f32 v96, v123, v104
	v_pk_mul_f32 v[102:103], v[98:99], v[100:101] op_sel_hi:[1,0]
	v_cvt_pk_bf16_f32 v97, v106, v101
	v_cvt_pk_bf16_f32 v98, v116, v105
	v_mad_i64_i32 v[104:105], s[0:1], v146, s53, v[112:113]
	v_mul_f32_e32 v88, 0xbfb8aa3b, v103
	v_exp_f32_e32 v88, v88
	v_lshl_add_u64 v[104:105], v[104:105], 0, v[114:115]
	v_cvt_pk_bf16_f32 v99, v110, v107
	global_store_dwordx4 v[104:105], v[96:99], off
	v_add_f32_e32 v88, 1.0, v88
	s_nop 0
	v_mov_b32_e32 v97, v84
	v_mov_b32_e32 v96, v80
	v_pk_mul_f32 v[96:97], v[96:97], v[100:101] op_sel_hi:[1,0]
	v_mul_f32_e32 v80, 0xbfb8aa3b, v97
	v_exp_f32_e32 v80, v80
	v_rcp_f32_e32 v84, v88
	s_nop 0
	v_mul_f32_e32 v84, v103, v84
	v_add_f32_e32 v80, 1.0, v80
	v_mul_f32_e32 v101, v102, v84
	v_mov_b32_e32 v92, v89
	v_pk_mul_f32 v[88:89], v[92:93], v[100:101] op_sel_hi:[1,0]
	v_mul_f32_e32 v92, 0xbfb8aa3b, v89
	v_exp_f32_e32 v92, v92
	v_rcp_f32_e32 v80, v80
	s_nop 0
	v_mul_f32_e32 v80, v97, v80
	v_add_f32_e32 v92, 1.0, v92
	v_mul_f32_e32 v96, v96, v80
	v_mov_b32_e32 v84, v81
	v_pk_mul_f32 v[80:81], v[84:85], v[100:101] op_sel_hi:[1,0]
	v_mul_f32_e32 v84, 0xbfb8aa3b, v81
	v_exp_f32_e32 v84, v84
	s_nop 0
	v_add_f32_e32 v93, 1.0, v84
	v_rcp_f32_e32 v84, v92
	s_nop 0
	v_mul_f32_e32 v84, v89, v84
	v_mul_f32_e32 v88, v88, v84
	v_mov_b32_e32 v84, v90
	v_mov_b32_e32 v85, v94
	v_pk_mul_f32 v[84:85], v[84:85], v[100:101] op_sel_hi:[1,0]
	v_mul_f32_e32 v90, 0xbfb8aa3b, v85
	v_exp_f32_e32 v90, v90
	v_rcp_f32_e32 v89, v93
	s_nop 0
	v_mul_f32_e32 v81, v81, v89
	v_add_f32_e32 v90, 1.0, v90
	v_mul_f32_e32 v89, v80, v81
	v_mov_b32_e32 v80, v82
	v_mov_b32_e32 v81, v86
	v_pk_mul_f32 v[80:81], v[80:81], v[100:101] op_sel_hi:[1,0]
	v_mul_f32_e32 v82, 0xbfb8aa3b, v81
	v_exp_f32_e32 v82, v82
	v_rcp_f32_e32 v86, v90
	s_nop 0
	v_mul_f32_e32 v85, v85, v86
	v_add_f32_e32 v82, 1.0, v82
	v_mul_f32_e32 v90, v84, v85
	v_mov_b32_e32 v94, v91
	v_pk_mul_f32 v[84:85], v[94:95], v[100:101] op_sel_hi:[1,0]
	v_mul_f32_e32 v91, 0xbfb8aa3b, v85
	v_exp_f32_e32 v91, v91
	v_rcp_f32_e32 v82, v82
	s_nop 0
	v_mul_f32_e32 v81, v81, v82
	v_add_f32_e32 v91, 1.0, v91
	v_mul_f32_e32 v94, v80, v81
	v_mov_b32_e32 v86, v83
	v_pk_mul_f32 v[80:81], v[86:87], v[100:101] op_sel_hi:[1,0]
	v_mul_f32_e32 v83, 0xbfb8aa3b, v81
	v_exp_f32_e32 v83, v83
	v_rcp_f32_e32 v82, v91
	s_nop 0
	v_mul_f32_e32 v82, v85, v82
	v_add_f32_e32 v83, 1.0, v83
	v_mul_f32_e32 v85, v84, v82
	v_rcp_f32_e32 v82, v83
	s_nop 0
	v_mul_f32_e32 v81, v81, v82
	v_mul_f32_e32 v91, v80, v81
	v_fmamk_f32 v80, v159, 0x39800000, v154
	v_rsq_f32_e32 v84, v80
	v_mov_b32_e32 v82, v72
	v_mov_b32_e32 v83, v76
	v_cvt_pk_bf16_f32 v80, v101, v88
	v_pk_mul_f32 v[86:87], v[82:83], v[84:85] op_sel_hi:[1,0]
	v_cvt_pk_bf16_f32 v81, v90, v85
	v_cvt_pk_bf16_f32 v82, v96, v89
	v_mad_i64_i32 v[88:89], s[0:1], v144, s53, v[112:113]
	v_mul_f32_e32 v72, 0xbfb8aa3b, v87
	v_exp_f32_e32 v72, v72
	v_lshl_add_u64 v[88:89], v[88:89], 0, v[114:115]
	v_cvt_pk_bf16_f32 v83, v94, v91
	global_store_dwordx4 v[88:89], v[80:83], off
	v_add_f32_e32 v72, 1.0, v72
	s_nop 0
	v_mov_b32_e32 v81, v68
	v_mov_b32_e32 v80, v64
	v_pk_mul_f32 v[80:81], v[80:81], v[84:85] op_sel_hi:[1,0]
	v_mul_f32_e32 v64, 0xbfb8aa3b, v81
	v_exp_f32_e32 v64, v64
	v_rcp_f32_e32 v68, v72
	s_nop 0
	v_mul_f32_e32 v68, v87, v68
	v_add_f32_e32 v64, 1.0, v64
	v_mul_f32_e32 v85, v86, v68
	v_mov_b32_e32 v76, v73
	v_pk_mul_f32 v[72:73], v[76:77], v[84:85] op_sel_hi:[1,0]
	v_mul_f32_e32 v76, 0xbfb8aa3b, v73
	v_exp_f32_e32 v76, v76
	v_rcp_f32_e32 v64, v64
	s_nop 0
	v_mul_f32_e32 v64, v81, v64
	v_add_f32_e32 v76, 1.0, v76
	v_mul_f32_e32 v80, v80, v64
	v_mov_b32_e32 v68, v65
	v_pk_mul_f32 v[64:65], v[68:69], v[84:85] op_sel_hi:[1,0]
	v_mul_f32_e32 v68, 0xbfb8aa3b, v65
	v_exp_f32_e32 v68, v68
	s_nop 0
	v_add_f32_e32 v77, 1.0, v68
	v_rcp_f32_e32 v68, v76
	s_nop 0
	v_mul_f32_e32 v68, v73, v68
	v_mul_f32_e32 v72, v72, v68
	v_mov_b32_e32 v68, v74
	v_mov_b32_e32 v69, v78
	v_pk_mul_f32 v[68:69], v[68:69], v[84:85] op_sel_hi:[1,0]
	v_mul_f32_e32 v74, 0xbfb8aa3b, v69
	v_exp_f32_e32 v74, v74
	v_rcp_f32_e32 v73, v77
	s_nop 0
	v_mul_f32_e32 v65, v65, v73
	v_add_f32_e32 v74, 1.0, v74
	v_mul_f32_e32 v73, v64, v65
	v_mov_b32_e32 v64, v66
	v_mov_b32_e32 v65, v70
	v_pk_mul_f32 v[64:65], v[64:65], v[84:85] op_sel_hi:[1,0]
	v_mul_f32_e32 v66, 0xbfb8aa3b, v65
	v_exp_f32_e32 v66, v66
	v_rcp_f32_e32 v70, v74
	s_nop 0
	v_mul_f32_e32 v69, v69, v70
	v_add_f32_e32 v66, 1.0, v66
	v_mul_f32_e32 v74, v68, v69
	v_mov_b32_e32 v78, v75
	v_pk_mul_f32 v[68:69], v[78:79], v[84:85] op_sel_hi:[1,0]
	v_mul_f32_e32 v75, 0xbfb8aa3b, v69
	v_exp_f32_e32 v75, v75
	v_rcp_f32_e32 v66, v66
	s_nop 0
	v_mul_f32_e32 v65, v65, v66
; DI float sigmoidf_(float z) { return 1.0f / (1.0f + __expf(-z)); }
; DI v4u pack8(const f4& a, const f4& b) { v4u w; w.x = cvt_pk_bf16(a[0], a[1]); w.y = cvt_pk_bf16(a[2], a[3]); w.z = cvt_pk_bf16(b[0], b[1]); w.w = cvt_pk_bf16(b[2], b[3]); return w; }
;     DI void operator()(f4 (&acc)[2][2][4][2], const Unit& u, int wr, int wc, int fr, int fq) const {
;     ...
; #pragma unroll
;         for (int ai = 0; ai < 2; ++ai)
; #pragma unroll
;             for (int m = 0; m < 4; ++m) { const int row = row0 + ai * HALF + m * 16; const float r = __builtin_amdgcn_rsqf(rr[ai][m] * (1.0f / D) + RMS_EPS);
;                 f4 o0, o1;
; #pragma unroll
;                 for (int e = 0; e < 4; ++e) { const float a0 = acc[ai][0][m][0][e] * r, a1 = acc[ai][0][m][1][e] * r;
;                     o0[e] = a0 * sigmoidf_(a0) * (acc[ai][1][m][0][e] * r); o1[e] = a1 * sigmoidf_(a1) * (acc[ai][1][m][1][e] * r); }
;                 *(v4u*)(uout + (size_t)row * DFF + col0) = pack8(o0, o1); }
	v_add_f32_e32 v75, 1.0, v75
	v_mul_f32_e32 v78, v64, v65
	v_mov_b32_e32 v70, v67
	v_pk_mul_f32 v[64:65], v[70:71], v[84:85] op_sel_hi:[1,0]
	v_mul_f32_e32 v67, 0xbfb8aa3b, v65
	v_exp_f32_e32 v67, v67
	v_rcp_f32_e32 v66, v75
	s_nop 0
	v_mul_f32_e32 v66, v69, v66
	v_add_f32_e32 v67, 1.0, v67
	v_mul_f32_e32 v69, v68, v66
	v_rcp_f32_e32 v66, v67
	s_nop 0
	v_mul_f32_e32 v65, v65, v66
	v_mul_f32_e32 v75, v64, v65
	v_fmamk_f32 v64, v158, 0x39800000, v154
	v_rsq_f32_e32 v68, v64
	v_mov_b32_e32 v66, v56
	v_mov_b32_e32 v67, v60
	v_cvt_pk_bf16_f32 v64, v85, v72
	v_pk_mul_f32 v[70:71], v[66:67], v[68:69] op_sel_hi:[1,0]
	v_cvt_pk_bf16_f32 v65, v74, v69
	v_cvt_pk_bf16_f32 v66, v80, v73
	v_mad_i64_i32 v[72:73], s[0:1], v120, s53, v[112:113]
	v_mul_f32_e32 v56, 0xbfb8aa3b, v71
	v_exp_f32_e32 v56, v56
	v_lshl_add_u64 v[72:73], v[72:73], 0, v[114:115]
	v_cvt_pk_bf16_f32 v67, v78, v75
	global_store_dwordx4 v[72:73], v[64:67], off
	v_add_f32_e32 v56, 1.0, v56
	s_nop 0
	v_mov_b32_e32 v65, v52
	v_mov_b32_e32 v64, v48
	v_pk_mul_f32 v[64:65], v[64:65], v[68:69] op_sel_hi:[1,0]
	v_mul_f32_e32 v48, 0xbfb8aa3b, v65
	v_exp_f32_e32 v48, v48
	v_rcp_f32_e32 v52, v56
	s_nop 0
	v_mul_f32_e32 v52, v71, v52
	v_add_f32_e32 v48, 1.0, v48
	v_mul_f32_e32 v69, v70, v52
	v_mov_b32_e32 v60, v57
	v_pk_mul_f32 v[56:57], v[60:61], v[68:69] op_sel_hi:[1,0]
	v_mul_f32_e32 v60, 0xbfb8aa3b, v57
	v_exp_f32_e32 v60, v60
	v_rcp_f32_e32 v48, v48
	s_nop 0
	v_mul_f32_e32 v48, v65, v48
	v_add_f32_e32 v60, 1.0, v60
	v_mul_f32_e32 v64, v64, v48
	v_mov_b32_e32 v52, v49
	v_pk_mul_f32 v[48:49], v[52:53], v[68:69] op_sel_hi:[1,0]
	v_mul_f32_e32 v52, 0xbfb8aa3b, v49
	v_exp_f32_e32 v52, v52
	s_nop 0
	v_add_f32_e32 v61, 1.0, v52
	v_rcp_f32_e32 v52, v60
	s_nop 0
	v_mul_f32_e32 v52, v57, v52
	v_mul_f32_e32 v56, v56, v52
	v_mov_b32_e32 v52, v58
	v_mov_b32_e32 v53, v62
	v_pk_mul_f32 v[52:53], v[52:53], v[68:69] op_sel_hi:[1,0]
	v_mul_f32_e32 v58, 0xbfb8aa3b, v53
	v_exp_f32_e32 v58, v58
	v_rcp_f32_e32 v57, v61
	s_nop 0
	v_mul_f32_e32 v49, v49, v57
	v_add_f32_e32 v58, 1.0, v58
	v_mul_f32_e32 v57, v48, v49
	v_mov_b32_e32 v48, v50
	v_mov_b32_e32 v49, v54
	v_pk_mul_f32 v[48:49], v[48:49], v[68:69] op_sel_hi:[1,0]
	v_mul_f32_e32 v50, 0xbfb8aa3b, v49
	v_exp_f32_e32 v50, v50
	v_rcp_f32_e32 v54, v58
	s_nop 0
	v_mul_f32_e32 v53, v53, v54
	v_add_f32_e32 v50, 1.0, v50
	v_mul_f32_e32 v58, v52, v53
	v_mov_b32_e32 v62, v59
	v_pk_mul_f32 v[52:53], v[62:63], v[68:69] op_sel_hi:[1,0]
	v_mul_f32_e32 v59, 0xbfb8aa3b, v53
	v_exp_f32_e32 v59, v59
	v_rcp_f32_e32 v50, v50
	s_nop 0
	v_mul_f32_e32 v49, v49, v50
	v_add_f32_e32 v59, 1.0, v59
	v_mul_f32_e32 v62, v48, v49
	v_mov_b32_e32 v54, v51
	v_pk_mul_f32 v[48:49], v[54:55], v[68:69] op_sel_hi:[1,0]
	v_mul_f32_e32 v51, 0xbfb8aa3b, v49
	v_exp_f32_e32 v51, v51
	v_rcp_f32_e32 v50, v59
	s_nop 0
	v_mul_f32_e32 v50, v53, v50
	v_add_f32_e32 v51, 1.0, v51
	v_mul_f32_e32 v53, v52, v50
	v_rcp_f32_e32 v50, v51
	s_nop 0
	v_mul_f32_e32 v49, v49, v50
	v_mul_f32_e32 v59, v48, v49
	v_fmamk_f32 v48, v157, 0x39800000, v154
	v_rsq_f32_e32 v52, v48
	v_mov_b32_e32 v50, v40
	v_mov_b32_e32 v51, v44
	v_cvt_pk_bf16_f32 v48, v69, v56
	v_pk_mul_f32 v[54:55], v[50:51], v[52:53] op_sel_hi:[1,0]
	v_cvt_pk_bf16_f32 v49, v58, v53
	v_cvt_pk_bf16_f32 v50, v64, v57
	v_mad_i64_i32 v[56:57], s[0:1], v156, s53, v[112:113]
	v_mul_f32_e32 v40, 0xbfb8aa3b, v55
	v_exp_f32_e32 v40, v40
	v_lshl_add_u64 v[56:57], v[56:57], 0, v[114:115]
	v_cvt_pk_bf16_f32 v51, v62, v59
	global_store_dwordx4 v[56:57], v[48:51], off
	v_add_f32_e32 v40, 1.0, v40
	s_nop 0
	v_mov_b32_e32 v49, v36
	v_mov_b32_e32 v48, v32
	v_pk_mul_f32 v[48:49], v[48:49], v[52:53] op_sel_hi:[1,0]
	v_mul_f32_e32 v32, 0xbfb8aa3b, v49
	v_exp_f32_e32 v32, v32
	v_rcp_f32_e32 v36, v40
	s_nop 0
	v_mul_f32_e32 v36, v55, v36
	v_add_f32_e32 v32, 1.0, v32
	v_mul_f32_e32 v53, v54, v36
	v_mov_b32_e32 v44, v41
	v_pk_mul_f32 v[40:41], v[44:45], v[52:53] op_sel_hi:[1,0]
	v_mul_f32_e32 v44, 0xbfb8aa3b, v41
	v_exp_f32_e32 v44, v44
	v_rcp_f32_e32 v32, v32
	s_nop 0
	v_mul_f32_e32 v32, v49, v32
	v_add_f32_e32 v44, 1.0, v44
	v_mul_f32_e32 v48, v48, v32
	v_mov_b32_e32 v36, v33
	v_pk_mul_f32 v[32:33], v[36:37], v[52:53] op_sel_hi:[1,0]
	v_mul_f32_e32 v36, 0xbfb8aa3b, v33
	v_exp_f32_e32 v36, v36
	s_nop 0
	v_add_f32_e32 v45, 1.0, v36
	v_rcp_f32_e32 v36, v44
	s_nop 0
	v_mul_f32_e32 v36, v41, v36
	v_mul_f32_e32 v40, v40, v36
	v_mov_b32_e32 v36, v42
	v_mov_b32_e32 v37, v46
	v_pk_mul_f32 v[36:37], v[36:37], v[52:53] op_sel_hi:[1,0]
	v_mul_f32_e32 v42, 0xbfb8aa3b, v37
	v_exp_f32_e32 v42, v42
	v_rcp_f32_e32 v41, v45
	s_nop 0
	v_mul_f32_e32 v33, v33, v41
	v_add_f32_e32 v42, 1.0, v42
	v_mul_f32_e32 v41, v32, v33
	v_mov_b32_e32 v32, v34
	v_mov_b32_e32 v33, v38
	v_pk_mul_f32 v[32:33], v[32:33], v[52:53] op_sel_hi:[1,0]
	v_mul_f32_e32 v34, 0xbfb8aa3b, v33
	v_exp_f32_e32 v34, v34
	v_rcp_f32_e32 v38, v42
	s_nop 0
	v_mul_f32_e32 v37, v37, v38
	v_add_f32_e32 v34, 1.0, v34
	v_mul_f32_e32 v42, v36, v37
	v_mov_b32_e32 v46, v43
	v_pk_mul_f32 v[36:37], v[46:47], v[52:53] op_sel_hi:[1,0]
	v_mul_f32_e32 v43, 0xbfb8aa3b, v37
	v_exp_f32_e32 v43, v43
	v_rcp_f32_e32 v34, v34
	s_nop 0
	v_mul_f32_e32 v33, v33, v34
	v_add_f32_e32 v43, 1.0, v43
	v_mul_f32_e32 v46, v32, v33
	v_mov_b32_e32 v38, v35
	v_pk_mul_f32 v[32:33], v[38:39], v[52:53] op_sel_hi:[1,0]
	v_mul_f32_e32 v35, 0xbfb8aa3b, v33
	v_exp_f32_e32 v35, v35
	v_rcp_f32_e32 v34, v43
	s_nop 0
	v_mul_f32_e32 v34, v37, v34
	v_add_f32_e32 v35, 1.0, v35
	v_mul_f32_e32 v37, v36, v34
	v_rcp_f32_e32 v34, v35
	s_nop 0
; #define PG8_BAR __builtin_amdgcn_s_barrier()
; DI float sigmoidf_(float z) { return 1.0f / (1.0f + __expf(-z)); }
; DI v4u pack8(const f4& a, const f4& b) { v4u w; w.x = cvt_pk_bf16(a[0], a[1]); w.y = cvt_pk_bf16(a[2], a[3]); w.z = cvt_pk_bf16(b[0], b[1]); w.w = cvt_pk_bf16(b[2], b[3]); return w; }
; template <class Epi, class Sched, bool ALIGN_EPI = false, bool SP2 = false>
; __device__ __forceinline__ void gemm_phase(PG8_LAS unsigned char* lds, const Gemm g, const Sched& S, const Epi& E, const int wid) {
;     ...
;         if (!has_next) break;
;         if (!Epi::CHAIN || !E.keep(cur)) {
; #pragma unroll
;         for (int a = 0; a < 2; ++a)
; #pragma unroll
;             for (int b = 0; b < 2; ++b)
; #pragma unroll
;                 for (int m = 0; m < 4; ++m)
; #pragma unroll
;                     for (int n = 0; n < 2; ++n) acc[a][b][m][n] = (f32x4){0.f, 0.f, 0.f, 0.f};
;         }
;         cur = nxt; cA = nA; cB = nB; ++ui;
;         if constexpr (ALIGN_EPI) { if (wr == 1) PG8_BAR; }
;     DI void operator()(f4 (&acc)[2][2][4][2], const Unit& u, int wr, int wc, int fr, int fq) const {
;     ...
; #pragma unroll
;         for (int ai = 0; ai < 2; ++ai)
; #pragma unroll
;             for (int m = 0; m < 4; ++m) { const int row = row0 + ai * HALF + m * 16; const float r = __builtin_amdgcn_rsqf(rr[ai][m] * (1.0f / D) + RMS_EPS);
;                 f4 o0, o1;
; #pragma unroll
;                 for (int e = 0; e < 4; ++e) { const float a0 = acc[ai][0][m][0][e] * r, a1 = acc[ai][0][m][1][e] * r;
;                     o0[e] = a0 * sigmoidf_(a0) * (acc[ai][1][m][0][e] * r); o1[e] = a1 * sigmoidf_(a1) * (acc[ai][1][m][1][e] * r); }
;                 *(v4u*)(uout + (size_t)row * DFF + col0) = pack8(o0, o1); }
	v_mul_f32_e32 v33, v33, v34
	v_mul_f32_e32 v43, v32, v33
	v_fmamk_f32 v32, v147, 0x39800000, v154
	v_rsq_f32_e32 v36, v32
	v_mov_b32_e32 v34, v24
	v_mov_b32_e32 v35, v28
	v_cvt_pk_bf16_f32 v32, v53, v40
	v_pk_mul_f32 v[38:39], v[34:35], v[36:37] op_sel_hi:[1,0]
	v_cvt_pk_bf16_f32 v33, v42, v37
	v_cvt_pk_bf16_f32 v34, v48, v41
	v_mad_i64_i32 v[40:41], s[0:1], v155, s53, v[112:113]
	v_mul_f32_e32 v24, 0xbfb8aa3b, v39
	v_exp_f32_e32 v24, v24
	v_lshl_add_u64 v[40:41], v[40:41], 0, v[114:115]
	v_cvt_pk_bf16_f32 v35, v46, v43
	global_store_dwordx4 v[40:41], v[32:35], off
	v_add_f32_e32 v24, 1.0, v24
	s_nop 0
	v_mov_b32_e32 v33, v20
	v_mov_b32_e32 v32, v16
	v_pk_mul_f32 v[32:33], v[32:33], v[36:37] op_sel_hi:[1,0]
	v_mul_f32_e32 v16, 0xbfb8aa3b, v33
	v_exp_f32_e32 v16, v16
	v_rcp_f32_e32 v20, v24
	s_nop 0
	v_mul_f32_e32 v20, v39, v20
	v_add_f32_e32 v16, 1.0, v16
	v_mul_f32_e32 v37, v38, v20
	v_mov_b32_e32 v28, v25
	v_pk_mul_f32 v[24:25], v[28:29], v[36:37] op_sel_hi:[1,0]
	v_mul_f32_e32 v28, 0xbfb8aa3b, v25
	v_exp_f32_e32 v28, v28
	v_rcp_f32_e32 v16, v16
	s_nop 0
	v_mul_f32_e32 v16, v33, v16
	v_add_f32_e32 v28, 1.0, v28
	v_mul_f32_e32 v32, v32, v16
	v_mov_b32_e32 v20, v17
	v_pk_mul_f32 v[16:17], v[20:21], v[36:37] op_sel_hi:[1,0]
	v_mul_f32_e32 v20, 0xbfb8aa3b, v17
	v_exp_f32_e32 v20, v20
	s_nop 0
	v_add_f32_e32 v29, 1.0, v20
	v_rcp_f32_e32 v20, v28
	s_nop 0
	v_mul_f32_e32 v20, v25, v20
	v_mul_f32_e32 v24, v24, v20
	v_mov_b32_e32 v20, v26
	v_mov_b32_e32 v21, v30
	v_pk_mul_f32 v[20:21], v[20:21], v[36:37] op_sel_hi:[1,0]
	v_mul_f32_e32 v26, 0xbfb8aa3b, v21
	v_exp_f32_e32 v26, v26
	v_rcp_f32_e32 v25, v29
	s_nop 0
	v_mul_f32_e32 v17, v17, v25
	v_add_f32_e32 v26, 1.0, v26
	v_mul_f32_e32 v25, v16, v17
	v_mov_b32_e32 v16, v18
	v_mov_b32_e32 v17, v22
	v_pk_mul_f32 v[16:17], v[16:17], v[36:37] op_sel_hi:[1,0]
	v_mul_f32_e32 v18, 0xbfb8aa3b, v17
	v_exp_f32_e32 v18, v18
	v_rcp_f32_e32 v22, v26
	s_nop 0
	v_mul_f32_e32 v21, v21, v22
	v_add_f32_e32 v18, 1.0, v18
	v_mul_f32_e32 v26, v20, v21
	v_mov_b32_e32 v30, v27
	v_pk_mul_f32 v[20:21], v[30:31], v[36:37] op_sel_hi:[1,0]
	v_mul_f32_e32 v27, 0xbfb8aa3b, v21
	v_exp_f32_e32 v27, v27
	v_rcp_f32_e32 v18, v18
	s_nop 0
	v_mul_f32_e32 v17, v17, v18
	v_add_f32_e32 v27, 1.0, v27
	v_mul_f32_e32 v30, v16, v17
	v_mov_b32_e32 v22, v19
	v_pk_mul_f32 v[16:17], v[22:23], v[36:37] op_sel_hi:[1,0]
	v_mul_f32_e32 v19, 0xbfb8aa3b, v17
	v_exp_f32_e32 v19, v19
	v_rcp_f32_e32 v18, v27
	s_nop 0
	v_mul_f32_e32 v18, v21, v18
	v_add_f32_e32 v19, 1.0, v19
	v_mul_f32_e32 v21, v20, v18
	v_rcp_f32_e32 v18, v19
	s_nop 0
	v_mul_f32_e32 v17, v17, v18
	v_mul_f32_e32 v27, v16, v17
	v_fmamk_f32 v16, v145, 0x39800000, v154
	v_rsq_f32_e32 v20, v16
	v_mov_b32_e32 v18, v8
	v_mov_b32_e32 v19, v12
	v_cvt_pk_bf16_f32 v16, v37, v24
	v_pk_mul_f32 v[22:23], v[18:19], v[20:21] op_sel_hi:[1,0]
	v_cvt_pk_bf16_f32 v17, v26, v21
	v_cvt_pk_bf16_f32 v18, v32, v25
	v_mad_i64_i32 v[24:25], s[0:1], v149, s53, v[112:113]
	v_mul_f32_e32 v8, 0xbfb8aa3b, v23
	v_exp_f32_e32 v8, v8
	v_lshl_add_u64 v[24:25], v[24:25], 0, v[114:115]
	v_cvt_pk_bf16_f32 v19, v30, v27
	global_store_dwordx4 v[24:25], v[16:19], off
	v_add_f32_e32 v8, 1.0, v8
	s_nop 0
	v_mov_b32_e32 v17, v4
	v_mov_b32_e32 v16, v0
	v_pk_mul_f32 v[16:17], v[16:17], v[20:21] op_sel_hi:[1,0]
	v_mul_f32_e32 v0, 0xbfb8aa3b, v17
	v_exp_f32_e32 v0, v0
	v_rcp_f32_e32 v4, v8
	s_nop 0
	v_mul_f32_e32 v4, v23, v4
	v_add_f32_e32 v0, 1.0, v0
	v_mul_f32_e32 v21, v22, v4
	v_mov_b32_e32 v12, v9
	v_pk_mul_f32 v[8:9], v[12:13], v[20:21] op_sel_hi:[1,0]
	v_mul_f32_e32 v12, 0xbfb8aa3b, v9
	v_exp_f32_e32 v12, v12
	v_rcp_f32_e32 v0, v0
	s_nop 0
	v_mul_f32_e32 v0, v17, v0
	v_add_f32_e32 v12, 1.0, v12
	v_mul_f32_e32 v16, v16, v0
	v_mov_b32_e32 v4, v1
	v_pk_mul_f32 v[0:1], v[4:5], v[20:21] op_sel_hi:[1,0]
	v_mul_f32_e32 v4, 0xbfb8aa3b, v1
	v_exp_f32_e32 v4, v4
	s_nop 0
	v_add_f32_e32 v13, 1.0, v4
	v_rcp_f32_e32 v4, v12
	s_nop 0
	v_mul_f32_e32 v4, v9, v4
	v_mul_f32_e32 v8, v8, v4
	v_mov_b32_e32 v4, v10
	v_mov_b32_e32 v5, v14
	v_pk_mul_f32 v[4:5], v[4:5], v[20:21] op_sel_hi:[1,0]
	v_mul_f32_e32 v10, 0xbfb8aa3b, v5
	v_exp_f32_e32 v10, v10
	v_rcp_f32_e32 v9, v13
	s_nop 0
	v_mul_f32_e32 v1, v1, v9
	v_add_f32_e32 v10, 1.0, v10
	v_mul_f32_e32 v9, v0, v1
	v_mov_b32_e32 v0, v2
	v_mov_b32_e32 v1, v6
	v_pk_mul_f32 v[0:1], v[0:1], v[20:21] op_sel_hi:[1,0]
	v_mul_f32_e32 v2, 0xbfb8aa3b, v1
	v_exp_f32_e32 v2, v2
	v_rcp_f32_e32 v6, v10
	s_nop 0
	v_mul_f32_e32 v5, v5, v6
	v_add_f32_e32 v2, 1.0, v2
	v_mul_f32_e32 v10, v4, v5
	v_mov_b32_e32 v14, v11
	v_pk_mul_f32 v[4:5], v[14:15], v[20:21] op_sel_hi:[1,0]
	v_mul_f32_e32 v11, 0xbfb8aa3b, v5
	v_exp_f32_e32 v11, v11
	v_rcp_f32_e32 v2, v2
	s_nop 0
	v_mul_f32_e32 v1, v1, v2
	v_add_f32_e32 v11, 1.0, v11
	v_mul_f32_e32 v14, v0, v1
	v_mov_b32_e32 v6, v3
	v_pk_mul_f32 v[0:1], v[6:7], v[20:21] op_sel_hi:[1,0]
	v_mul_f32_e32 v3, 0xbfb8aa3b, v1
	v_exp_f32_e32 v3, v3
	v_rcp_f32_e32 v2, v11
	s_nop 0
	v_mul_f32_e32 v2, v5, v2
	v_add_f32_e32 v3, 1.0, v3
	v_mul_f32_e32 v2, v4, v2
	v_rcp_f32_e32 v3, v3
	s_nop 0
	v_mul_f32_e32 v1, v1, v3
	v_mad_i64_i32 v[4:5], s[0:1], v121, s53, v[112:113]
	v_mul_f32_e32 v3, v0, v1
	v_lshl_add_u64 v[4:5], v[4:5], 0, v[114:115]
	s_andn2_b64 vcc, exec, s[4:5]
	s_mov_b64 s[0:1], -1
	v_cvt_pk_bf16_f32 v0, v21, v8
	v_cvt_pk_bf16_f32 v1, v10, v2
	v_cvt_pk_bf16_f32 v2, v16, v9
	v_cvt_pk_bf16_f32 v3, v14, v3
	global_store_dwordx4 v[4:5], v[0:3], off
	s_cbranch_vccnz .LBB0_2822
	s_andn2_b64 vcc, exec, s[12:13]
	s_cbranch_vccnz .LBB0_2821
	s_barrier
	s_branch .LBB0_2821

; DI float sigmoidf_(float z) { return 1.0f / (1.0f + __expf(-z)); }
; DI v4u pack8(const f4& a, const f4& b) { v4u w; w.x = cvt_pk_bf16(a[0], a[1]); w.y = cvt_pk_bf16(a[2], a[3]); w.z = cvt_pk_bf16(b[0], b[1]); w.w = cvt_pk_bf16(b[2], b[3]); return w; }
; DI void unpack8(const v4u& w, f4& a, f4& b) { a[0] = bf_lo(w.x); a[1] = bf_hi(w.x); a[2] = bf_lo(w.y); a[3] = bf_hi(w.y); b[0] = bf_lo(w.z); b[1] = bf_hi(w.z); b[2] = bf_lo(w.w); b[3] = bf_hi(w.w); }
;     DI void operator()(f4 (&acc)[2][2][4][2], const Unit& u, int wr, int wc, int fr, int fq) const {
;     ...
;         float rr[2][4];
; #pragma unroll
;         for (int ai = 0; ai < 2; ++ai)
; #pragma unroll
;             for (int m = 0; m < 4; ++m) rr[ai][m] = ss_in[row0 + ai * HALF + m * 16];
; #pragma unroll
;         for (int ai = 0; ai < 2; ++ai)
; #pragma unroll
;             for (int mp = 0; mp < 2; ++mp) {
;                 v4u pv[2][2], hv[2][2];
; #pragma unroll
;                 for (int mm = 0; mm < 2; ++mm)
; #pragma unroll
;                     for (int bj = 0; bj < 2; ++bj) { const size_t off = (size_t)(row0 + ai * HALF + (2 * mp + mm) * 16) * D + col0 + bj * HALF;
;                         pv[mm][bj] = *(const v4u*)(pp + off); hv[mm][bj] = *(const v4u*)(hb + off); }
;                 asm volatile("" ::: "memory");
; #pragma unroll
;                 for (int mm = 0; mm < 2; ++mm) { const int m = 2 * mp + mm, row = row0 + ai * HALF + m * 16; const float r = __builtin_amdgcn_rsqf(rr[ai][m] * (1.0f / D) + RMS_EPS); float s = 0.f;
; #pragma unroll
;                     for (int bj = 0; bj < 2; ++bj) { const size_t off = (size_t)row * D + col0 + bj * HALF;
;                         f4 p0, p1; unpack8(pv[mm][bj], p0, p1);
;                         f4 h0, h1; unpack8(hv[mm][bj], h0, h1);
; #pragma unroll
;                         for (int t = 0; t < 4; ++t) { h0[t] += sigmoidf_(acc[ai][bj][m][0][t] * r) * p0[t]; h1[t] += sigmoidf_(acc[ai][bj][m][1][t] * r) * p1[t]; }
;                         *(v4u*)(h3b + off) = pack8(h0, h1);
;                         s += (h0[0] * h0[0] + h0[1] * h0[1]) + (h0[2] * h0[2] + h0[3] * h0[3]) + (h1[0] * h1[0] + h1[1] * h1[1]) + (h1[2] * h1[2] + h1[3] * h1[3]); }
.LBB0_3033:
	s_lshl_b32 s1, s6, 8
	s_add_i32 s1, s1, s47
	v_mbcnt_lo_u32_b32 v134, -1, 0
	v_mbcnt_hi_u32_b32 v134, -1, v134
	s_lshl_b32 s0, s0, 8
	v_and_or_b32 v170, v134, 15, s1
	v_ashrrev_i32_e32 v128, 1, v134
	v_ashrrev_i32_e32 v171, 31, v170
	v_and_b32_e32 v130, -8, v128
	v_lshl_add_u64 v[128:129], v[170:171], 2, s[16:17]
	global_load_dword v193, v[128:129], off
	s_or_b32 s0, s0, s48
	v_add_u32_e32 v168, s0, v130
	v_ashrrev_i32_e32 v169, 31, v168
	v_lshlrev_b64 v[130:131], 12, v[170:171]
	v_lshl_add_u64 v[130:131], v[130:131], 0, v[168:169]
	v_lshlrev_b64 v[130:131], 1, v[130:131]
	v_lshl_add_u64 v[132:133], s[14:15], 0, v[130:131]
	v_lshl_add_u64 v[130:131], s[8:9], 0, v[130:131]
	global_load_dwordx4 v[194:197], v[132:133], off
	global_load_dwordx4 v[198:201], v[130:131], off
	v_or_b32_e32 v176, 16, v170
	v_or_b32_e32 v174, 32, v170
	v_or_b32_e32 v172, 48, v170
	v_ashrrev_i32_e32 v177, 31, v176
	v_ashrrev_i32_e32 v175, 31, v174
	v_ashrrev_i32_e32 v173, 31, v172
	v_cmp_gt_u32_e64 s[6:7], 16, v134
	v_lshl_add_u64 v[134:135], v[176:177], 2, s[16:17]
	v_lshl_add_u64 v[136:137], v[174:175], 2, s[16:17]
	v_lshl_add_u64 v[138:139], v[172:173], 2, s[16:17]
	global_load_dword v189, v[128:129], off offset:512
	global_load_dword v188, v[128:129], off offset:576
	global_load_dword v187, v[128:129], off offset:640
	global_load_dword v192, v[134:135], off
	global_load_dword v191, v[136:137], off
	global_load_dword v190, v[138:139], off
	global_load_dword v186, v[128:129], off offset:704
	global_load_dwordx4 v[148:151], v[132:133], off offset:256
	global_load_dwordx4 v[144:147], v[130:131], off offset:256
	v_lshlrev_b64 v[140:141], 12, v[176:177]
	v_lshl_add_u64 v[128:129], v[140:141], 0, v[168:169]
	v_lshlrev_b64 v[128:129], 1, v[128:129]
	v_lshl_add_u64 v[130:131], s[14:15], 0, v[128:129]
	v_lshl_add_u64 v[128:129], s[8:9], 0, v[128:129]
	global_load_dwordx4 v[140:143], v[130:131], off
	global_load_dwordx4 v[132:135], v[130:131], off offset:256
	global_load_dwordx4 v[136:139], v[128:129], off
	s_nop 0
	global_load_dwordx4 v[128:131], v[128:129], off offset:256
	v_lshlrev_b64 v[178:179], 13, v[170:171]
	s_waitcnt vmcnt(0)
	v_fmamk_f32 v193, v193, 0x39800000, v184
	v_rsq_f32_e32 v193, v193
	v_lshlrev_b32_e32 v204, 16, v196
	v_mul_f32_e32 v124, v124, v193
	v_mul_f32_e32 v120, v120, v193
	v_mul_f32_e32 v124, 0xbfb8aa3b, v124
	v_mul_f32_e32 v120, 0xbfb8aa3b, v120
	v_exp_f32_e32 v124, v124
	v_exp_f32_e32 v120, v120
	v_mul_f32_e32 v125, v125, v193
	v_mul_f32_e32 v125, 0xbfb8aa3b, v125
	v_add_f32_e32 v124, 1.0, v124
	v_add_f32_e32 v120, 1.0, v120
	v_exp_f32_e32 v125, v125
	s_nop 0
	v_add_f32_e32 v125, 1.0, v125
	v_rcp_f32_e32 v124, v124
	v_mul_f32_e32 v121, v121, v193
	v_lshlrev_b32_e32 v208, 16, v200
	v_rcp_f32_e32 v120, v120
	v_mul_f32_e32 v121, 0xbfb8aa3b, v121
	v_fmac_f32_e32 v208, v120, v204
	v_exp_f32_e32 v121, v121
	v_lshlrev_b32_e32 v202, 16, v194
	v_lshlrev_b32_e32 v206, 16, v198
	v_fmac_f32_e32 v206, v124, v202
	v_add_f32_e32 v121, 1.0, v121
	v_rcp_f32_e32 v120, v125
	v_mul_f32_e32 v125, v126, v193
	v_mul_f32_e32 v125, 0xbfb8aa3b, v125
	v_and_b32_e32 v194, 0xffff0000, v194
	v_and_b32_e32 v198, 0xffff0000, v198
	v_exp_f32_e32 v125, v125
	v_fmac_f32_e32 v198, v120, v194
	v_add_f32_e32 v125, 1.0, v125
	v_mul_f32_e32 v122, v122, v193
	v_mul_f32_e32 v122, 0xbfb8aa3b, v122
	v_and_b32_e32 v196, 0xffff0000, v196
	v_and_b32_e32 v200, 0xffff0000, v200
	v_rcp_f32_e32 v120, v121
	v_exp_f32_e32 v122, v122
	v_fmac_f32_e32 v200, v120, v196
	v_add_f32_e32 v122, 1.0, v122
	v_lshlrev_b32_e32 v203, 16, v195
	v_lshlrev_b32_e32 v207, 16, v199
	v_rcp_f32_e32 v120, v125
	v_mul_f32_e32 v125, v127, v193
	v_fmac_f32_e32 v207, v120, v203
	v_mul_f32_e32 v125, 0xbfb8aa3b, v125
	v_exp_f32_e32 v125, v125
	s_nop 0
	v_add_f32_e32 v124, 1.0, v125
	v_rcp_f32_e32 v120, v122
	v_mul_f32_e32 v122, v123, v193
	v_mul_f32_e32 v122, 0xbfb8aa3b, v122
	v_lshlrev_b32_e32 v205, 16, v197
	v_lshlrev_b32_e32 v209, 16, v201
	v_exp_f32_e32 v122, v122
	v_fmac_f32_e32 v209, v120, v205
	v_add_f32_e32 v122, 1.0, v122
	v_and_b32_e32 v195, 0xffff0000, v195
	v_and_b32_e32 v199, 0xffff0000, v199
	v_rcp_f32_e32 v120, v124
	s_nop 0
	v_fmac_f32_e32 v199, v120, v195
	v_mul_f32_e32 v116, v116, v193
	v_mul_f32_e32 v116, 0xbfb8aa3b, v116
	v_exp_f32_e32 v116, v116
	v_and_b32_e32 v197, 0xffff0000, v197
	v_and_b32_e32 v201, 0xffff0000, v201
	v_rcp_f32_e32 v120, v122
	v_add_f32_e32 v116, 1.0, v116
	v_fmac_f32_e32 v201, v120, v197
	v_cvt_pk_bf16_f32 v120, v206, v198
	v_mul_f32_e32 v124, v198, v198
	v_cvt_pk_bf16_f32 v121, v207, v199
	v_mul_f32_e32 v125, v199, v199
	v_fmac_f32_e32 v124, v206, v206
	v_fmac_f32_e32 v125, v207, v207
	v_add_f32_e32 v124, v124, v125
	v_mul_f32_e32 v125, v200, v200
	v_mul_f32_e32 v112, v112, v193
	v_fmac_f32_e32 v125, v208, v208
	v_mul_f32_e32 v112, 0xbfb8aa3b, v112
	v_cvt_pk_bf16_f32 v122, v208, v200
	v_cvt_pk_bf16_f32 v123, v209, v201
	v_add_f32_e32 v124, v125, v124
	v_mul_f32_e32 v125, v201, v201
	v_exp_f32_e32 v112, v112
	s_nop 0
	v_add_f32_e32 v112, 1.0, v112
	v_mul_f32_e32 v117, v117, v193
	v_fmac_f32_e32 v125, v209, v209
	v_mul_f32_e32 v117, 0xbfb8aa3b, v117
	v_add_f32_e32 v124, v125, v124
	v_lshlrev_b32_e32 v125, 16, v148
	v_lshlrev_b32_e32 v195, 16, v144
	v_rcp_f32_e32 v116, v116
	v_exp_f32_e32 v117, v117
	v_fmac_f32_e32 v195, v116, v125
	v_add_f32_e32 v117, 1.0, v117
	v_mul_f32_e32 v113, v113, v193
	v_and_b32_e32 v126, 0xffff0000, v148
	v_lshlrev_b32_e32 v127, 16, v149
	v_and_b32_e32 v148, 0xffff0000, v149
	v_lshlrev_b32_e32 v149, 16, v150
	v_lshlrev_b32_e32 v197, 16, v146
	v_rcp_f32_e32 v112, v112
	v_mul_f32_e32 v113, 0xbfb8aa3b, v113
	v_fmac_f32_e32 v197, v112, v149
; DI float sigmoidf_(float z) { return 1.0f / (1.0f + __expf(-z)); }
; DI v4u pack8(const f4& a, const f4& b) { v4u w; w.x = cvt_pk_bf16(a[0], a[1]); w.y = cvt_pk_bf16(a[2], a[3]); w.z = cvt_pk_bf16(b[0], b[1]); w.w = cvt_pk_bf16(b[2], b[3]); return w; }
; DI void unpack8(const v4u& w, f4& a, f4& b) { a[0] = bf_lo(w.x); a[1] = bf_hi(w.x); a[2] = bf_lo(w.y); a[3] = bf_hi(w.y); b[0] = bf_lo(w.z); b[1] = bf_hi(w.z); b[2] = bf_lo(w.w); b[3] = bf_hi(w.w); }
;     DI void operator()(f4 (&acc)[2][2][4][2], const Unit& u, int wr, int wc, int fr, int fq) const {
;     ...
;                 for (int mm = 0; mm < 2; ++mm) { const int m = 2 * mp + mm, row = row0 + ai * HALF + m * 16; const float r = __builtin_amdgcn_rsqf(rr[ai][m] * (1.0f / D) + RMS_EPS); float s = 0.f;
; #pragma unroll
;                     for (int bj = 0; bj < 2; ++bj) { const size_t off = (size_t)row * D + col0 + bj * HALF;
;                         f4 p0, p1; unpack8(pv[mm][bj], p0, p1);
;                         f4 h0, h1; unpack8(hv[mm][bj], h0, h1);
; #pragma unroll
;                         for (int t = 0; t < 4; ++t) { h0[t] += sigmoidf_(acc[ai][bj][m][0][t] * r) * p0[t]; h1[t] += sigmoidf_(acc[ai][bj][m][1][t] * r) * p1[t]; }
;                         *(v4u*)(h3b + off) = pack8(h0, h1);
;                         s += (h0[0] * h0[0] + h0[1] * h0[1]) + (h0[2] * h0[2] + h0[3] * h0[3]) + (h1[0] * h1[0] + h1[1] * h1[1]) + (h1[2] * h1[2] + h1[3] * h1[3]); }
;                     s += __shfl_xor(s, 16); s += __shfl_xor(s, 32);
;                     if (fq == 0) atomicAdd(ss_out + row, s); }
	v_exp_f32_e32 v113, v113
	s_nop 0
	v_add_f32_e32 v113, 1.0, v113
	v_rcp_f32_e32 v112, v117
	v_mul_f32_e32 v117, v118, v193
	v_mul_f32_e32 v117, 0xbfb8aa3b, v117
	v_and_b32_e32 v144, 0xffff0000, v144
	v_exp_f32_e32 v117, v117
	v_fmac_f32_e32 v144, v112, v126
	v_add_f32_e32 v117, 1.0, v117
	v_mul_f32_e32 v114, v114, v193
	v_mul_f32_e32 v114, 0xbfb8aa3b, v114
	v_and_b32_e32 v150, 0xffff0000, v150
	v_and_b32_e32 v146, 0xffff0000, v146
	v_rcp_f32_e32 v112, v113
	v_exp_f32_e32 v114, v114
	v_fmac_f32_e32 v146, v112, v150
	v_add_f32_e32 v114, 1.0, v114
	v_lshlrev_b32_e32 v196, 16, v145
	v_rcp_f32_e32 v112, v117
	v_mul_f32_e32 v117, v119, v193
	v_fmac_f32_e32 v196, v112, v127
	v_mul_f32_e32 v117, 0xbfb8aa3b, v117
	v_exp_f32_e32 v117, v117
	s_nop 0
	v_add_f32_e32 v116, 1.0, v117
	v_rcp_f32_e32 v112, v114
	v_mul_f32_e32 v114, v115, v193
	v_mul_f32_e32 v114, 0xbfb8aa3b, v114
	v_lshlrev_b32_e32 v194, 16, v151
	v_lshlrev_b32_e32 v200, 16, v147
	v_exp_f32_e32 v114, v114
	v_fmac_f32_e32 v200, v112, v194
	v_add_f32_e32 v114, 1.0, v114
	v_and_b32_e32 v145, 0xffff0000, v145
	v_rcp_f32_e32 v112, v116
	s_nop 0
	v_fmac_f32_e32 v145, v112, v148
	v_and_b32_e32 v151, 0xffff0000, v151
	v_and_b32_e32 v147, 0xffff0000, v147
	v_rcp_f32_e32 v112, v114
	s_nop 0
	v_fmac_f32_e32 v147, v112, v151
	v_mul_f32_e32 v112, v144, v144
	v_mul_f32_e32 v113, v145, v145
	v_fmac_f32_e32 v112, v195, v195
	v_fmac_f32_e32 v113, v196, v196
	v_add_f32_e32 v112, v112, v113
	v_mul_f32_e32 v113, v146, v146
	v_fmac_f32_e32 v113, v197, v197
	v_add_f32_e32 v112, v113, v112
	v_mul_f32_e32 v113, v147, v147
	v_fmac_f32_e32 v113, v200, v200
	v_add_f32_e32 v112, v113, v112
	v_and_b32_e32 v113, 64, v185
	v_add_f32_e32 v115, v124, v112
	v_xor_b32_e32 v112, 16, v185
	v_add_u32_e32 v116, 64, v113
	v_cmp_lt_i32_e32 vcc, v112, v116
	s_nop 1
	v_cndmask_b32_e32 v112, v185, v112, vcc
	v_lshlrev_b32_e32 v124, 2, v112
	ds_bpermute_b32 v117, v124, v115
	v_lshl_add_u64 v[112:113], s[12:13], 0, v[178:179]
	v_lshl_add_u64 v[118:119], v[168:169], 1, v[112:113]
	v_xor_b32_e32 v113, 32, v185
	v_cmp_lt_i32_e32 vcc, v113, v116
	global_store_dwordx4 v[118:119], v[120:123], off
	s_waitcnt lgkmcnt(0)
	v_add_f32_e32 v112, v115, v117
	v_cndmask_b32_e32 v113, v185, v113, vcc
	v_lshlrev_b32_e32 v122, 2, v113
	ds_bpermute_b32 v113, v122, v112
	v_cvt_pk_bf16_f32 v114, v195, v144
	v_cvt_pk_bf16_f32 v115, v196, v145
	v_cvt_pk_bf16_f32 v116, v197, v146
	v_cvt_pk_bf16_f32 v117, v200, v147
	global_store_dwordx4 v[118:119], v[114:117], off offset:256
	s_and_saveexec_b64 s[0:1], s[6:7]
	s_cbranch_execz .LBB0_3035
	v_lshl_add_u64 v[114:115], v[170:171], 2, s[18:19]
	s_waitcnt lgkmcnt(0)
	v_add_f32_e32 v112, v112, v113
	global_atomic_add_f32 v[114:115], v112, off
.LBB0_3035:
	s_or_b64 exec, exec, s[0:1]
	v_fmamk_f32 v112, v192, 0x39800000, v184
	v_rsq_f32_e32 v114, v112
	v_lshlrev_b32_e32 v115, 16, v140
	v_and_b32_e32 v116, 0xffff0000, v140
	v_lshlrev_b32_e32 v117, 16, v141
	v_mul_f32_e32 v108, v108, v114
	v_mul_f32_e32 v108, 0xbfb8aa3b, v108
	v_exp_f32_e32 v108, v108
	v_and_b32_e32 v118, 0xffff0000, v141
	v_mul_f32_e32 v104, v104, v114
	v_mul_f32_e32 v104, 0xbfb8aa3b, v104
	v_add_f32_e32 v108, 1.0, v108
	v_lshlrev_b32_e32 v121, 16, v143
	v_and_b32_e32 v123, 0xffff0000, v143
	v_exp_f32_e32 v104, v104
	s_nop 0
	v_add_f32_e32 v104, 1.0, v104
	v_mul_f32_e32 v109, v109, v114
	v_mul_f32_e32 v109, 0xbfb8aa3b, v109
	v_lshlrev_b32_e32 v125, 16, v136
	v_rcp_f32_e32 v108, v108
	v_exp_f32_e32 v109, v109
	v_fmac_f32_e32 v125, v108, v115
	v_add_f32_e32 v109, 1.0, v109
	v_mul_f32_e32 v105, v105, v114
	v_lshlrev_b32_e32 v119, 16, v142
	v_and_b32_e32 v126, 0xffff0000, v136
	v_lshlrev_b32_e32 v127, 16, v137
	v_and_b32_e32 v136, 0xffff0000, v137
	v_lshlrev_b32_e32 v137, 16, v138
	v_rcp_f32_e32 v104, v104
	v_mul_f32_e32 v105, 0xbfb8aa3b, v105
	v_fmac_f32_e32 v137, v104, v119
	v_exp_f32_e32 v105, v105
	s_nop 0
	v_add_f32_e32 v105, 1.0, v105
	v_rcp_f32_e32 v104, v109
	v_mul_f32_e32 v109, v110, v114
	v_mul_f32_e32 v109, 0xbfb8aa3b, v109
	v_exp_f32_e32 v109, v109
	v_fmac_f32_e32 v126, v104, v116
	v_add_f32_e32 v109, 1.0, v109
	v_mul_f32_e32 v106, v106, v114
	v_mul_f32_e32 v106, 0xbfb8aa3b, v106
	v_and_b32_e32 v120, 0xffff0000, v142
	v_and_b32_e32 v138, 0xffff0000, v138
	v_rcp_f32_e32 v104, v105
	v_exp_f32_e32 v106, v106
	v_fmac_f32_e32 v138, v104, v120
	v_add_f32_e32 v106, 1.0, v106
	v_rcp_f32_e32 v104, v109
	v_mul_f32_e32 v109, v111, v114
	v_fmac_f32_e32 v127, v104, v117
	v_mul_f32_e32 v109, 0xbfb8aa3b, v109
	v_exp_f32_e32 v109, v109
	s_nop 0
	v_add_f32_e32 v108, 1.0, v109
	v_rcp_f32_e32 v104, v106
	v_mul_f32_e32 v106, v107, v114
	v_mul_f32_e32 v106, 0xbfb8aa3b, v106
	v_lshlrev_b32_e32 v142, 16, v139
	v_exp_f32_e32 v106, v106
	v_fmac_f32_e32 v142, v104, v121
	v_add_f32_e32 v106, 1.0, v106
	v_rcp_f32_e32 v104, v108
	s_nop 0
	v_fmac_f32_e32 v136, v104, v118
	v_mul_f32_e32 v100, v100, v114
	v_mul_f32_e32 v100, 0xbfb8aa3b, v100
	v_exp_f32_e32 v100, v100
	v_and_b32_e32 v139, 0xffff0000, v139
	v_rcp_f32_e32 v104, v106
	v_mul_f32_e32 v108, v126, v126
	v_mul_f32_e32 v109, v136, v136
	v_add_f32_e32 v100, 1.0, v100
	v_fmac_f32_e32 v139, v104, v123
	v_cvt_pk_bf16_f32 v104, v125, v126
	v_cvt_pk_bf16_f32 v105, v127, v136
	v_fmac_f32_e32 v108, v125, v125
	v_fmac_f32_e32 v109, v127, v127
	v_add_f32_e32 v108, v108, v109
	v_mul_f32_e32 v109, v138, v138
	v_lshlrev_b32_e32 v120, 16, v128
	v_and_b32_e32 v121, 0xffff0000, v128
	v_fmac_f32_e32 v109, v137, v137
	v_add_f32_e32 v108, v109, v108
	v_mul_f32_e32 v109, v139, v139
	v_mul_f32_e32 v96, v96, v114
	v_fmac_f32_e32 v109, v142, v142
	v_mul_f32_e32 v96, 0xbfb8aa3b, v96
	v_add_f32_e32 v108, v109, v108
	v_lshlrev_b32_e32 v109, 16, v132
; DI float sigmoidf_(float z) { return 1.0f / (1.0f + __expf(-z)); }
; DI v4u pack8(const f4& a, const f4& b) { v4u w; w.x = cvt_pk_bf16(a[0], a[1]); w.y = cvt_pk_bf16(a[2], a[3]); w.z = cvt_pk_bf16(b[0], b[1]); w.w = cvt_pk_bf16(b[2], b[3]); return w; }
; DI void unpack8(const v4u& w, f4& a, f4& b) { a[0] = bf_lo(w.x); a[1] = bf_hi(w.x); a[2] = bf_lo(w.y); a[3] = bf_hi(w.y); b[0] = bf_lo(w.z); b[1] = bf_hi(w.z); b[2] = bf_lo(w.w); b[3] = bf_hi(w.w); }
;     DI void operator()(f4 (&acc)[2][2][4][2], const Unit& u, int wr, int wc, int fr, int fq) const {
;     ...
;             for (int mp = 0; mp < 2; ++mp) {
;                 v4u pv[2][2], hv[2][2];
; #pragma unroll
;                 for (int mm = 0; mm < 2; ++mm)
; #pragma unroll
;                     for (int bj = 0; bj < 2; ++bj) { const size_t off = (size_t)(row0 + ai * HALF + (2 * mp + mm) * 16) * D + col0 + bj * HALF;
;                         pv[mm][bj] = *(const v4u*)(pp + off); hv[mm][bj] = *(const v4u*)(hb + off); }
;                 asm volatile("" ::: "memory");
; #pragma unroll
;                 for (int mm = 0; mm < 2; ++mm) { const int m = 2 * mp + mm, row = row0 + ai * HALF + m * 16; const float r = __builtin_amdgcn_rsqf(rr[ai][m] * (1.0f / D) + RMS_EPS); float s = 0.f;
; #pragma unroll
;                     for (int bj = 0; bj < 2; ++bj) { const size_t off = (size_t)row * D + col0 + bj * HALF;
;                         f4 p0, p1; unpack8(pv[mm][bj], p0, p1);
;                         f4 h0, h1; unpack8(hv[mm][bj], h0, h1);
; #pragma unroll
;                         for (int t = 0; t < 4; ++t) { h0[t] += sigmoidf_(acc[ai][bj][m][0][t] * r) * p0[t]; h1[t] += sigmoidf_(acc[ai][bj][m][1][t] * r) * p1[t]; }
;                         *(v4u*)(h3b + off) = pack8(h0, h1);
;                         s += (h0[0] * h0[0] + h0[1] * h0[1]) + (h0[2] * h0[2] + h0[3] * h0[3]) + (h1[0] * h1[0] + h1[1] * h1[1]) + (h1[2] * h1[2] + h1[3] * h1[3]); }
;                     s += __shfl_xor(s, 16); s += __shfl_xor(s, 32);
;                     if (fq == 0) atomicAdd(ss_out + row, s); }
	v_and_b32_e32 v110, 0xffff0000, v132
	v_exp_f32_e32 v96, v96
	v_lshlrev_b32_e32 v111, 16, v133
	v_and_b32_e32 v115, 0xffff0000, v133
	v_lshlrev_b32_e32 v116, 16, v134
	v_and_b32_e32 v117, 0xffff0000, v134
	v_add_f32_e32 v96, 1.0, v96
	v_mul_f32_e32 v101, v101, v114
	v_mul_f32_e32 v101, 0xbfb8aa3b, v101
	v_rcp_f32_e32 v100, v100
	v_exp_f32_e32 v101, v101
	v_fmac_f32_e32 v120, v100, v109
	v_add_f32_e32 v101, 1.0, v101
	v_mul_f32_e32 v97, v97, v114
	v_lshlrev_b32_e32 v126, 16, v130
	v_rcp_f32_e32 v96, v96
	v_mul_f32_e32 v97, 0xbfb8aa3b, v97
	v_fmac_f32_e32 v126, v96, v116
	v_exp_f32_e32 v97, v97
	s_nop 0
	v_add_f32_e32 v97, 1.0, v97
	v_rcp_f32_e32 v96, v101
	v_mul_f32_e32 v101, v102, v114
	v_mul_f32_e32 v101, 0xbfb8aa3b, v101
	v_exp_f32_e32 v101, v101
	v_fmac_f32_e32 v121, v96, v110
	v_add_f32_e32 v101, 1.0, v101
	v_mul_f32_e32 v98, v98, v114
	v_mul_f32_e32 v98, 0xbfb8aa3b, v98
	v_lshlrev_b32_e32 v123, 16, v129
	v_and_b32_e32 v125, 0xffff0000, v129
	v_and_b32_e32 v129, 0xffff0000, v130
	v_rcp_f32_e32 v96, v97
	v_exp_f32_e32 v98, v98
	v_fmac_f32_e32 v129, v96, v117
	v_add_f32_e32 v98, 1.0, v98
	v_rcp_f32_e32 v96, v101
	v_mul_f32_e32 v101, v103, v114
	v_fmac_f32_e32 v123, v96, v111
	v_mul_f32_e32 v101, 0xbfb8aa3b, v101
	v_exp_f32_e32 v101, v101
	s_nop 0
	v_add_f32_e32 v100, 1.0, v101
	v_rcp_f32_e32 v96, v98
	v_mul_f32_e32 v98, v99, v114
	v_mul_f32_e32 v98, 0xbfb8aa3b, v98
	v_lshlrev_b32_e32 v118, 16, v135
	v_lshlrev_b32_e32 v130, 16, v131
	v_exp_f32_e32 v98, v98
	v_fmac_f32_e32 v130, v96, v118
	v_add_f32_e32 v98, 1.0, v98
	v_rcp_f32_e32 v96, v100
	s_nop 0
	v_fmac_f32_e32 v125, v96, v115
	v_and_b32_e32 v119, 0xffff0000, v135
	v_and_b32_e32 v131, 0xffff0000, v131
	v_rcp_f32_e32 v96, v98
	s_nop 0
	v_fmac_f32_e32 v131, v96, v119
	v_mul_f32_e32 v96, v121, v121
	v_mul_f32_e32 v97, v125, v125
	v_fmac_f32_e32 v96, v120, v120
	v_fmac_f32_e32 v97, v123, v123
	v_add_f32_e32 v96, v96, v97
	v_mul_f32_e32 v97, v129, v129
	v_fmac_f32_e32 v97, v126, v126
	v_add_f32_e32 v96, v97, v96
	v_mul_f32_e32 v97, v131, v131
	v_fmac_f32_e32 v97, v130, v130
	v_add_f32_e32 v96, v97, v96
	v_add_f32_e32 v99, v108, v96
	ds_bpermute_b32 v100, v124, v99
	s_waitcnt lgkmcnt(1)
	v_lshlrev_b64 v[112:113], 13, v[176:177]
	v_lshl_add_u64 v[96:97], s[12:13], 0, v[112:113]
	v_lshl_add_u64 v[102:103], v[168:169], 1, v[96:97]
	v_cvt_pk_bf16_f32 v106, v137, v138
	s_waitcnt lgkmcnt(0)
	v_add_f32_e32 v96, v99, v100
	ds_bpermute_b32 v97, v122, v96
	v_cvt_pk_bf16_f32 v107, v142, v139
	global_store_dwordx4 v[102:103], v[104:107], off
	v_cvt_pk_bf16_f32 v98, v120, v121
	v_cvt_pk_bf16_f32 v99, v123, v125
	v_cvt_pk_bf16_f32 v100, v126, v129
	v_cvt_pk_bf16_f32 v101, v130, v131
	global_store_dwordx4 v[102:103], v[98:101], off offset:256
	s_and_saveexec_b64 s[0:1], s[6:7]
	s_cbranch_execz .LBB0_3037
	v_lshl_add_u64 v[98:99], v[176:177], 2, s[18:19]
	s_waitcnt lgkmcnt(0)
	v_add_f32_e32 v96, v96, v97
	global_atomic_add_f32 v[98:99], v96, off
.LBB0_3037:
	s_or_b64 exec, exec, s[0:1]
	s_waitcnt lgkmcnt(0)
	v_lshlrev_b64 v[96:97], 12, v[174:175]
	v_lshl_add_u64 v[96:97], v[96:97], 0, v[168:169]
	v_lshlrev_b64 v[96:97], 1, v[96:97]
	v_lshl_add_u64 v[98:99], s[14:15], 0, v[96:97]
	v_lshl_add_u64 v[96:97], s[8:9], 0, v[96:97]
	global_load_dwordx4 v[126:129], v[98:99], off
	global_load_dwordx4 v[130:133], v[96:97], off
	v_fmamk_f32 v102, v191, 0x39800000, v184
	v_rsq_f32_e32 v123, v102
	v_lshlrev_b64 v[100:101], 12, v[172:173]
	v_lshl_add_u64 v[100:101], v[100:101], 0, v[168:169]
	v_lshlrev_b64 v[100:101], 1, v[100:101]
	v_mul_f32_e32 v92, v92, v123
	v_mul_f32_e32 v88, v88, v123
	v_mul_f32_e32 v92, 0xbfb8aa3b, v92
	v_mul_f32_e32 v93, v93, v123
	v_mul_f32_e32 v88, 0xbfb8aa3b, v88
	v_exp_f32_e32 v92, v92
	v_mul_f32_e32 v93, 0xbfb8aa3b, v93
	v_exp_f32_e32 v88, v88
	v_exp_f32_e32 v93, v93
	v_add_f32_e32 v92, 1.0, v92
	v_lshl_add_u64 v[102:103], s[14:15], 0, v[100:101]
	v_lshl_add_u64 v[134:135], s[8:9], 0, v[100:101]
	v_add_f32_e32 v88, 1.0, v88
	global_load_dwordx4 v[116:119], v[98:99], off offset:256
	global_load_dwordx4 v[112:115], v[96:97], off offset:256
	global_load_dwordx4 v[108:111], v[102:103], off
	s_nop 0
	global_load_dwordx4 v[100:103], v[102:103], off offset:256
	s_nop 0
	global_load_dwordx4 v[104:107], v[134:135], off
	global_load_dwordx4 v[96:99], v[134:135], off offset:256
	v_add_f32_e32 v93, 1.0, v93
	v_mul_f32_e32 v89, v89, v123
	v_rcp_f32_e32 v92, v92
	v_mul_f32_e32 v89, 0xbfb8aa3b, v89
	v_rcp_f32_e32 v88, v88
	v_exp_f32_e32 v89, v89
	v_mul_f32_e32 v90, v90, v123
	v_mul_f32_e32 v90, 0xbfb8aa3b, v90
	v_exp_f32_e32 v90, v90
	v_add_f32_e32 v89, 1.0, v89
	v_mul_f32_e32 v84, v84, v123
	v_mul_f32_e32 v84, 0xbfb8aa3b, v84
	v_add_f32_e32 v90, 1.0, v90
	v_exp_f32_e32 v84, v84
	v_mul_f32_e32 v80, v80, v123
	v_mul_f32_e32 v80, 0xbfb8aa3b, v80
	v_add_f32_e32 v84, 1.0, v84
	v_exp_f32_e32 v80, v80
	v_mul_f32_e32 v85, v85, v123
	v_mul_f32_e32 v85, 0xbfb8aa3b, v85
	v_exp_f32_e32 v85, v85
	v_add_f32_e32 v80, 1.0, v80
	v_mul_f32_e32 v81, v81, v123
	v_mul_f32_e32 v81, 0xbfb8aa3b, v81
	v_add_f32_e32 v85, 1.0, v85
	v_exp_f32_e32 v81, v81
	v_mul_f32_e32 v82, v82, v123
	v_mul_f32_e32 v82, 0xbfb8aa3b, v82
	s_waitcnt vmcnt(7)
	v_lshlrev_b32_e32 v135, 16, v128
	s_waitcnt vmcnt(6)
; DI float sigmoidf_(float z) { return 1.0f / (1.0f + __expf(-z)); }
; DI v4u pack8(const f4& a, const f4& b) { v4u w; w.x = cvt_pk_bf16(a[0], a[1]); w.y = cvt_pk_bf16(a[2], a[3]); w.z = cvt_pk_bf16(b[0], b[1]); w.w = cvt_pk_bf16(b[2], b[3]); return w; }
; DI void unpack8(const v4u& w, f4& a, f4& b) { a[0] = bf_lo(w.x); a[1] = bf_hi(w.x); a[2] = bf_lo(w.y); a[3] = bf_hi(w.y); b[0] = bf_lo(w.z); b[1] = bf_hi(w.z); b[2] = bf_lo(w.w); b[3] = bf_hi(w.w); }
;     DI void operator()(f4 (&acc)[2][2][4][2], const Unit& u, int wr, int wc, int fr, int fq) const {
;     ...
;                 for (int mm = 0; mm < 2; ++mm) { const int m = 2 * mp + mm, row = row0 + ai * HALF + m * 16; const float r = __builtin_amdgcn_rsqf(rr[ai][m] * (1.0f / D) + RMS_EPS); float s = 0.f;
; #pragma unroll
;                     for (int bj = 0; bj < 2; ++bj) { const size_t off = (size_t)row * D + col0 + bj * HALF;
;                         f4 p0, p1; unpack8(pv[mm][bj], p0, p1);
;                         f4 h0, h1; unpack8(hv[mm][bj], h0, h1);
; #pragma unroll
;                         for (int t = 0; t < 4; ++t) { h0[t] += sigmoidf_(acc[ai][bj][m][0][t] * r) * p0[t]; h1[t] += sigmoidf_(acc[ai][bj][m][1][t] * r) * p1[t]; }
;                         *(v4u*)(h3b + off) = pack8(h0, h1);
;                         s += (h0[0] * h0[0] + h0[1] * h0[1]) + (h0[2] * h0[2] + h0[3] * h0[3]) + (h1[0] * h1[0] + h1[1] * h1[1]) + (h1[2] * h1[2] + h1[3] * h1[3]); }
;                     s += __shfl_xor(s, 16); s += __shfl_xor(s, 32);
;                     if (fq == 0) atomicAdd(ss_out + row, s); }
	v_lshlrev_b32_e32 v141, 16, v132
	v_lshlrev_b32_e32 v125, 16, v126
	v_lshlrev_b32_e32 v138, 16, v130
	v_fmac_f32_e32 v141, v88, v135
	v_fmac_f32_e32 v138, v92, v125
	v_rcp_f32_e32 v88, v93
	v_mul_f32_e32 v93, v94, v123
	v_mul_f32_e32 v93, 0xbfb8aa3b, v93
	v_and_b32_e32 v126, 0xffff0000, v126
	v_and_b32_e32 v130, 0xffff0000, v130
	v_exp_f32_e32 v93, v93
	v_fmac_f32_e32 v130, v88, v126
	v_add_f32_e32 v93, 1.0, v93
	v_and_b32_e32 v128, 0xffff0000, v128
	v_and_b32_e32 v132, 0xffff0000, v132
	v_rcp_f32_e32 v88, v89
	s_nop 0
	v_fmac_f32_e32 v132, v88, v128
	v_lshlrev_b32_e32 v134, 16, v127
	v_lshlrev_b32_e32 v140, 16, v131
	v_rcp_f32_e32 v88, v93
	v_mul_f32_e32 v93, v95, v123
	v_fmac_f32_e32 v140, v88, v134
	v_mul_f32_e32 v93, 0xbfb8aa3b, v93
	v_exp_f32_e32 v93, v93
	s_nop 0
	v_add_f32_e32 v92, 1.0, v93
	v_rcp_f32_e32 v88, v90
	v_mul_f32_e32 v90, v91, v123
	v_mul_f32_e32 v90, 0xbfb8aa3b, v90
	v_lshlrev_b32_e32 v137, 16, v129
	v_lshlrev_b32_e32 v142, 16, v133
	v_exp_f32_e32 v90, v90
	v_fmac_f32_e32 v142, v88, v137
	v_add_f32_e32 v90, 1.0, v90
	v_and_b32_e32 v127, 0xffff0000, v127
	v_and_b32_e32 v131, 0xffff0000, v131
	v_rcp_f32_e32 v88, v92
	s_nop 0
	v_fmac_f32_e32 v131, v88, v127
	v_and_b32_e32 v129, 0xffff0000, v129
	v_and_b32_e32 v133, 0xffff0000, v133
	v_rcp_f32_e32 v88, v90
	s_nop 0
	v_fmac_f32_e32 v133, v88, v129
	v_cvt_pk_bf16_f32 v88, v138, v130
	v_mul_f32_e32 v92, v130, v130
	v_mul_f32_e32 v93, v131, v131
	v_fmac_f32_e32 v92, v138, v138
	v_fmac_f32_e32 v93, v140, v140
	v_cvt_pk_bf16_f32 v89, v140, v131
	v_cvt_pk_bf16_f32 v90, v141, v132
	v_add_f32_e32 v92, v92, v93
	v_mul_f32_e32 v93, v132, v132
	v_fmac_f32_e32 v93, v141, v141
	v_cvt_pk_bf16_f32 v91, v142, v133
	v_add_f32_e32 v92, v93, v92
	v_mul_f32_e32 v93, v133, v133
	v_fmac_f32_e32 v93, v142, v142
	v_add_f32_e32 v92, v93, v92
	s_waitcnt vmcnt(5)
	v_lshlrev_b32_e32 v93, 16, v116
	s_waitcnt vmcnt(4)
	v_lshlrev_b32_e32 v126, 16, v112
	v_rcp_f32_e32 v84, v84
	s_nop 0
	v_fmac_f32_e32 v126, v84, v93
	v_and_b32_e32 v94, 0xffff0000, v116
	v_lshlrev_b32_e32 v95, 16, v117
	v_and_b32_e32 v116, 0xffff0000, v117
	v_lshlrev_b32_e32 v117, 16, v118
	v_lshlrev_b32_e32 v128, 16, v114
	v_rcp_f32_e32 v80, v80
	s_nop 0
	v_fmac_f32_e32 v128, v80, v117
	v_add_f32_e32 v81, 1.0, v81
	v_rcp_f32_e32 v80, v85
	v_mul_f32_e32 v85, v86, v123
	v_mul_f32_e32 v85, 0xbfb8aa3b, v85
	v_and_b32_e32 v112, 0xffff0000, v112
	v_exp_f32_e32 v85, v85
	v_fmac_f32_e32 v112, v80, v94
	v_add_f32_e32 v85, 1.0, v85
	v_and_b32_e32 v118, 0xffff0000, v118
	v_and_b32_e32 v114, 0xffff0000, v114
	v_rcp_f32_e32 v80, v81
	v_exp_f32_e32 v82, v82
	v_fmac_f32_e32 v114, v80, v118
	v_add_f32_e32 v82, 1.0, v82
	v_lshlrev_b32_e32 v127, 16, v113
	v_rcp_f32_e32 v80, v85
	v_mul_f32_e32 v85, v87, v123
	v_fmac_f32_e32 v127, v80, v95
	v_mul_f32_e32 v85, 0xbfb8aa3b, v85
	v_exp_f32_e32 v85, v85
	s_nop 0
	v_add_f32_e32 v84, 1.0, v85
	v_rcp_f32_e32 v80, v82
	v_mul_f32_e32 v82, v83, v123
	v_mul_f32_e32 v82, 0xbfb8aa3b, v82
	v_lshlrev_b32_e32 v125, 16, v119
	v_lshlrev_b32_e32 v131, 16, v115
	v_exp_f32_e32 v82, v82
	v_fmac_f32_e32 v131, v80, v125
	v_add_f32_e32 v82, 1.0, v82
	v_and_b32_e32 v113, 0xffff0000, v113
	v_rcp_f32_e32 v80, v84
	s_nop 0
	v_fmac_f32_e32 v113, v80, v116
	v_and_b32_e32 v119, 0xffff0000, v119
	v_and_b32_e32 v115, 0xffff0000, v115
	v_rcp_f32_e32 v80, v82
	s_nop 0
	v_fmac_f32_e32 v115, v80, v119
	v_mul_f32_e32 v80, v112, v112
	v_mul_f32_e32 v81, v113, v113
	v_fmac_f32_e32 v80, v126, v126
	v_fmac_f32_e32 v81, v127, v127
	v_add_f32_e32 v80, v80, v81
	v_mul_f32_e32 v81, v114, v114
	v_fmac_f32_e32 v81, v128, v128
	v_add_f32_e32 v80, v81, v80
	v_mul_f32_e32 v81, v115, v115
	v_fmac_f32_e32 v81, v131, v131
	v_add_f32_e32 v80, v81, v80
	v_add_f32_e32 v83, v92, v80
	ds_bpermute_b32 v84, v124, v83
	v_lshlrev_b64 v[120:121], 13, v[174:175]
	v_lshl_add_u64 v[80:81], s[12:13], 0, v[120:121]
	v_lshl_add_u64 v[86:87], v[168:169], 1, v[80:81]
	global_store_dwordx4 v[86:87], v[88:91], off
	s_waitcnt lgkmcnt(0)
	v_add_f32_e32 v80, v83, v84
	ds_bpermute_b32 v81, v122, v80
	v_cvt_pk_bf16_f32 v82, v126, v112
	v_cvt_pk_bf16_f32 v83, v127, v113
	v_cvt_pk_bf16_f32 v84, v128, v114
	v_cvt_pk_bf16_f32 v85, v131, v115
	global_store_dwordx4 v[86:87], v[82:85], off offset:256
	s_and_saveexec_b64 s[0:1], s[6:7]
	s_cbranch_execz .LBB0_3039
	v_lshl_add_u64 v[82:83], v[174:175], 2, s[18:19]
	s_waitcnt lgkmcnt(0)
	v_add_f32_e32 v80, v80, v81
	global_atomic_add_f32 v[82:83], v80, off
; DI float sigmoidf_(float z) { return 1.0f / (1.0f + __expf(-z)); }
; DI v4u pack8(const f4& a, const f4& b) { v4u w; w.x = cvt_pk_bf16(a[0], a[1]); w.y = cvt_pk_bf16(a[2], a[3]); w.z = cvt_pk_bf16(b[0], b[1]); w.w = cvt_pk_bf16(b[2], b[3]); return w; }
; DI void unpack8(const v4u& w, f4& a, f4& b) { a[0] = bf_lo(w.x); a[1] = bf_hi(w.x); a[2] = bf_lo(w.y); a[3] = bf_hi(w.y); b[0] = bf_lo(w.z); b[1] = bf_hi(w.z); b[2] = bf_lo(w.w); b[3] = bf_hi(w.w); }
;     DI void operator()(f4 (&acc)[2][2][4][2], const Unit& u, int wr, int wc, int fr, int fq) const {
;     ...
;                 for (int mm = 0; mm < 2; ++mm) { const int m = 2 * mp + mm, row = row0 + ai * HALF + m * 16; const float r = __builtin_amdgcn_rsqf(rr[ai][m] * (1.0f / D) + RMS_EPS); float s = 0.f;
; #pragma unroll
;                     for (int bj = 0; bj < 2; ++bj) { const size_t off = (size_t)row * D + col0 + bj * HALF;
;                         f4 p0, p1; unpack8(pv[mm][bj], p0, p1);
;                         f4 h0, h1; unpack8(hv[mm][bj], h0, h1);
; #pragma unroll
;                         for (int t = 0; t < 4; ++t) { h0[t] += sigmoidf_(acc[ai][bj][m][0][t] * r) * p0[t]; h1[t] += sigmoidf_(acc[ai][bj][m][1][t] * r) * p1[t]; }
;                         *(v4u*)(h3b + off) = pack8(h0, h1);
;                         s += (h0[0] * h0[0] + h0[1] * h0[1]) + (h0[2] * h0[2] + h0[3] * h0[3]) + (h1[0] * h1[0] + h1[1] * h1[1]) + (h1[2] * h1[2] + h1[3] * h1[3]); }
;                     s += __shfl_xor(s, 16); s += __shfl_xor(s, 32);
;                     if (fq == 0) atomicAdd(ss_out + row, s); }
.LBB0_3039:
	s_or_b64 exec, exec, s[0:1]
	v_fmamk_f32 v80, v190, 0x39800000, v184
	v_rsq_f32_e32 v82, v80
	s_waitcnt vmcnt(3)
	v_lshlrev_b32_e32 v91, 16, v104
	v_and_b32_e32 v92, 0xffff0000, v104
	v_lshlrev_b32_e32 v93, 16, v105
	v_mul_f32_e32 v76, v76, v82
	v_mul_f32_e32 v76, 0xbfb8aa3b, v76
	v_exp_f32_e32 v76, v76
	v_and_b32_e32 v94, 0xffff0000, v105
	v_mul_f32_e32 v72, v72, v82
	v_mul_f32_e32 v72, 0xbfb8aa3b, v72
	v_add_f32_e32 v76, 1.0, v76
	v_lshlrev_b32_e32 v85, 16, v109
	v_and_b32_e32 v86, 0xffff0000, v109
	v_exp_f32_e32 v72, v72
	v_lshlrev_b32_e32 v87, 16, v110
	v_and_b32_e32 v88, 0xffff0000, v110
	v_lshlrev_b32_e32 v89, 16, v111
	v_and_b32_e32 v90, 0xffff0000, v111
	v_add_f32_e32 v72, 1.0, v72
	v_mul_f32_e32 v77, v77, v82
	v_mul_f32_e32 v77, 0xbfb8aa3b, v77
	v_lshlrev_b32_e32 v83, 16, v108
	v_rcp_f32_e32 v76, v76
	v_exp_f32_e32 v77, v77
	v_fmac_f32_e32 v91, v76, v83
	v_add_f32_e32 v77, 1.0, v77
	v_mul_f32_e32 v73, v73, v82
	v_lshlrev_b32_e32 v95, 16, v106
	v_rcp_f32_e32 v72, v72
	v_mul_f32_e32 v73, 0xbfb8aa3b, v73
	v_fmac_f32_e32 v95, v72, v87
	v_exp_f32_e32 v73, v73
	s_nop 0
	v_add_f32_e32 v73, 1.0, v73
	v_rcp_f32_e32 v72, v77
	v_mul_f32_e32 v77, v78, v82
	v_mul_f32_e32 v77, 0xbfb8aa3b, v77
	v_and_b32_e32 v84, 0xffff0000, v108
	v_exp_f32_e32 v77, v77
	v_fmac_f32_e32 v92, v72, v84
	v_add_f32_e32 v77, 1.0, v77
	v_mul_f32_e32 v74, v74, v82
	v_mul_f32_e32 v74, 0xbfb8aa3b, v74
	v_and_b32_e32 v106, 0xffff0000, v106
	v_rcp_f32_e32 v72, v73
	v_exp_f32_e32 v74, v74
	v_fmac_f32_e32 v106, v72, v88
	v_add_f32_e32 v74, 1.0, v74
	v_rcp_f32_e32 v72, v77
	v_mul_f32_e32 v77, v79, v82
	v_fmac_f32_e32 v93, v72, v85
	v_mul_f32_e32 v77, 0xbfb8aa3b, v77
	v_exp_f32_e32 v77, v77
	s_nop 0
	v_add_f32_e32 v76, 1.0, v77
	v_rcp_f32_e32 v72, v74
	v_mul_f32_e32 v74, v75, v82
	v_mul_f32_e32 v74, 0xbfb8aa3b, v74
	v_lshlrev_b32_e32 v108, 16, v107
	v_exp_f32_e32 v74, v74
	v_fmac_f32_e32 v108, v72, v89
	v_add_f32_e32 v74, 1.0, v74
	v_rcp_f32_e32 v72, v76
	s_nop 0
	v_fmac_f32_e32 v94, v72, v86
	v_mul_f32_e32 v68, v68, v82
	v_mul_f32_e32 v68, 0xbfb8aa3b, v68
	v_exp_f32_e32 v68, v68
	v_and_b32_e32 v107, 0xffff0000, v107
	v_rcp_f32_e32 v72, v74
	v_mul_f32_e32 v77, v94, v94
	v_add_f32_e32 v68, 1.0, v68
	v_fmac_f32_e32 v107, v72, v90
	v_cvt_pk_bf16_f32 v72, v91, v92
	v_cvt_pk_bf16_f32 v73, v93, v94
	v_fmac_f32_e32 v77, v93, v93
	v_mul_f32_e32 v76, v92, v92
	v_fmac_f32_e32 v76, v91, v91
	v_mul_f32_e32 v64, v64, v82
	v_add_f32_e32 v76, v76, v77
	v_mul_f32_e32 v77, v106, v106
	v_mul_f32_e32 v64, 0xbfb8aa3b, v64
	v_cvt_pk_bf16_f32 v74, v95, v106
	v_fmac_f32_e32 v77, v95, v95
	s_waitcnt vmcnt(2)
	v_lshlrev_b32_e32 v92, 16, v98
	v_and_b32_e32 v95, 0xffff0000, v98
	v_exp_f32_e32 v64, v64
	v_add_f32_e32 v76, v77, v76
	v_mul_f32_e32 v77, v107, v107
	v_fmac_f32_e32 v77, v108, v108
	v_lshlrev_b32_e32 v88, 16, v96
	v_and_b32_e32 v89, 0xffff0000, v96
	v_lshlrev_b32_e32 v90, 16, v97
	v_and_b32_e32 v91, 0xffff0000, v97
	v_lshlrev_b32_e32 v96, 16, v99
	v_and_b32_e32 v97, 0xffff0000, v99
	v_add_f32_e32 v76, v77, v76
	v_lshlrev_b32_e32 v77, 16, v100
	v_and_b32_e32 v78, 0xffff0000, v100
	v_add_f32_e32 v64, 1.0, v64
	v_mul_f32_e32 v69, v69, v82
	v_mul_f32_e32 v69, 0xbfb8aa3b, v69
	v_rcp_f32_e32 v68, v68
	v_exp_f32_e32 v69, v69
	v_fmac_f32_e32 v88, v68, v77
	v_add_f32_e32 v69, 1.0, v69
	v_mul_f32_e32 v65, v65, v82
	v_lshlrev_b32_e32 v84, 16, v102
	v_rcp_f32_e32 v64, v64
	v_mul_f32_e32 v65, 0xbfb8aa3b, v65
	v_fmac_f32_e32 v92, v64, v84
	v_exp_f32_e32 v65, v65
	s_nop 0
	v_add_f32_e32 v65, 1.0, v65
	v_rcp_f32_e32 v64, v69
	v_mul_f32_e32 v69, v70, v82
	v_mul_f32_e32 v69, 0xbfb8aa3b, v69
	v_exp_f32_e32 v69, v69
	v_fmac_f32_e32 v89, v64, v78
	v_add_f32_e32 v69, 1.0, v69
	v_mul_f32_e32 v66, v66, v82
	v_mul_f32_e32 v66, 0xbfb8aa3b, v66
	v_and_b32_e32 v85, 0xffff0000, v102
	v_rcp_f32_e32 v64, v65
	v_exp_f32_e32 v66, v66
	v_fmac_f32_e32 v95, v64, v85
	v_add_f32_e32 v66, 1.0, v66
	v_lshlrev_b32_e32 v79, 16, v101
	v_rcp_f32_e32 v64, v69
	v_mul_f32_e32 v69, v71, v82
	v_fmac_f32_e32 v90, v64, v79
	v_mul_f32_e32 v69, 0xbfb8aa3b, v69
	v_exp_f32_e32 v69, v69
	s_nop 0
	v_add_f32_e32 v68, 1.0, v69
	v_rcp_f32_e32 v64, v66
	v_mul_f32_e32 v66, v67, v82
	v_mul_f32_e32 v66, 0xbfb8aa3b, v66
	v_lshlrev_b32_e32 v86, 16, v103
	v_exp_f32_e32 v66, v66
	v_fmac_f32_e32 v96, v64, v86
	v_add_f32_e32 v66, 1.0, v66
	v_and_b32_e32 v83, 0xffff0000, v101
	v_rcp_f32_e32 v64, v68
	s_nop 0
	v_fmac_f32_e32 v91, v64, v83
	v_and_b32_e32 v87, 0xffff0000, v103
	v_rcp_f32_e32 v64, v66
	s_nop 0
	v_fmac_f32_e32 v97, v64, v87
	v_mul_f32_e32 v64, v89, v89
	v_mul_f32_e32 v65, v91, v91
	v_fmac_f32_e32 v64, v88, v88
	v_fmac_f32_e32 v65, v90, v90
	v_add_f32_e32 v64, v64, v65
	v_mul_f32_e32 v65, v95, v95
	v_fmac_f32_e32 v65, v92, v92
	v_add_f32_e32 v64, v65, v64
	v_mul_f32_e32 v65, v97, v97
	v_fmac_f32_e32 v65, v96, v96
	v_add_f32_e32 v64, v65, v64
	v_add_f32_e32 v67, v76, v64
	ds_bpermute_b32 v68, v124, v67
	s_waitcnt lgkmcnt(1)
	v_lshlrev_b64 v[80:81], 13, v[172:173]
	v_lshl_add_u64 v[64:65], s[12:13], 0, v[80:81]
	v_lshl_add_u64 v[70:71], v[168:169], 1, v[64:65]
	v_cvt_pk_bf16_f32 v75, v108, v107
	s_waitcnt lgkmcnt(0)
	v_add_f32_e32 v64, v67, v68
	ds_bpermute_b32 v65, v122, v64
	global_store_dwordx4 v[70:71], v[72:75], off
	v_cvt_pk_bf16_f32 v66, v88, v89
	v_cvt_pk_bf16_f32 v67, v90, v91
	v_cvt_pk_bf16_f32 v68, v92, v95
	v_cvt_pk_bf16_f32 v69, v96, v97
	global_store_dwordx4 v[70:71], v[66:69], off offset:256
	s_and_saveexec_b64 s[0:1], s[6:7]
	s_cbranch_execz .LBB0_3041
	v_lshl_add_u64 v[66:67], v[172:173], 2, s[18:19]
	s_waitcnt lgkmcnt(0)
	v_add_f32_e32 v64, v64, v65
	global_atomic_add_f32 v[66:67], v64, off
; DI float sigmoidf_(float z) { return 1.0f / (1.0f + __expf(-z)); }
; DI v4u pack8(const f4& a, const f4& b) { v4u w; w.x = cvt_pk_bf16(a[0], a[1]); w.y = cvt_pk_bf16(a[2], a[3]); w.z = cvt_pk_bf16(b[0], b[1]); w.w = cvt_pk_bf16(b[2], b[3]); return w; }
; DI void unpack8(const v4u& w, f4& a, f4& b) { a[0] = bf_lo(w.x); a[1] = bf_hi(w.x); a[2] = bf_lo(w.y); a[3] = bf_hi(w.y); b[0] = bf_lo(w.z); b[1] = bf_hi(w.z); b[2] = bf_lo(w.w); b[3] = bf_hi(w.w); }
;     DI void operator()(f4 (&acc)[2][2][4][2], const Unit& u, int wr, int wc, int fr, int fq) const {
;     ...
;         for (int ai = 0; ai < 2; ++ai)
; #pragma unroll
;             for (int mp = 0; mp < 2; ++mp) {
;                 v4u pv[2][2], hv[2][2];
; #pragma unroll
;                 for (int mm = 0; mm < 2; ++mm)
; #pragma unroll
;                     for (int bj = 0; bj < 2; ++bj) { const size_t off = (size_t)(row0 + ai * HALF + (2 * mp + mm) * 16) * D + col0 + bj * HALF;
;                         pv[mm][bj] = *(const v4u*)(pp + off); hv[mm][bj] = *(const v4u*)(hb + off); }
;                 asm volatile("" ::: "memory");
; #pragma unroll
;                 for (int mm = 0; mm < 2; ++mm) { const int m = 2 * mp + mm, row = row0 + ai * HALF + m * 16; const float r = __builtin_amdgcn_rsqf(rr[ai][m] * (1.0f / D) + RMS_EPS); float s = 0.f;
; #pragma unroll
;                     for (int bj = 0; bj < 2; ++bj) { const size_t off = (size_t)row * D + col0 + bj * HALF;
;                         f4 p0, p1; unpack8(pv[mm][bj], p0, p1);
;                         f4 h0, h1; unpack8(hv[mm][bj], h0, h1);
; #pragma unroll
;                         for (int t = 0; t < 4; ++t) { h0[t] += sigmoidf_(acc[ai][bj][m][0][t] * r) * p0[t]; h1[t] += sigmoidf_(acc[ai][bj][m][1][t] * r) * p1[t]; }
;                         *(v4u*)(h3b + off) = pack8(h0, h1);
;                         s += (h0[0] * h0[0] + h0[1] * h0[1]) + (h0[2] * h0[2] + h0[3] * h0[3]) + (h1[0] * h1[0] + h1[1] * h1[1]) + (h1[2] * h1[2] + h1[3] * h1[3]); }
;                     s += __shfl_xor(s, 16); s += __shfl_xor(s, 32);
;                     if (fq == 0) atomicAdd(ss_out + row, s); }
.LBB0_3041:
	s_or_b64 exec, exec, s[0:1]
	v_add_u32_e32 v86, 0x80, v170
	v_ashrrev_i32_e32 v87, 31, v86
	s_waitcnt lgkmcnt(0)
	v_lshlrev_b64 v[64:65], 12, v[86:87]
	v_lshl_add_u64 v[64:65], v[64:65], 0, v[168:169]
	v_lshlrev_b64 v[64:65], 1, v[64:65]
	v_lshl_add_u64 v[66:67], s[14:15], 0, v[64:65]
	v_lshl_add_u64 v[64:65], s[8:9], 0, v[64:65]
	global_load_dwordx4 v[90:93], v[66:67], off
	global_load_dwordx4 v[94:97], v[64:65], off
	v_fmamk_f32 v68, v189, 0x39800000, v184
	v_rsq_f32_e32 v104, v68
	v_add_u32_e32 v84, 0x90, v170
	v_ashrrev_i32_e32 v85, 31, v84
	v_lshlrev_b64 v[68:69], 12, v[84:85]
	v_mul_f32_e32 v60, v60, v104
	v_mul_f32_e32 v56, v56, v104
	v_mul_f32_e32 v60, 0xbfb8aa3b, v60
	v_mul_f32_e32 v56, 0xbfb8aa3b, v56
	v_exp_f32_e32 v60, v60
	v_lshl_add_u64 v[68:69], v[68:69], 0, v[168:169]
	v_exp_f32_e32 v56, v56
	v_lshlrev_b64 v[68:69], 1, v[68:69]
	v_lshl_add_u64 v[70:71], s[14:15], 0, v[68:69]
	v_lshl_add_u64 v[102:103], s[8:9], 0, v[68:69]
	global_load_dwordx4 v[98:101], v[66:67], off offset:256
	global_load_dwordx4 v[80:83], v[64:65], off offset:256
	global_load_dwordx4 v[76:79], v[70:71], off
	s_nop 0
	global_load_dwordx4 v[68:71], v[70:71], off offset:256
	s_nop 0
	global_load_dwordx4 v[72:75], v[102:103], off
	global_load_dwordx4 v[64:67], v[102:103], off offset:256
	v_add_f32_e32 v60, 1.0, v60
	v_add_f32_e32 v56, 1.0, v56
	v_mul_f32_e32 v61, v61, v104
	v_mul_f32_e32 v61, 0xbfb8aa3b, v61
	v_exp_f32_e32 v61, v61
	s_nop 0
	v_add_f32_e32 v61, 1.0, v61
	v_rcp_f32_e32 v60, v60
	v_mul_f32_e32 v57, v57, v104
	v_rcp_f32_e32 v56, v56
	v_mul_f32_e32 v57, 0xbfb8aa3b, v57
	v_exp_f32_e32 v57, v57
	v_mul_f32_e32 v58, v58, v104
	v_mul_f32_e32 v58, 0xbfb8aa3b, v58
	v_exp_f32_e32 v58, v58
	v_add_f32_e32 v57, 1.0, v57
	v_mul_f32_e32 v52, v52, v104
	v_mul_f32_e32 v52, 0xbfb8aa3b, v52
	v_add_f32_e32 v58, 1.0, v58
	v_exp_f32_e32 v52, v52
	v_mul_f32_e32 v48, v48, v104
	v_mul_f32_e32 v48, 0xbfb8aa3b, v48
	v_add_f32_e32 v52, 1.0, v52
	v_exp_f32_e32 v48, v48
	v_mul_f32_e32 v53, v53, v104
	v_mul_f32_e32 v53, 0xbfb8aa3b, v53
	v_exp_f32_e32 v53, v53
	v_add_f32_e32 v48, 1.0, v48
	v_mul_f32_e32 v49, v49, v104
	v_mul_f32_e32 v49, 0xbfb8aa3b, v49
	v_add_f32_e32 v53, 1.0, v53
	v_exp_f32_e32 v49, v49
	v_mul_f32_e32 v50, v50, v104
	v_mul_f32_e32 v50, 0xbfb8aa3b, v50
	s_waitcnt vmcnt(7)
	v_lshlrev_b32_e32 v105, 16, v92
	s_waitcnt vmcnt(6)
	v_lshlrev_b32_e32 v111, 16, v96
	v_fmac_f32_e32 v111, v56, v105
	v_lshlrev_b32_e32 v102, 16, v90
	v_lshlrev_b32_e32 v107, 16, v94
	v_fmac_f32_e32 v107, v60, v102
	v_rcp_f32_e32 v56, v61
	v_mul_f32_e32 v61, v62, v104
	v_mul_f32_e32 v61, 0xbfb8aa3b, v61
	v_and_b32_e32 v90, 0xffff0000, v90
	v_and_b32_e32 v94, 0xffff0000, v94
	v_exp_f32_e32 v61, v61
	v_fmac_f32_e32 v94, v56, v90
	v_add_f32_e32 v61, 1.0, v61
	v_and_b32_e32 v92, 0xffff0000, v92
	v_and_b32_e32 v96, 0xffff0000, v96
	v_rcp_f32_e32 v56, v57
	s_nop 0
	v_fmac_f32_e32 v96, v56, v92
	v_lshlrev_b32_e32 v103, 16, v91
	v_lshlrev_b32_e32 v108, 16, v95
	v_rcp_f32_e32 v56, v61
	v_mul_f32_e32 v61, v63, v104
	v_fmac_f32_e32 v108, v56, v103
	v_mul_f32_e32 v61, 0xbfb8aa3b, v61
	v_exp_f32_e32 v61, v61
	s_nop 0
	v_add_f32_e32 v60, 1.0, v61
	v_rcp_f32_e32 v56, v58
	v_mul_f32_e32 v58, v59, v104
	v_mul_f32_e32 v58, 0xbfb8aa3b, v58
	v_lshlrev_b32_e32 v106, 16, v93
	v_lshlrev_b32_e32 v112, 16, v97
	v_exp_f32_e32 v58, v58
	v_fmac_f32_e32 v112, v56, v106
	v_add_f32_e32 v58, 1.0, v58
	v_and_b32_e32 v91, 0xffff0000, v91
	v_and_b32_e32 v95, 0xffff0000, v95
	v_rcp_f32_e32 v56, v60
	s_nop 0
	v_fmac_f32_e32 v95, v56, v91
	v_mul_f32_e32 v60, v94, v94
	v_mul_f32_e32 v61, v95, v95
	v_fmac_f32_e32 v60, v107, v107
	v_fmac_f32_e32 v61, v108, v108
	v_and_b32_e32 v93, 0xffff0000, v93
	v_and_b32_e32 v97, 0xffff0000, v97
	v_rcp_f32_e32 v56, v58
	v_add_f32_e32 v60, v60, v61
	v_mul_f32_e32 v61, v96, v96
	v_fmac_f32_e32 v97, v56, v93
	v_fmac_f32_e32 v61, v111, v111
	v_add_f32_e32 v60, v61, v60
	v_mul_f32_e32 v61, v97, v97
	v_fmac_f32_e32 v61, v112, v112
	v_add_f32_e32 v60, v61, v60
	s_waitcnt vmcnt(5)
	v_lshlrev_b32_e32 v61, 16, v98
	v_and_b32_e32 v62, 0xffff0000, v98
	v_lshlrev_b32_e32 v63, 16, v99
	v_and_b32_e32 v90, 0xffff0000, v99
	v_cvt_pk_bf16_f32 v56, v107, v94
	v_lshlrev_b32_e32 v93, 16, v101
	v_and_b32_e32 v94, 0xffff0000, v101
	v_cvt_pk_bf16_f32 v57, v108, v95
	s_waitcnt vmcnt(4)
	v_lshlrev_b32_e32 v95, 16, v80
	v_rcp_f32_e32 v52, v52
	s_nop 0
	v_fmac_f32_e32 v95, v52, v61
	v_cvt_pk_bf16_f32 v58, v111, v96
	v_cvt_pk_bf16_f32 v59, v112, v97
	v_lshlrev_b32_e32 v91, 16, v100
	v_lshlrev_b32_e32 v97, 16, v82
	v_rcp_f32_e32 v48, v48
	s_nop 0
	v_fmac_f32_e32 v97, v48, v91
	v_add_f32_e32 v49, 1.0, v49
	v_rcp_f32_e32 v48, v53
	v_mul_f32_e32 v53, v54, v104
	v_mul_f32_e32 v53, 0xbfb8aa3b, v53
	v_and_b32_e32 v80, 0xffff0000, v80
	v_exp_f32_e32 v53, v53
	v_fmac_f32_e32 v80, v48, v62
	v_add_f32_e32 v53, 1.0, v53
	v_and_b32_e32 v92, 0xffff0000, v100
	v_and_b32_e32 v82, 0xffff0000, v82
	v_rcp_f32_e32 v48, v49
	v_exp_f32_e32 v50, v50
	v_fmac_f32_e32 v82, v48, v92
	v_add_f32_e32 v50, 1.0, v50
	v_lshlrev_b32_e32 v96, 16, v81
	v_rcp_f32_e32 v48, v53
	v_mul_f32_e32 v53, v55, v104
	v_fmac_f32_e32 v96, v48, v63
	v_mul_f32_e32 v53, 0xbfb8aa3b, v53
	v_exp_f32_e32 v53, v53
	s_nop 0
	v_add_f32_e32 v52, 1.0, v53
	v_rcp_f32_e32 v48, v50
	v_mul_f32_e32 v50, v51, v104
	v_mul_f32_e32 v50, 0xbfb8aa3b, v50
	v_lshlrev_b32_e32 v100, 16, v83
	v_exp_f32_e32 v50, v50
	v_fmac_f32_e32 v100, v48, v93
	v_add_f32_e32 v50, 1.0, v50
	v_and_b32_e32 v81, 0xffff0000, v81
	v_rcp_f32_e32 v48, v52
	s_nop 0
	v_fmac_f32_e32 v81, v48, v90
	v_and_b32_e32 v83, 0xffff0000, v83
	v_rcp_f32_e32 v48, v50
	s_nop 0
	v_fmac_f32_e32 v83, v48, v94
	v_mul_f32_e32 v48, v80, v80
	v_mul_f32_e32 v49, v81, v81
	v_fmac_f32_e32 v48, v95, v95
	v_fmac_f32_e32 v49, v96, v96
	v_add_f32_e32 v48, v48, v49
	v_mul_f32_e32 v49, v82, v82
	v_fmac_f32_e32 v49, v97, v97
	v_add_f32_e32 v48, v49, v48
	v_mul_f32_e32 v49, v83, v83
	v_fmac_f32_e32 v49, v100, v100
	v_add_f32_e32 v48, v49, v48
	v_add_f32_e32 v51, v60, v48
	ds_bpermute_b32 v52, v124, v51
	v_lshlrev_b64 v[88:89], 13, v[86:87]
	v_lshl_add_u64 v[48:49], s[12:13], 0, v[88:89]
	v_lshl_add_u64 v[54:55], v[168:169], 1, v[48:49]
	global_store_dwordx4 v[54:55], v[56:59], off
	s_waitcnt lgkmcnt(0)
	v_add_f32_e32 v48, v51, v52
	ds_bpermute_b32 v49, v122, v48
	v_cvt_pk_bf16_f32 v50, v95, v80
	v_cvt_pk_bf16_f32 v51, v96, v81
	v_cvt_pk_bf16_f32 v52, v97, v82
	v_cvt_pk_bf16_f32 v53, v100, v83
	global_store_dwordx4 v[54:55], v[50:53], off offset:256
	s_and_saveexec_b64 s[0:1], s[6:7]
	s_cbranch_execz .LBB0_3043
	v_lshl_add_u64 v[50:51], v[86:87], 2, s[18:19]
	s_waitcnt lgkmcnt(0)
	v_add_f32_e32 v48, v48, v49
	global_atomic_add_f32 v[50:51], v48, off
; DI float sigmoidf_(float z) { return 1.0f / (1.0f + __expf(-z)); }
; DI v4u pack8(const f4& a, const f4& b) { v4u w; w.x = cvt_pk_bf16(a[0], a[1]); w.y = cvt_pk_bf16(a[2], a[3]); w.z = cvt_pk_bf16(b[0], b[1]); w.w = cvt_pk_bf16(b[2], b[3]); return w; }
; DI void unpack8(const v4u& w, f4& a, f4& b) { a[0] = bf_lo(w.x); a[1] = bf_hi(w.x); a[2] = bf_lo(w.y); a[3] = bf_hi(w.y); b[0] = bf_lo(w.z); b[1] = bf_hi(w.z); b[2] = bf_lo(w.w); b[3] = bf_hi(w.w); }
;     DI void operator()(f4 (&acc)[2][2][4][2], const Unit& u, int wr, int wc, int fr, int fq) const {
;     ...
;                 for (int mm = 0; mm < 2; ++mm) { const int m = 2 * mp + mm, row = row0 + ai * HALF + m * 16; const float r = __builtin_amdgcn_rsqf(rr[ai][m] * (1.0f / D) + RMS_EPS); float s = 0.f;
; #pragma unroll
;                     for (int bj = 0; bj < 2; ++bj) { const size_t off = (size_t)row * D + col0 + bj * HALF;
;                         f4 p0, p1; unpack8(pv[mm][bj], p0, p1);
;                         f4 h0, h1; unpack8(hv[mm][bj], h0, h1);
; #pragma unroll
;                         for (int t = 0; t < 4; ++t) { h0[t] += sigmoidf_(acc[ai][bj][m][0][t] * r) * p0[t]; h1[t] += sigmoidf_(acc[ai][bj][m][1][t] * r) * p1[t]; }
;                         *(v4u*)(h3b + off) = pack8(h0, h1);
;                         s += (h0[0] * h0[0] + h0[1] * h0[1]) + (h0[2] * h0[2] + h0[3] * h0[3]) + (h1[0] * h1[0] + h1[1] * h1[1]) + (h1[2] * h1[2] + h1[3] * h1[3]); }
;                     s += __shfl_xor(s, 16); s += __shfl_xor(s, 32);
;                     if (fq == 0) atomicAdd(ss_out + row, s); }
.LBB0_3043:
	s_or_b64 exec, exec, s[0:1]
	v_fmamk_f32 v48, v188, 0x39800000, v184
	v_rsq_f32_e32 v50, v48
	s_waitcnt vmcnt(3)
	v_lshlrev_b32_e32 v59, 16, v72
	v_and_b32_e32 v60, 0xffff0000, v72
	v_lshlrev_b32_e32 v61, 16, v73
	v_mul_f32_e32 v44, v44, v50
	v_mul_f32_e32 v44, 0xbfb8aa3b, v44
	v_exp_f32_e32 v44, v44
	v_and_b32_e32 v62, 0xffff0000, v73
	v_mul_f32_e32 v40, v40, v50
	v_mul_f32_e32 v40, 0xbfb8aa3b, v40
	v_add_f32_e32 v44, 1.0, v44
	v_lshlrev_b32_e32 v53, 16, v77
	v_and_b32_e32 v54, 0xffff0000, v77
	v_exp_f32_e32 v40, v40
	v_lshlrev_b32_e32 v55, 16, v78
	v_and_b32_e32 v56, 0xffff0000, v78
	v_lshlrev_b32_e32 v57, 16, v79
	v_and_b32_e32 v58, 0xffff0000, v79
	v_add_f32_e32 v40, 1.0, v40
	v_mul_f32_e32 v45, v45, v50
	v_mul_f32_e32 v45, 0xbfb8aa3b, v45
	v_lshlrev_b32_e32 v51, 16, v76
	v_rcp_f32_e32 v44, v44
	v_exp_f32_e32 v45, v45
	v_fmac_f32_e32 v59, v44, v51
	v_add_f32_e32 v45, 1.0, v45
	v_mul_f32_e32 v41, v41, v50
	v_lshlrev_b32_e32 v63, 16, v74
	v_rcp_f32_e32 v40, v40
	v_mul_f32_e32 v41, 0xbfb8aa3b, v41
	v_fmac_f32_e32 v63, v40, v55
	v_exp_f32_e32 v41, v41
	s_nop 0
	v_add_f32_e32 v41, 1.0, v41
	v_rcp_f32_e32 v40, v45
	v_mul_f32_e32 v45, v46, v50
	v_mul_f32_e32 v45, 0xbfb8aa3b, v45
	v_and_b32_e32 v52, 0xffff0000, v76
	v_exp_f32_e32 v45, v45
	v_fmac_f32_e32 v60, v40, v52
	v_add_f32_e32 v45, 1.0, v45
	v_mul_f32_e32 v42, v42, v50
	v_mul_f32_e32 v42, 0xbfb8aa3b, v42
	v_and_b32_e32 v74, 0xffff0000, v74
	v_rcp_f32_e32 v40, v41
	v_exp_f32_e32 v42, v42
	v_fmac_f32_e32 v74, v40, v56
	v_add_f32_e32 v42, 1.0, v42
	v_rcp_f32_e32 v40, v45
	v_mul_f32_e32 v45, v47, v50
	v_fmac_f32_e32 v61, v40, v53
	v_mul_f32_e32 v45, 0xbfb8aa3b, v45
	v_exp_f32_e32 v45, v45
	s_nop 0
	v_add_f32_e32 v44, 1.0, v45
	v_rcp_f32_e32 v40, v42
	v_mul_f32_e32 v42, v43, v50
	v_mul_f32_e32 v42, 0xbfb8aa3b, v42
	v_lshlrev_b32_e32 v76, 16, v75
	v_exp_f32_e32 v42, v42
	v_fmac_f32_e32 v76, v40, v57
	v_add_f32_e32 v42, 1.0, v42
	v_rcp_f32_e32 v40, v44
	s_nop 0
	v_fmac_f32_e32 v62, v40, v54
	v_mul_f32_e32 v36, v36, v50
	v_mul_f32_e32 v36, 0xbfb8aa3b, v36
	v_exp_f32_e32 v36, v36
	v_and_b32_e32 v75, 0xffff0000, v75
	v_rcp_f32_e32 v40, v42
	v_mul_f32_e32 v45, v62, v62
	v_add_f32_e32 v36, 1.0, v36
	v_fmac_f32_e32 v75, v40, v58
	v_cvt_pk_bf16_f32 v40, v59, v60
	v_cvt_pk_bf16_f32 v41, v61, v62
	v_fmac_f32_e32 v45, v61, v61
	v_mul_f32_e32 v44, v60, v60
	v_fmac_f32_e32 v44, v59, v59
	v_mul_f32_e32 v32, v32, v50
	v_add_f32_e32 v44, v44, v45
	v_mul_f32_e32 v45, v74, v74
	v_mul_f32_e32 v32, 0xbfb8aa3b, v32
	v_cvt_pk_bf16_f32 v42, v63, v74
	v_fmac_f32_e32 v45, v63, v63
	s_waitcnt vmcnt(2)
	v_lshlrev_b32_e32 v60, 16, v66
	v_and_b32_e32 v63, 0xffff0000, v66
	v_exp_f32_e32 v32, v32
	v_add_f32_e32 v44, v45, v44
	v_mul_f32_e32 v45, v75, v75
	v_fmac_f32_e32 v45, v76, v76
	v_lshlrev_b32_e32 v56, 16, v64
	v_and_b32_e32 v57, 0xffff0000, v64
	v_lshlrev_b32_e32 v58, 16, v65
	v_and_b32_e32 v59, 0xffff0000, v65
	v_lshlrev_b32_e32 v64, 16, v67
	v_and_b32_e32 v65, 0xffff0000, v67
	v_add_f32_e32 v44, v45, v44
	v_lshlrev_b32_e32 v45, 16, v68
	v_and_b32_e32 v46, 0xffff0000, v68
	v_add_f32_e32 v32, 1.0, v32
	v_mul_f32_e32 v37, v37, v50
	v_mul_f32_e32 v37, 0xbfb8aa3b, v37
	v_rcp_f32_e32 v36, v36
	v_exp_f32_e32 v37, v37
	v_fmac_f32_e32 v56, v36, v45
	v_add_f32_e32 v37, 1.0, v37
	v_mul_f32_e32 v33, v33, v50
	v_lshlrev_b32_e32 v52, 16, v70
	v_rcp_f32_e32 v32, v32
	v_mul_f32_e32 v33, 0xbfb8aa3b, v33
	v_fmac_f32_e32 v60, v32, v52
	v_exp_f32_e32 v33, v33
	s_nop 0
	v_add_f32_e32 v33, 1.0, v33
	v_rcp_f32_e32 v32, v37
	v_mul_f32_e32 v37, v38, v50
	v_mul_f32_e32 v37, 0xbfb8aa3b, v37
	v_exp_f32_e32 v37, v37
	v_fmac_f32_e32 v57, v32, v46
	v_add_f32_e32 v37, 1.0, v37
	v_mul_f32_e32 v34, v34, v50
	v_mul_f32_e32 v34, 0xbfb8aa3b, v34
	v_and_b32_e32 v53, 0xffff0000, v70
	v_rcp_f32_e32 v32, v33
	v_exp_f32_e32 v34, v34
	v_fmac_f32_e32 v63, v32, v53
	v_add_f32_e32 v34, 1.0, v34
	v_lshlrev_b32_e32 v47, 16, v69
	v_rcp_f32_e32 v32, v37
	v_mul_f32_e32 v37, v39, v50
	v_fmac_f32_e32 v58, v32, v47
	v_mul_f32_e32 v37, 0xbfb8aa3b, v37
	v_exp_f32_e32 v37, v37
	s_nop 0
	v_add_f32_e32 v36, 1.0, v37
	v_rcp_f32_e32 v32, v34
	v_mul_f32_e32 v34, v35, v50
	v_mul_f32_e32 v34, 0xbfb8aa3b, v34
	v_lshlrev_b32_e32 v54, 16, v71
	v_exp_f32_e32 v34, v34
	v_fmac_f32_e32 v64, v32, v54
	v_add_f32_e32 v34, 1.0, v34
	v_and_b32_e32 v51, 0xffff0000, v69
	v_rcp_f32_e32 v32, v36
	s_nop 0
	v_fmac_f32_e32 v59, v32, v51
	v_and_b32_e32 v55, 0xffff0000, v71
	v_rcp_f32_e32 v32, v34
	s_nop 0
	v_fmac_f32_e32 v65, v32, v55
	v_mul_f32_e32 v32, v57, v57
	v_mul_f32_e32 v33, v59, v59
	v_fmac_f32_e32 v32, v56, v56
	v_fmac_f32_e32 v33, v58, v58
	v_add_f32_e32 v32, v32, v33
	v_mul_f32_e32 v33, v63, v63
	v_fmac_f32_e32 v33, v60, v60
	v_add_f32_e32 v32, v33, v32
	v_mul_f32_e32 v33, v65, v65
	v_fmac_f32_e32 v33, v64, v64
	v_add_f32_e32 v32, v33, v32
	v_add_f32_e32 v35, v44, v32
	ds_bpermute_b32 v36, v124, v35
	s_waitcnt lgkmcnt(1)
	v_lshlrev_b64 v[48:49], 13, v[84:85]
	v_lshl_add_u64 v[32:33], s[12:13], 0, v[48:49]
	v_lshl_add_u64 v[38:39], v[168:169], 1, v[32:33]
	v_cvt_pk_bf16_f32 v43, v76, v75
	s_waitcnt lgkmcnt(0)
	v_add_f32_e32 v32, v35, v36
	ds_bpermute_b32 v33, v122, v32
	global_store_dwordx4 v[38:39], v[40:43], off
	v_cvt_pk_bf16_f32 v34, v56, v57
	v_cvt_pk_bf16_f32 v35, v58, v59
	v_cvt_pk_bf16_f32 v36, v60, v63
	v_cvt_pk_bf16_f32 v37, v64, v65
	global_store_dwordx4 v[38:39], v[34:37], off offset:256
	s_and_saveexec_b64 s[0:1], s[6:7]
	s_cbranch_execz .LBB0_3045
	v_lshl_add_u64 v[34:35], v[84:85], 2, s[18:19]
	s_waitcnt lgkmcnt(0)
	v_add_f32_e32 v32, v32, v33
	global_atomic_add_f32 v[34:35], v32, off
; DI float sigmoidf_(float z) { return 1.0f / (1.0f + __expf(-z)); }
; DI v4u pack8(const f4& a, const f4& b) { v4u w; w.x = cvt_pk_bf16(a[0], a[1]); w.y = cvt_pk_bf16(a[2], a[3]); w.z = cvt_pk_bf16(b[0], b[1]); w.w = cvt_pk_bf16(b[2], b[3]); return w; }
; DI void unpack8(const v4u& w, f4& a, f4& b) { a[0] = bf_lo(w.x); a[1] = bf_hi(w.x); a[2] = bf_lo(w.y); a[3] = bf_hi(w.y); b[0] = bf_lo(w.z); b[1] = bf_hi(w.z); b[2] = bf_lo(w.w); b[3] = bf_hi(w.w); }
;     DI void operator()(f4 (&acc)[2][2][4][2], const Unit& u, int wr, int wc, int fr, int fq) const {
;     ...
;         for (int ai = 0; ai < 2; ++ai)
; #pragma unroll
;             for (int mp = 0; mp < 2; ++mp) {
;                 v4u pv[2][2], hv[2][2];
; #pragma unroll
;                 for (int mm = 0; mm < 2; ++mm)
; #pragma unroll
;                     for (int bj = 0; bj < 2; ++bj) { const size_t off = (size_t)(row0 + ai * HALF + (2 * mp + mm) * 16) * D + col0 + bj * HALF;
;                         pv[mm][bj] = *(const v4u*)(pp + off); hv[mm][bj] = *(const v4u*)(hb + off); }
;                 asm volatile("" ::: "memory");
; #pragma unroll
;                 for (int mm = 0; mm < 2; ++mm) { const int m = 2 * mp + mm, row = row0 + ai * HALF + m * 16; const float r = __builtin_amdgcn_rsqf(rr[ai][m] * (1.0f / D) + RMS_EPS); float s = 0.f;
; #pragma unroll
;                     for (int bj = 0; bj < 2; ++bj) { const size_t off = (size_t)row * D + col0 + bj * HALF;
;                         f4 p0, p1; unpack8(pv[mm][bj], p0, p1);
;                         f4 h0, h1; unpack8(hv[mm][bj], h0, h1);
; #pragma unroll
;                         for (int t = 0; t < 4; ++t) { h0[t] += sigmoidf_(acc[ai][bj][m][0][t] * r) * p0[t]; h1[t] += sigmoidf_(acc[ai][bj][m][1][t] * r) * p1[t]; }
;                         *(v4u*)(h3b + off) = pack8(h0, h1);
;                         s += (h0[0] * h0[0] + h0[1] * h0[1]) + (h0[2] * h0[2] + h0[3] * h0[3]) + (h1[0] * h1[0] + h1[1] * h1[1]) + (h1[2] * h1[2] + h1[3] * h1[3]); }
;                     s += __shfl_xor(s, 16); s += __shfl_xor(s, 32);
;                     if (fq == 0) atomicAdd(ss_out + row, s); }
.LBB0_3045:
	s_or_b64 exec, exec, s[0:1]
	v_add_u32_e32 v54, 0xa0, v170
	v_ashrrev_i32_e32 v55, 31, v54
	s_waitcnt lgkmcnt(0)
	v_lshlrev_b64 v[32:33], 12, v[54:55]
	v_lshl_add_u64 v[32:33], v[32:33], 0, v[168:169]
	v_lshlrev_b64 v[32:33], 1, v[32:33]
	v_lshl_add_u64 v[34:35], s[14:15], 0, v[32:33]
	v_lshl_add_u64 v[32:33], s[8:9], 0, v[32:33]
	global_load_dwordx4 v[58:61], v[34:35], off
	global_load_dwordx4 v[62:65], v[32:33], off
	v_fmamk_f32 v36, v187, 0x39800000, v184
	v_rsq_f32_e32 v72, v36
	v_add_u32_e32 v52, 0xb0, v170
	v_ashrrev_i32_e32 v53, 31, v52
	v_lshlrev_b64 v[36:37], 12, v[52:53]
	v_mul_f32_e32 v28, v28, v72
	v_mul_f32_e32 v24, v24, v72
	v_mul_f32_e32 v28, 0xbfb8aa3b, v28
	v_mul_f32_e32 v24, 0xbfb8aa3b, v24
	v_exp_f32_e32 v28, v28
	v_lshl_add_u64 v[36:37], v[36:37], 0, v[168:169]
	v_exp_f32_e32 v24, v24
	v_lshlrev_b64 v[36:37], 1, v[36:37]
	v_lshl_add_u64 v[38:39], s[14:15], 0, v[36:37]
	v_lshl_add_u64 v[70:71], s[8:9], 0, v[36:37]
	global_load_dwordx4 v[66:69], v[34:35], off offset:256
	global_load_dwordx4 v[48:51], v[32:33], off offset:256
	global_load_dwordx4 v[44:47], v[38:39], off
	s_nop 0
	global_load_dwordx4 v[36:39], v[38:39], off offset:256
	s_nop 0
	global_load_dwordx4 v[40:43], v[70:71], off
	global_load_dwordx4 v[32:35], v[70:71], off offset:256
	v_add_f32_e32 v28, 1.0, v28
	v_add_f32_e32 v24, 1.0, v24
	v_mul_f32_e32 v29, v29, v72
	v_mul_f32_e32 v29, 0xbfb8aa3b, v29
	v_exp_f32_e32 v29, v29
	s_nop 0
	v_add_f32_e32 v29, 1.0, v29
	v_rcp_f32_e32 v28, v28
	v_mul_f32_e32 v25, v25, v72
	v_rcp_f32_e32 v24, v24
	v_mul_f32_e32 v25, 0xbfb8aa3b, v25
	v_exp_f32_e32 v25, v25
	v_mul_f32_e32 v26, v26, v72
	v_mul_f32_e32 v26, 0xbfb8aa3b, v26
	v_exp_f32_e32 v26, v26
	v_add_f32_e32 v25, 1.0, v25
	v_mul_f32_e32 v20, v20, v72
	v_mul_f32_e32 v20, 0xbfb8aa3b, v20
	v_add_f32_e32 v26, 1.0, v26
	v_exp_f32_e32 v20, v20
	v_mul_f32_e32 v16, v16, v72
	v_mul_f32_e32 v16, 0xbfb8aa3b, v16
	v_add_f32_e32 v20, 1.0, v20
	v_exp_f32_e32 v16, v16
	v_mul_f32_e32 v21, v21, v72
	v_mul_f32_e32 v21, 0xbfb8aa3b, v21
	v_exp_f32_e32 v21, v21
	v_add_f32_e32 v16, 1.0, v16
	v_mul_f32_e32 v17, v17, v72
	v_mul_f32_e32 v17, 0xbfb8aa3b, v17
	v_add_f32_e32 v21, 1.0, v21
	v_exp_f32_e32 v17, v17
	v_mul_f32_e32 v18, v18, v72
	v_mul_f32_e32 v18, 0xbfb8aa3b, v18
	s_waitcnt vmcnt(7)
	v_lshlrev_b32_e32 v73, 16, v60
	s_waitcnt vmcnt(6)
	v_lshlrev_b32_e32 v79, 16, v64
	v_fmac_f32_e32 v79, v24, v73
	v_lshlrev_b32_e32 v70, 16, v58
	v_lshlrev_b32_e32 v75, 16, v62
	v_fmac_f32_e32 v75, v28, v70
	v_rcp_f32_e32 v24, v29
	v_mul_f32_e32 v29, v30, v72
	v_mul_f32_e32 v29, 0xbfb8aa3b, v29
	v_and_b32_e32 v58, 0xffff0000, v58
	v_and_b32_e32 v62, 0xffff0000, v62
	v_exp_f32_e32 v29, v29
	v_fmac_f32_e32 v62, v24, v58
	v_add_f32_e32 v29, 1.0, v29
	v_and_b32_e32 v60, 0xffff0000, v60
	v_and_b32_e32 v64, 0xffff0000, v64
	v_rcp_f32_e32 v24, v25
	s_nop 0
	v_fmac_f32_e32 v64, v24, v60
	v_lshlrev_b32_e32 v71, 16, v59
	v_lshlrev_b32_e32 v76, 16, v63
	v_rcp_f32_e32 v24, v29
	v_mul_f32_e32 v29, v31, v72
	v_fmac_f32_e32 v76, v24, v71
	v_mul_f32_e32 v29, 0xbfb8aa3b, v29
	v_exp_f32_e32 v29, v29
	s_nop 0
	v_add_f32_e32 v28, 1.0, v29
	v_rcp_f32_e32 v24, v26
	v_mul_f32_e32 v26, v27, v72
	v_mul_f32_e32 v26, 0xbfb8aa3b, v26
	v_lshlrev_b32_e32 v74, 16, v61
	v_lshlrev_b32_e32 v80, 16, v65
	v_exp_f32_e32 v26, v26
	v_fmac_f32_e32 v80, v24, v74
	v_add_f32_e32 v26, 1.0, v26
	v_and_b32_e32 v59, 0xffff0000, v59
	v_and_b32_e32 v63, 0xffff0000, v63
	v_rcp_f32_e32 v24, v28
	s_nop 0
	v_fmac_f32_e32 v63, v24, v59
	v_mul_f32_e32 v28, v62, v62
	v_mul_f32_e32 v29, v63, v63
	v_fmac_f32_e32 v28, v75, v75
	v_fmac_f32_e32 v29, v76, v76
	v_and_b32_e32 v61, 0xffff0000, v61
	v_and_b32_e32 v65, 0xffff0000, v65
	v_rcp_f32_e32 v24, v26
	v_add_f32_e32 v28, v28, v29
	v_mul_f32_e32 v29, v64, v64
	v_fmac_f32_e32 v65, v24, v61
	v_fmac_f32_e32 v29, v79, v79
	v_add_f32_e32 v28, v29, v28
	v_mul_f32_e32 v29, v65, v65
	v_fmac_f32_e32 v29, v80, v80
	v_add_f32_e32 v28, v29, v28
	s_waitcnt vmcnt(5)
	v_lshlrev_b32_e32 v29, 16, v66
	v_and_b32_e32 v30, 0xffff0000, v66
	v_lshlrev_b32_e32 v31, 16, v67
	v_and_b32_e32 v58, 0xffff0000, v67
	v_cvt_pk_bf16_f32 v24, v75, v62
	v_lshlrev_b32_e32 v61, 16, v69
	v_and_b32_e32 v62, 0xffff0000, v69
	v_cvt_pk_bf16_f32 v25, v76, v63
	s_waitcnt vmcnt(4)
	v_lshlrev_b32_e32 v63, 16, v48
	v_rcp_f32_e32 v20, v20
	s_nop 0
	v_fmac_f32_e32 v63, v20, v29
	v_cvt_pk_bf16_f32 v26, v79, v64
	v_cvt_pk_bf16_f32 v27, v80, v65
	v_lshlrev_b32_e32 v59, 16, v68
	v_lshlrev_b32_e32 v65, 16, v50
	v_rcp_f32_e32 v16, v16
	s_nop 0
	v_fmac_f32_e32 v65, v16, v59
	v_add_f32_e32 v17, 1.0, v17
	v_rcp_f32_e32 v16, v21
	v_mul_f32_e32 v21, v22, v72
	v_mul_f32_e32 v21, 0xbfb8aa3b, v21
	v_and_b32_e32 v48, 0xffff0000, v48
	v_exp_f32_e32 v21, v21
	v_fmac_f32_e32 v48, v16, v30
	v_add_f32_e32 v21, 1.0, v21
	v_and_b32_e32 v60, 0xffff0000, v68
	v_and_b32_e32 v50, 0xffff0000, v50
	v_rcp_f32_e32 v16, v17
	v_exp_f32_e32 v18, v18
	v_fmac_f32_e32 v50, v16, v60
	v_add_f32_e32 v18, 1.0, v18
	v_lshlrev_b32_e32 v64, 16, v49
	v_rcp_f32_e32 v16, v21
	v_mul_f32_e32 v21, v23, v72
	v_fmac_f32_e32 v64, v16, v31
	v_mul_f32_e32 v21, 0xbfb8aa3b, v21
	v_exp_f32_e32 v21, v21
	s_nop 0
	v_add_f32_e32 v20, 1.0, v21
	v_rcp_f32_e32 v16, v18
	v_mul_f32_e32 v18, v19, v72
	v_mul_f32_e32 v18, 0xbfb8aa3b, v18
	v_lshlrev_b32_e32 v68, 16, v51
	v_exp_f32_e32 v18, v18
	v_fmac_f32_e32 v68, v16, v61
	v_add_f32_e32 v18, 1.0, v18
	v_and_b32_e32 v49, 0xffff0000, v49
	v_rcp_f32_e32 v16, v20
	s_nop 0
	v_fmac_f32_e32 v49, v16, v58
	v_and_b32_e32 v51, 0xffff0000, v51
	v_rcp_f32_e32 v16, v18
	s_nop 0
	v_fmac_f32_e32 v51, v16, v62
	v_mul_f32_e32 v16, v48, v48
	v_mul_f32_e32 v17, v49, v49
	v_fmac_f32_e32 v16, v63, v63
	v_fmac_f32_e32 v17, v64, v64
	v_add_f32_e32 v16, v16, v17
	v_mul_f32_e32 v17, v50, v50
	v_fmac_f32_e32 v17, v65, v65
	v_add_f32_e32 v16, v17, v16
	v_mul_f32_e32 v17, v51, v51
	v_fmac_f32_e32 v17, v68, v68
	v_add_f32_e32 v16, v17, v16
	v_add_f32_e32 v19, v28, v16
	ds_bpermute_b32 v20, v124, v19
	v_lshlrev_b64 v[56:57], 13, v[54:55]
	v_lshl_add_u64 v[16:17], s[12:13], 0, v[56:57]
	v_lshl_add_u64 v[22:23], v[168:169], 1, v[16:17]
	global_store_dwordx4 v[22:23], v[24:27], off
	s_waitcnt lgkmcnt(0)
	v_add_f32_e32 v16, v19, v20
	ds_bpermute_b32 v17, v122, v16
	v_cvt_pk_bf16_f32 v18, v63, v48
	v_cvt_pk_bf16_f32 v19, v64, v49
	v_cvt_pk_bf16_f32 v20, v65, v50
	v_cvt_pk_bf16_f32 v21, v68, v51
	global_store_dwordx4 v[22:23], v[18:21], off offset:256
	s_and_saveexec_b64 s[0:1], s[6:7]
	s_cbranch_execz .LBB0_3047
	v_lshl_add_u64 v[18:19], v[54:55], 2, s[18:19]
	s_waitcnt lgkmcnt(0)
	v_add_f32_e32 v16, v16, v17
	global_atomic_add_f32 v[18:19], v16, off
; DI float sigmoidf_(float z) { return 1.0f / (1.0f + __expf(-z)); }
; DI v4u pack8(const f4& a, const f4& b) { v4u w; w.x = cvt_pk_bf16(a[0], a[1]); w.y = cvt_pk_bf16(a[2], a[3]); w.z = cvt_pk_bf16(b[0], b[1]); w.w = cvt_pk_bf16(b[2], b[3]); return w; }
; DI void unpack8(const v4u& w, f4& a, f4& b) { a[0] = bf_lo(w.x); a[1] = bf_hi(w.x); a[2] = bf_lo(w.y); a[3] = bf_hi(w.y); b[0] = bf_lo(w.z); b[1] = bf_hi(w.z); b[2] = bf_lo(w.w); b[3] = bf_hi(w.w); }
;     DI void operator()(f4 (&acc)[2][2][4][2], const Unit& u, int wr, int wc, int fr, int fq) const {
;     ...
;                 for (int mm = 0; mm < 2; ++mm) { const int m = 2 * mp + mm, row = row0 + ai * HALF + m * 16; const float r = __builtin_amdgcn_rsqf(rr[ai][m] * (1.0f / D) + RMS_EPS); float s = 0.f;
; #pragma unroll
;                     for (int bj = 0; bj < 2; ++bj) { const size_t off = (size_t)row * D + col0 + bj * HALF;
;                         f4 p0, p1; unpack8(pv[mm][bj], p0, p1);
;                         f4 h0, h1; unpack8(hv[mm][bj], h0, h1);
; #pragma unroll
;                         for (int t = 0; t < 4; ++t) { h0[t] += sigmoidf_(acc[ai][bj][m][0][t] * r) * p0[t]; h1[t] += sigmoidf_(acc[ai][bj][m][1][t] * r) * p1[t]; }
;                         *(v4u*)(h3b + off) = pack8(h0, h1);
;                         s += (h0[0] * h0[0] + h0[1] * h0[1]) + (h0[2] * h0[2] + h0[3] * h0[3]) + (h1[0] * h1[0] + h1[1] * h1[1]) + (h1[2] * h1[2] + h1[3] * h1[3]); }
;                     s += __shfl_xor(s, 16); s += __shfl_xor(s, 32);
;                     if (fq == 0) atomicAdd(ss_out + row, s); }
.LBB0_3047:
	s_or_b64 exec, exec, s[0:1]
	v_fmamk_f32 v16, v186, 0x39800000, v184
	v_rsq_f32_e32 v18, v16
	s_waitcnt vmcnt(3)
	v_lshlrev_b32_e32 v27, 16, v40
	v_and_b32_e32 v28, 0xffff0000, v40
	v_lshlrev_b32_e32 v29, 16, v41
	v_mul_f32_e32 v12, v12, v18
	v_mul_f32_e32 v12, 0xbfb8aa3b, v12
	v_exp_f32_e32 v12, v12
	v_and_b32_e32 v30, 0xffff0000, v41
	v_mul_f32_e32 v8, v8, v18
	v_mul_f32_e32 v8, 0xbfb8aa3b, v8
	v_add_f32_e32 v12, 1.0, v12
	v_lshlrev_b32_e32 v21, 16, v45
	v_and_b32_e32 v22, 0xffff0000, v45
	v_exp_f32_e32 v8, v8
	v_lshlrev_b32_e32 v23, 16, v46
	v_and_b32_e32 v24, 0xffff0000, v46
	v_lshlrev_b32_e32 v25, 16, v47
	v_and_b32_e32 v26, 0xffff0000, v47
	v_add_f32_e32 v8, 1.0, v8
	v_mul_f32_e32 v13, v13, v18
	v_mul_f32_e32 v13, 0xbfb8aa3b, v13
	v_lshlrev_b32_e32 v19, 16, v44
	v_rcp_f32_e32 v12, v12
	v_exp_f32_e32 v13, v13
	v_fmac_f32_e32 v27, v12, v19
	v_add_f32_e32 v13, 1.0, v13
	v_mul_f32_e32 v9, v9, v18
	v_lshlrev_b32_e32 v31, 16, v42
	v_rcp_f32_e32 v8, v8
	v_mul_f32_e32 v9, 0xbfb8aa3b, v9
	v_fmac_f32_e32 v31, v8, v23
	v_exp_f32_e32 v9, v9
	s_nop 0
	v_add_f32_e32 v9, 1.0, v9
	v_rcp_f32_e32 v8, v13
	v_mul_f32_e32 v13, v14, v18
	v_mul_f32_e32 v13, 0xbfb8aa3b, v13
	v_and_b32_e32 v20, 0xffff0000, v44
	v_exp_f32_e32 v13, v13
	v_fmac_f32_e32 v28, v8, v20
	v_add_f32_e32 v13, 1.0, v13
	v_mul_f32_e32 v10, v10, v18
	v_mul_f32_e32 v10, 0xbfb8aa3b, v10
	v_and_b32_e32 v42, 0xffff0000, v42
	v_rcp_f32_e32 v8, v9
	v_exp_f32_e32 v10, v10
	v_fmac_f32_e32 v42, v8, v24
	v_add_f32_e32 v10, 1.0, v10
	v_rcp_f32_e32 v8, v13
	v_mul_f32_e32 v13, v15, v18
	v_fmac_f32_e32 v29, v8, v21
	v_mul_f32_e32 v13, 0xbfb8aa3b, v13
	v_exp_f32_e32 v13, v13
	s_nop 0
	v_add_f32_e32 v12, 1.0, v13
	v_rcp_f32_e32 v8, v10
	v_mul_f32_e32 v10, v11, v18
	v_mul_f32_e32 v10, 0xbfb8aa3b, v10
	v_lshlrev_b32_e32 v44, 16, v43
	v_exp_f32_e32 v10, v10
	v_fmac_f32_e32 v44, v8, v25
	v_add_f32_e32 v10, 1.0, v10
	v_rcp_f32_e32 v8, v12
	s_nop 0
	v_fmac_f32_e32 v30, v8, v22
	v_mul_f32_e32 v4, v4, v18
	v_mul_f32_e32 v4, 0xbfb8aa3b, v4
	v_exp_f32_e32 v4, v4
	v_and_b32_e32 v43, 0xffff0000, v43
	v_rcp_f32_e32 v8, v10
	v_mul_f32_e32 v13, v30, v30
	v_add_f32_e32 v4, 1.0, v4
	v_fmac_f32_e32 v43, v8, v26
	v_cvt_pk_bf16_f32 v8, v27, v28
	v_cvt_pk_bf16_f32 v9, v29, v30
	v_fmac_f32_e32 v13, v29, v29
	v_mul_f32_e32 v12, v28, v28
	v_fmac_f32_e32 v12, v27, v27
	v_mul_f32_e32 v0, v0, v18
	v_add_f32_e32 v12, v12, v13
	v_mul_f32_e32 v13, v42, v42
	v_mul_f32_e32 v0, 0xbfb8aa3b, v0
	v_cvt_pk_bf16_f32 v10, v31, v42
	v_fmac_f32_e32 v13, v31, v31
	s_waitcnt vmcnt(2)
	v_lshlrev_b32_e32 v28, 16, v34
	v_and_b32_e32 v31, 0xffff0000, v34
	v_exp_f32_e32 v0, v0
	v_add_f32_e32 v12, v13, v12
	v_mul_f32_e32 v13, v43, v43
	v_fmac_f32_e32 v13, v44, v44
	v_lshlrev_b32_e32 v24, 16, v32
	v_and_b32_e32 v25, 0xffff0000, v32
	v_lshlrev_b32_e32 v26, 16, v33
	v_and_b32_e32 v27, 0xffff0000, v33
	v_lshlrev_b32_e32 v32, 16, v35
	v_and_b32_e32 v33, 0xffff0000, v35
	v_add_f32_e32 v12, v13, v12
	v_lshlrev_b32_e32 v13, 16, v36
	v_and_b32_e32 v14, 0xffff0000, v36
	v_add_f32_e32 v0, 1.0, v0
	v_mul_f32_e32 v5, v5, v18
	v_mul_f32_e32 v5, 0xbfb8aa3b, v5
	v_rcp_f32_e32 v4, v4
	v_exp_f32_e32 v5, v5
	v_fmac_f32_e32 v24, v4, v13
	v_add_f32_e32 v5, 1.0, v5
	v_mul_f32_e32 v1, v1, v18
	v_lshlrev_b32_e32 v20, 16, v38
	v_rcp_f32_e32 v0, v0
	v_mul_f32_e32 v1, 0xbfb8aa3b, v1
	v_fmac_f32_e32 v28, v0, v20
	v_exp_f32_e32 v1, v1
	s_nop 0
	v_add_f32_e32 v1, 1.0, v1
	v_rcp_f32_e32 v0, v5
	v_mul_f32_e32 v5, v6, v18
	v_mul_f32_e32 v5, 0xbfb8aa3b, v5
	v_exp_f32_e32 v5, v5
	v_fmac_f32_e32 v25, v0, v14
	v_add_f32_e32 v5, 1.0, v5
	v_mul_f32_e32 v2, v2, v18
	v_mul_f32_e32 v2, 0xbfb8aa3b, v2
	v_and_b32_e32 v21, 0xffff0000, v38
	v_rcp_f32_e32 v0, v1
	v_exp_f32_e32 v2, v2
	v_fmac_f32_e32 v31, v0, v21
	v_add_f32_e32 v2, 1.0, v2
	v_lshlrev_b32_e32 v15, 16, v37
	v_rcp_f32_e32 v0, v5
	v_mul_f32_e32 v5, v7, v18
	v_fmac_f32_e32 v26, v0, v15
	v_mul_f32_e32 v5, 0xbfb8aa3b, v5
	v_exp_f32_e32 v5, v5
	s_nop 0
	v_add_f32_e32 v4, 1.0, v5
	v_rcp_f32_e32 v0, v2
	v_mul_f32_e32 v2, v3, v18
	v_mul_f32_e32 v2, 0xbfb8aa3b, v2
	v_lshlrev_b32_e32 v22, 16, v39
	v_exp_f32_e32 v2, v2
	v_fmac_f32_e32 v32, v0, v22
	v_add_f32_e32 v2, 1.0, v2
	v_and_b32_e32 v19, 0xffff0000, v37
	v_rcp_f32_e32 v0, v4
	s_nop 0
	v_fmac_f32_e32 v27, v0, v19
	v_and_b32_e32 v23, 0xffff0000, v39
	v_rcp_f32_e32 v0, v2
	s_nop 0
	v_fmac_f32_e32 v33, v0, v23
	v_mul_f32_e32 v0, v25, v25
	v_mul_f32_e32 v1, v27, v27
	v_fmac_f32_e32 v0, v24, v24
	v_fmac_f32_e32 v1, v26, v26
	v_add_f32_e32 v0, v0, v1
	v_mul_f32_e32 v1, v31, v31
	v_fmac_f32_e32 v1, v28, v28
	v_add_f32_e32 v0, v1, v0
	v_mul_f32_e32 v1, v33, v33
	v_fmac_f32_e32 v1, v32, v32
	v_add_f32_e32 v0, v1, v0
	v_add_f32_e32 v3, v12, v0
	ds_bpermute_b32 v4, v124, v3
	s_waitcnt lgkmcnt(1)
	v_lshlrev_b64 v[16:17], 13, v[52:53]
	v_lshl_add_u64 v[0:1], s[12:13], 0, v[16:17]
	v_lshl_add_u64 v[6:7], v[168:169], 1, v[0:1]
	v_cvt_pk_bf16_f32 v11, v44, v43
	s_waitcnt lgkmcnt(0)
	v_add_f32_e32 v0, v3, v4
	ds_bpermute_b32 v1, v122, v0
	global_store_dwordx4 v[6:7], v[8:11], off
	v_cvt_pk_bf16_f32 v2, v24, v25
	v_cvt_pk_bf16_f32 v3, v26, v27
	v_cvt_pk_bf16_f32 v4, v28, v31
	v_cvt_pk_bf16_f32 v5, v32, v33
	global_store_dwordx4 v[6:7], v[2:5], off offset:256
	s_and_saveexec_b64 s[0:1], s[6:7]
	s_cbranch_execz .LBB0_3049
	v_lshl_add_u64 v[2:3], v[52:53], 2, s[18:19]
	s_waitcnt lgkmcnt(0)
	v_add_f32_e32 v0, v0, v1
	global_atomic_add_f32 v[2:3], v0, off

; #define GAS __attribute__((address_space(1)))
; DI void unpack8(const v4u& w, f4& a, f4& b) { a[0] = bf_lo(w.x); a[1] = bf_hi(w.x); a[2] = bf_lo(w.y); a[3] = bf_hi(w.y); b[0] = bf_lo(w.z); b[1] = bf_hi(w.z); b[2] = bf_lo(w.w); b[3] = bf_hi(w.w); }
; DI void final_phase(const float* const* in, unsigned char* ws, float* out, int gw, int NGW, int lane) {
;     ...
;     for (int m = gw; m < M; m += NGW) { const float r = 1.0f / sqrtf(ss3[m] * (1.0f / D) + RMS_EPS);
;         const GAS v4u* src = (const GAS v4u*)(hb + (size_t)m * D) + lane; GAS f32x4* o = (GAS f32x4*)(out + (size_t)m * D) + 2 * lane; const GAS f32x4* g = (const GAS f32x4*)nf + 2 * lane;
;         v4u w[8];
; #pragma unroll
;         for (int j = 0; j < 8; ++j) w[j] = __builtin_nontemporal_load(src + 64 * j);
; #pragma unroll
;         for (int j = 0; j < 8; ++j) { f32x4 a, b; epi::unpack8(w[j], a, b); a = a * r * g[128 * j]; b = b * r * g[128 * j + 1]; __builtin_nontemporal_store(a, o + 128 * j); __builtin_nontemporal_store(b, o + 128 * j + 1); } }
.LBB0_3108:
	s_nop 1
	v_lshl_add_u64 v[0:1], s[16:17], 0, v[32:33]
	v_add_co_u32_e32 v62, vcc, s11, v0
	s_mov_b32 s18, s0
	s_add_u32 s0, s16, s8
	v_addc_co_u32_e32 v63, vcc, 0, v1, vcc
	s_addc_u32 s1, s17, s9
	v_add_co_u32_e32 v64, vcc, s12, v0
	global_load_dwordx4 v[38:41], v[16:17], off offset:16
	global_load_dwordx4 v[42:45], v[16:17], off
	v_addc_co_u32_e32 v65, vcc, 0, v1, vcc
	global_load_dword v34, v35, s[0:1]
	global_load_dwordx4 v[46:49], v[64:65], off offset:-4096 nt
	global_load_dwordx4 v[50:53], v[62:63], off offset:1024 nt
	global_load_dwordx4 v[54:57], v[62:63], off offset:2048 nt
	global_load_dwordx4 v[58:61], v[62:63], off offset:3072 nt
	global_load_dwordx4 v[12:15], v[64:65], off nt
	global_load_dwordx4 v[8:11], v[64:65], off offset:1024 nt
	global_load_dwordx4 v[4:7], v[64:65], off offset:2048 nt
	global_load_dwordx4 v[0:3], v[64:65], off offset:3072 nt
	s_add_i32 s74, s74, s18
	s_add_u32 s8, s8, s2
	s_addc_u32 s9, s9, s3
	v_lshl_add_u64 v[32:33], v[32:33], 0, s[6:7]
	s_cmpk_lt_i32 s74, 0x4000
	s_waitcnt vmcnt(0)
	v_fmamk_f32 v34, v34, 0x39800000, v36
	v_mul_f32_e32 v66, 0x4f800000, v34
	v_cmp_gt_f32_e32 vcc, s10, v34
	v_lshlrev_b32_e32 v62, 16, v46
	v_and_b32_e32 v63, 0xffff0000, v46
	v_cndmask_b32_e32 v34, v34, v66, vcc
	v_sqrt_f32_e32 v66, v34
	v_lshlrev_b32_e32 v46, 16, v47
	v_and_b32_e32 v47, 0xffff0000, v47
	v_lshlrev_b32_e32 v64, 16, v48
	v_add_u32_e32 v67, -1, v66
	v_add_u32_e32 v68, 1, v66
	v_fma_f32 v69, -v67, v66, v34
	v_fma_f32 v70, -v68, v66, v34
	v_cmp_ge_f32_e64 s[0:1], 0, v69
	v_and_b32_e32 v65, 0xffff0000, v48
	v_lshlrev_b32_e32 v48, 16, v49
	v_cndmask_b32_e64 v66, v66, v67, s[0:1]
	v_cmp_lt_f32_e64 s[0:1], 0, v70
	v_and_b32_e32 v49, 0xffff0000, v49
	s_nop 0
	v_cndmask_b32_e64 v66, v66, v68, s[0:1]
	v_mul_f32_e32 v67, 0x37800000, v66
	v_cndmask_b32_e32 v66, v66, v67, vcc
	v_cmp_class_f32_e32 vcc, v34, v37
	s_nop 1
	v_cndmask_b32_e32 v34, v66, v34, vcc
	v_div_scale_f32 v66, s[0:1], v34, v34, 1.0
	v_rcp_f32_e32 v68, v66
	v_div_scale_f32 v67, vcc, 1.0, v34, 1.0
	s_mov_b32 s0, s18
	v_fma_f32 v69, -v66, v68, 1.0
	v_fmac_f32_e32 v68, v69, v68
	v_mul_f32_e32 v69, v67, v68
	v_fma_f32 v70, -v66, v69, v67
	v_fmac_f32_e32 v69, v70, v68
	v_fma_f32 v66, -v66, v69, v67
	v_div_fmas_f32 v66, v66, v68, v69
	v_div_fixup_f32 v34, v66, v34, 1.0
	v_pk_mul_f32 v[62:63], v[34:35], v[62:63] op_sel_hi:[0,1]
	v_pk_mul_f32 v[46:47], v[34:35], v[46:47] op_sel_hi:[0,1]
	v_pk_mul_f32 v[64:65], v[34:35], v[64:65] op_sel_hi:[0,1]
	v_pk_mul_f32 v[48:49], v[34:35], v[48:49] op_sel_hi:[0,1]
	v_pk_mul_f32 v[44:45], v[46:47], v[44:45]
	v_pk_mul_f32 v[42:43], v[62:63], v[42:43]
	v_pk_mul_f32 v[40:41], v[48:49], v[40:41]
	v_pk_mul_f32 v[38:39], v[64:65], v[38:39]
	global_store_dwordx4 v[30:31], v[42:45], off nt
	global_store_dwordx4 v[30:31], v[38:41], off offset:16 nt
	s_nop 0
	global_load_dwordx4 v[38:41], v[16:17], off offset:2048
	s_nop 0
	global_load_dwordx4 v[42:45], v[16:17], off offset:2064
	v_lshlrev_b32_e32 v46, 16, v50
	v_and_b32_e32 v47, 0xffff0000, v50
	v_lshlrev_b32_e32 v48, 16, v51
	v_and_b32_e32 v49, 0xffff0000, v51
	v_lshlrev_b32_e32 v50, 16, v52
	v_and_b32_e32 v51, 0xffff0000, v52
	v_lshlrev_b32_e32 v52, 16, v53
	v_and_b32_e32 v53, 0xffff0000, v53
	v_pk_mul_f32 v[48:49], v[34:35], v[48:49] op_sel_hi:[0,1]
	v_pk_mul_f32 v[46:47], v[34:35], v[46:47] op_sel_hi:[0,1]
	v_pk_mul_f32 v[52:53], v[34:35], v[52:53] op_sel_hi:[0,1]
	v_pk_mul_f32 v[50:51], v[34:35], v[50:51] op_sel_hi:[0,1]
	s_waitcnt vmcnt(1)
	v_pk_mul_f32 v[38:39], v[46:47], v[38:39]
	v_pk_mul_f32 v[40:41], v[48:49], v[40:41]
	s_waitcnt vmcnt(0)
	v_pk_mul_f32 v[42:43], v[50:51], v[42:43]
	v_pk_mul_f32 v[44:45], v[52:53], v[44:45]
	global_store_dwordx4 v[30:31], v[38:41], off offset:2048 nt
	global_store_dwordx4 v[30:31], v[42:45], off offset:2064 nt
	global_load_dwordx4 v[38:41], v[18:19], off
	s_nop 0
	global_load_dwordx4 v[42:45], v[18:19], off offset:16
	v_add_co_u32_e32 v46, vcc, s13, v30
	v_lshlrev_b32_e32 v50, 16, v54
	s_nop 0
	v_addc_co_u32_e32 v47, vcc, 0, v31, vcc
	v_and_b32_e32 v51, 0xffff0000, v54
	v_lshlrev_b32_e32 v52, 16, v55
	v_and_b32_e32 v53, 0xffff0000, v55
	v_add_co_u32_e32 v48, vcc, s14, v30
	v_lshlrev_b32_e32 v54, 16, v56
	v_and_b32_e32 v55, 0xffff0000, v56
	v_lshlrev_b32_e32 v56, 16, v57
	v_and_b32_e32 v57, 0xffff0000, v57
	v_pk_mul_f32 v[52:53], v[34:35], v[52:53] op_sel_hi:[0,1]
	v_pk_mul_f32 v[50:51], v[34:35], v[50:51] op_sel_hi:[0,1]
	v_addc_co_u32_e32 v49, vcc, 0, v31, vcc
	v_pk_mul_f32 v[56:57], v[34:35], v[56:57] op_sel_hi:[0,1]
	v_pk_mul_f32 v[54:55], v[34:35], v[54:55] op_sel_hi:[0,1]
	s_waitcnt vmcnt(1)
	v_pk_mul_f32 v[38:39], v[50:51], v[38:39]
	v_pk_mul_f32 v[40:41], v[52:53], v[40:41]
	s_waitcnt vmcnt(0)
; DI void unpack8(const v4u& w, f4& a, f4& b) { a[0] = bf_lo(w.x); a[1] = bf_hi(w.x); a[2] = bf_lo(w.y); a[3] = bf_hi(w.y); b[0] = bf_lo(w.z); b[1] = bf_hi(w.z); b[2] = bf_lo(w.w); b[3] = bf_hi(w.w); }
; DI void final_phase(const float* const* in, unsigned char* ws, float* out, int gw, int NGW, int lane) {
;     ...
;         for (int j = 0; j < 8; ++j) w[j] = __builtin_nontemporal_load(src + 64 * j);
; #pragma unroll
;         for (int j = 0; j < 8; ++j) { f32x4 a, b; epi::unpack8(w[j], a, b); a = a * r * g[128 * j]; b = b * r * g[128 * j + 1]; __builtin_nontemporal_store(a, o + 128 * j); __builtin_nontemporal_store(b, o + 128 * j + 1); } }
	v_pk_mul_f32 v[42:43], v[54:55], v[42:43]
	v_pk_mul_f32 v[44:45], v[56:57], v[44:45]
	global_store_dwordx4 v[48:49], v[38:41], off offset:-4096 nt
	global_store_dwordx4 v[46:47], v[42:45], off offset:16 nt
	global_load_dwordx4 v[38:41], v[20:21], off
	s_nop 0
	global_load_dwordx4 v[42:45], v[20:21], off offset:16
	v_lshlrev_b32_e32 v50, 16, v58
	v_and_b32_e32 v51, 0xffff0000, v58
	v_lshlrev_b32_e32 v52, 16, v59
	v_and_b32_e32 v53, 0xffff0000, v59
	v_lshlrev_b32_e32 v54, 16, v60
	v_and_b32_e32 v55, 0xffff0000, v60
	v_lshlrev_b32_e32 v56, 16, v61
	v_and_b32_e32 v57, 0xffff0000, v61
	v_pk_mul_f32 v[52:53], v[34:35], v[52:53] op_sel_hi:[0,1]
	v_pk_mul_f32 v[50:51], v[34:35], v[50:51] op_sel_hi:[0,1]
	v_pk_mul_f32 v[56:57], v[34:35], v[56:57] op_sel_hi:[0,1]
	v_pk_mul_f32 v[54:55], v[34:35], v[54:55] op_sel_hi:[0,1]
	s_waitcnt vmcnt(1)
	v_pk_mul_f32 v[38:39], v[50:51], v[38:39]
	v_pk_mul_f32 v[40:41], v[52:53], v[40:41]
	s_waitcnt vmcnt(0)
	v_pk_mul_f32 v[42:43], v[54:55], v[42:43]
	v_pk_mul_f32 v[44:45], v[56:57], v[44:45]
	global_store_dwordx4 v[46:47], v[38:41], off offset:2048 nt
	global_store_dwordx4 v[46:47], v[42:45], off offset:2064 nt
	global_load_dwordx4 v[38:41], v[22:23], off
	s_nop 0
	global_load_dwordx4 v[42:45], v[22:23], off offset:16
	v_lshlrev_b32_e32 v46, 16, v12
	v_and_b32_e32 v47, 0xffff0000, v12
	v_lshlrev_b32_e32 v12, 16, v13
	v_and_b32_e32 v13, 0xffff0000, v13
	v_lshlrev_b32_e32 v50, 16, v14
	v_and_b32_e32 v51, 0xffff0000, v14
	v_lshlrev_b32_e32 v14, 16, v15
	v_and_b32_e32 v15, 0xffff0000, v15
	v_pk_mul_f32 v[52:53], v[34:35], v[12:13] op_sel_hi:[0,1]
	v_pk_mul_f32 v[12:13], v[34:35], v[46:47] op_sel_hi:[0,1]
	v_pk_mul_f32 v[46:47], v[34:35], v[14:15] op_sel_hi:[0,1]
	v_pk_mul_f32 v[50:51], v[34:35], v[50:51] op_sel_hi:[0,1]
	s_waitcnt vmcnt(1)
	v_pk_mul_f32 v[12:13], v[12:13], v[38:39]
	v_pk_mul_f32 v[14:15], v[52:53], v[40:41]
	s_waitcnt vmcnt(0)
	v_pk_mul_f32 v[38:39], v[50:51], v[42:43]
	v_pk_mul_f32 v[40:41], v[46:47], v[44:45]
	global_store_dwordx4 v[48:49], v[12:15], off nt
	global_store_dwordx4 v[48:49], v[38:41], off offset:16 nt
	global_load_dwordx4 v[12:15], v[24:25], off
	s_nop 0
	global_load_dwordx4 v[38:41], v[24:25], off offset:16
	v_lshlrev_b32_e32 v42, 16, v8
	v_and_b32_e32 v43, 0xffff0000, v8
	v_lshlrev_b32_e32 v8, 16, v9
	v_and_b32_e32 v9, 0xffff0000, v9
	v_lshlrev_b32_e32 v44, 16, v10
	v_and_b32_e32 v45, 0xffff0000, v10
	v_lshlrev_b32_e32 v10, 16, v11
	v_and_b32_e32 v11, 0xffff0000, v11
	v_pk_mul_f32 v[46:47], v[34:35], v[8:9] op_sel_hi:[0,1]
	v_pk_mul_f32 v[8:9], v[34:35], v[42:43] op_sel_hi:[0,1]
	v_pk_mul_f32 v[42:43], v[34:35], v[10:11] op_sel_hi:[0,1]
	v_pk_mul_f32 v[44:45], v[34:35], v[44:45] op_sel_hi:[0,1]
	s_waitcnt vmcnt(1)
	v_pk_mul_f32 v[8:9], v[8:9], v[12:13]
	v_pk_mul_f32 v[10:11], v[46:47], v[14:15]
	s_waitcnt vmcnt(0)
	v_pk_mul_f32 v[12:13], v[44:45], v[38:39]
	v_pk_mul_f32 v[14:15], v[42:43], v[40:41]
	global_store_dwordx4 v[48:49], v[8:11], off offset:2048 nt
	global_store_dwordx4 v[48:49], v[12:15], off offset:2064 nt
	global_load_dwordx4 v[8:11], v[26:27], off
	s_nop 0
	global_load_dwordx4 v[12:15], v[26:27], off offset:16
	v_lshlrev_b32_e32 v40, 16, v4
	v_and_b32_e32 v41, 0xffff0000, v4
	v_lshlrev_b32_e32 v4, 16, v5
	v_and_b32_e32 v5, 0xffff0000, v5
	v_add_co_u32_e32 v38, vcc, s15, v30
	v_lshlrev_b32_e32 v42, 16, v6
	v_and_b32_e32 v43, 0xffff0000, v6
	v_lshlrev_b32_e32 v6, 16, v7
	v_and_b32_e32 v7, 0xffff0000, v7
	v_pk_mul_f32 v[44:45], v[34:35], v[4:5] op_sel_hi:[0,1]
	v_pk_mul_f32 v[4:5], v[34:35], v[40:41] op_sel_hi:[0,1]
	v_addc_co_u32_e32 v39, vcc, 0, v31, vcc
	v_pk_mul_f32 v[40:41], v[34:35], v[6:7] op_sel_hi:[0,1]
	v_pk_mul_f32 v[42:43], v[34:35], v[42:43] op_sel_hi:[0,1]
	v_lshl_add_u64 v[30:31], v[30:31], 0, s[4:5]
	s_waitcnt vmcnt(1)
	v_pk_mul_f32 v[4:5], v[4:5], v[8:9]
	v_pk_mul_f32 v[6:7], v[44:45], v[10:11]
	s_waitcnt vmcnt(0)
	v_pk_mul_f32 v[8:9], v[42:43], v[12:13]
	v_pk_mul_f32 v[10:11], v[40:41], v[14:15]
	global_store_dwordx4 v[38:39], v[4:7], off nt
	global_store_dwordx4 v[38:39], v[8:11], off offset:16 nt
	global_load_dwordx4 v[4:7], v[28:29], off
	s_nop 0
	global_load_dwordx4 v[8:11], v[28:29], off offset:16
	v_lshlrev_b32_e32 v12, 16, v0
	v_and_b32_e32 v13, 0xffff0000, v0
	v_lshlrev_b32_e32 v0, 16, v1
	v_and_b32_e32 v1, 0xffff0000, v1
	v_lshlrev_b32_e32 v14, 16, v2
	v_and_b32_e32 v15, 0xffff0000, v2
	v_lshlrev_b32_e32 v2, 16, v3
	v_and_b32_e32 v3, 0xffff0000, v3
	v_pk_mul_f32 v[40:41], v[34:35], v[0:1] op_sel_hi:[0,1]
	v_pk_mul_f32 v[0:1], v[34:35], v[12:13] op_sel_hi:[0,1]
	v_pk_mul_f32 v[12:13], v[34:35], v[2:3] op_sel_hi:[0,1]
	v_pk_mul_f32 v[14:15], v[34:35], v[14:15] op_sel_hi:[0,1]
	s_waitcnt vmcnt(1)
	v_pk_mul_f32 v[0:1], v[0:1], v[4:5]
	v_pk_mul_f32 v[2:3], v[40:41], v[6:7]
	s_waitcnt vmcnt(0)
	v_pk_mul_f32 v[4:5], v[14:15], v[8:9]
	v_pk_mul_f32 v[6:7], v[12:13], v[10:11]
	global_store_dwordx4 v[38:39], v[0:3], off offset:2048 nt
	global_store_dwordx4 v[38:39], v[4:7], off offset:2064 nt
	s_cbranch_scc1 .LBB0_3108
